# variant: quad MFMA order (distance-2 chains sharing srcB) instead of pair order
# baseline (speedup 1.0000x reference)
.LBB0_120:
	ds_read_b128 v[128:131], v178
	ds_read_b128 v[132:135], v178 offset:1024
	ds_read_b128 v[154:157], v178 offset:2048
	ds_read_b128 v[158:161], v178 offset:3072
	ds_read_b128 v[162:165], v179
	ds_read_b128 v[166:169], v179 offset:1024
	ds_read_b128 v[182:185], v179 offset:2048
	ds_read_b128 v[186:189], v179 offset:3072
	s_add_u32 s67, s88, 0xfffc0080
	s_addc_u32 s68, s89, -1
	s_cmp_eq_u32 s66, 12
	s_cselect_b32 s93, s52, s68
	s_cselect_b32 s92, s53, s67
	s_cselect_b32 s91, s56, s59
	s_cselect_b32 s90, s57, s58
	v_lshl_add_u64 v[170:171], s[88:89], 0, v[144:145]
	s_add_i32 m0, s17, 0xc000
	ds_read_b128 v[190:193], v180
	ds_read_b128 v[194:197], v180 offset:1024
	ds_read_b128 v[198:201], v180 offset:2048
	ds_read_b128 v[202:205], v180 offset:3072
	ds_read_b128 v[206:209], v180 offset:4096
	ds_read_b128 v[210:213], v180 offset:5120
	ds_read_b128 v[214:217], v180 offset:6144
	ds_read_b128 v[218:221], v180 offset:7168
	global_load_lds_dwordx4 v[170:171], off
	s_add_i32 m0, s17, 0xe000
	v_lshl_add_u64 v[170:171], s[88:89], 0, v[148:149]
	global_load_lds_dwordx4 v[170:171], off
	s_cmp_eq_u32 s66, -2
	s_waitcnt vmcnt(8) lgkmcnt(0)
	s_barrier
	s_setprio 1
	s_cbranch_scc1 .Lzv_0_0
	v_mfma_f32_16x16x32_bf16 v[124:127], v[128:131], v[190:193], v[124:127]
	v_mfma_f32_16x16x32_bf16 v[116:119], v[154:157], v[190:193], v[116:119]
	v_mfma_f32_16x16x32_bf16 v[124:127], v[132:135], v[194:197], v[124:127]
	v_mfma_f32_16x16x32_bf16 v[116:119], v[158:161], v[194:197], v[116:119]
	v_mfma_f32_16x16x32_bf16 v[108:111], v[128:131], v[198:201], v[108:111]
	v_mfma_f32_16x16x32_bf16 v[100:103], v[154:157], v[198:201], v[100:103]
	v_mfma_f32_16x16x32_bf16 v[108:111], v[132:135], v[202:205], v[108:111]
	v_mfma_f32_16x16x32_bf16 v[100:103], v[158:161], v[202:205], v[100:103]
	v_mfma_f32_16x16x32_bf16 v[92:95], v[128:131], v[206:209], v[92:95]
	v_mfma_f32_16x16x32_bf16 v[84:87], v[154:157], v[206:209], v[84:87]
	v_mfma_f32_16x16x32_bf16 v[92:95], v[132:135], v[210:213], v[92:95]
	v_mfma_f32_16x16x32_bf16 v[84:87], v[158:161], v[210:213], v[84:87]
	v_mfma_f32_16x16x32_bf16 v[76:79], v[128:131], v[214:217], v[76:79]
	v_mfma_f32_16x16x32_bf16 v[68:71], v[154:157], v[214:217], v[68:71]
	v_mfma_f32_16x16x32_bf16 v[76:79], v[132:135], v[218:221], v[76:79]
	v_mfma_f32_16x16x32_bf16 v[68:71], v[158:161], v[218:221], v[68:71]
	v_mfma_f32_16x16x32_bf16 v[120:123], v[162:165], v[190:193], v[120:123]
	v_mfma_f32_16x16x32_bf16 v[112:115], v[182:185], v[190:193], v[112:115]
	v_mfma_f32_16x16x32_bf16 v[120:123], v[166:169], v[194:197], v[120:123]
	v_mfma_f32_16x16x32_bf16 v[112:115], v[186:189], v[194:197], v[112:115]
	v_mfma_f32_16x16x32_bf16 v[104:107], v[162:165], v[198:201], v[104:107]
	v_mfma_f32_16x16x32_bf16 v[96:99], v[182:185], v[198:201], v[96:99]
	v_mfma_f32_16x16x32_bf16 v[104:107], v[166:169], v[202:205], v[104:107]
	v_mfma_f32_16x16x32_bf16 v[96:99], v[186:189], v[202:205], v[96:99]
	v_mfma_f32_16x16x32_bf16 v[88:91], v[162:165], v[206:209], v[88:91]
	v_mfma_f32_16x16x32_bf16 v[80:83], v[182:185], v[206:209], v[80:83]
	v_mfma_f32_16x16x32_bf16 v[88:91], v[166:169], v[210:213], v[88:91]
	v_mfma_f32_16x16x32_bf16 v[80:83], v[186:189], v[210:213], v[80:83]
	v_mfma_f32_16x16x32_bf16 v[72:75], v[162:165], v[214:217], v[72:75]
	v_mfma_f32_16x16x32_bf16 v[64:67], v[182:185], v[214:217], v[64:67]
	s_setprio 3
	s_barrier
	v_mfma_f32_16x16x32_bf16 v[72:75], v[166:169], v[218:221], v[72:75]
	v_mfma_f32_16x16x32_bf16 v[64:67], v[186:189], v[218:221], v[64:67]
	s_setprio 0
.Lzj_0_0:
	s_add_i32 s67, s25, s16
	v_lshl_add_u64 v[170:171], s[90:91], 0, v[140:141]
	s_mov_b32 m0, s67
	ds_read_b128 v[190:193], v180 offset:16384
	ds_read_b128 v[194:197], v180 offset:17408
	ds_read_b128 v[198:201], v180 offset:18432
	ds_read_b128 v[202:205], v180 offset:19456
	ds_read_b128 v[206:209], v180 offset:20480
	ds_read_b128 v[210:213], v180 offset:21504
	ds_read_b128 v[214:217], v180 offset:22528
	ds_read_b128 v[218:221], v180 offset:23552
	global_load_lds_dwordx4 v[170:171], off
	s_add_i32 m0, s67, 0x2000
	s_add_u32 s68, s90, 0x40000
	v_lshl_add_u64 v[222:223], s[90:91], 0, v[136:137]
	s_addc_u32 s69, s91, 0
	s_add_i32 s67, s26, s16
	global_load_lds_dwordx4 v[222:223], off
	v_lshl_add_u64 v[224:225], s[68:69], 0, v[140:141]
	s_mov_b32 m0, s67
	global_load_lds_dwordx4 v[224:225], off
	s_add_i32 m0, s67, 0x2000
	v_lshl_add_u64 v[224:225], s[68:69], 0, v[136:137]
	global_load_lds_dwordx4 v[224:225], off
	s_mov_b32 m0, s17
	v_lshl_add_u64 v[224:225], s[92:93], 0, v[142:143]
	global_load_lds_dwordx4 v[224:225], off
	s_mov_b32 m0, s18
	v_lshl_add_u64 v[226:227], s[92:93], 0, v[138:139]
	global_load_lds_dwordx4 v[226:227], off
	s_cmp_eq_u32 s66, -2
	s_waitcnt vmcnt(8) lgkmcnt(0)
	s_barrier
	s_setprio 1
	s_cbranch_scc1 .Lzv_0_1
	v_mfma_f32_16x16x32_bf16 v[60:63], v[128:131], v[190:193], v[60:63]
	v_mfma_f32_16x16x32_bf16 v[52:55], v[154:157], v[190:193], v[52:55]
	v_mfma_f32_16x16x32_bf16 v[60:63], v[132:135], v[194:197], v[60:63]
	v_mfma_f32_16x16x32_bf16 v[52:55], v[158:161], v[194:197], v[52:55]
	v_mfma_f32_16x16x32_bf16 v[44:47], v[128:131], v[198:201], v[44:47]
	v_mfma_f32_16x16x32_bf16 v[36:39], v[154:157], v[198:201], v[36:39]
	v_mfma_f32_16x16x32_bf16 v[44:47], v[132:135], v[202:205], v[44:47]
	v_mfma_f32_16x16x32_bf16 v[36:39], v[158:161], v[202:205], v[36:39]
	v_mfma_f32_16x16x32_bf16 v[28:31], v[128:131], v[206:209], v[28:31]
	v_mfma_f32_16x16x32_bf16 v[20:23], v[154:157], v[206:209], v[20:23]
	v_mfma_f32_16x16x32_bf16 v[28:31], v[132:135], v[210:213], v[28:31]
	v_mfma_f32_16x16x32_bf16 v[20:23], v[158:161], v[210:213], v[20:23]
	v_mfma_f32_16x16x32_bf16 v[12:15], v[128:131], v[214:217], v[12:15]
	v_mfma_f32_16x16x32_bf16 v[4:7], v[154:157], v[214:217], v[4:7]
	v_mfma_f32_16x16x32_bf16 v[12:15], v[132:135], v[218:221], v[12:15]
	v_mfma_f32_16x16x32_bf16 v[4:7], v[158:161], v[218:221], v[4:7]
	v_mfma_f32_16x16x32_bf16 v[56:59], v[162:165], v[190:193], v[56:59]
	v_mfma_f32_16x16x32_bf16 v[48:51], v[182:185], v[190:193], v[48:51]
	v_mfma_f32_16x16x32_bf16 v[56:59], v[166:169], v[194:197], v[56:59]
	v_mfma_f32_16x16x32_bf16 v[48:51], v[186:189], v[194:197], v[48:51]
	v_mfma_f32_16x16x32_bf16 v[40:43], v[162:165], v[198:201], v[40:43]
	v_mfma_f32_16x16x32_bf16 v[32:35], v[182:185], v[198:201], v[32:35]
	v_mfma_f32_16x16x32_bf16 v[40:43], v[166:169], v[202:205], v[40:43]
	v_mfma_f32_16x16x32_bf16 v[32:35], v[186:189], v[202:205], v[32:35]
	v_mfma_f32_16x16x32_bf16 v[24:27], v[162:165], v[206:209], v[24:27]
	v_mfma_f32_16x16x32_bf16 v[16:19], v[182:185], v[206:209], v[16:19]
	v_mfma_f32_16x16x32_bf16 v[24:27], v[166:169], v[210:213], v[24:27]
	v_mfma_f32_16x16x32_bf16 v[16:19], v[186:189], v[210:213], v[16:19]
	v_mfma_f32_16x16x32_bf16 v[8:11], v[162:165], v[214:217], v[8:11]
	v_mfma_f32_16x16x32_bf16 v[0:3], v[182:185], v[214:217], v[0:3]
	s_setprio 3
	s_barrier
	v_mfma_f32_16x16x32_bf16 v[8:11], v[166:169], v[218:221], v[8:11]
	v_mfma_f32_16x16x32_bf16 v[0:3], v[186:189], v[218:221], v[0:3]
	s_setprio 0
.Lzj_0_1:
	s_add_i32 s67, 0, 0x18000
	s_add_i32 s73, 0, 0x1c000
	v_add_u32_e32 v158, s67, v175
	v_add_u32_e32 v186, s73, v175
	ds_read_b128 v[128:131], v158
	ds_read_b128 v[132:135], v158 offset:1024
	ds_read_b128 v[154:157], v158 offset:2048
	ds_read_b128 v[158:161], v158 offset:3072
	ds_read_b128 v[162:165], v186
	ds_read_b128 v[166:169], v186 offset:1024
	ds_read_b128 v[182:185], v186 offset:2048
	ds_read_b128 v[186:189], v186 offset:3072
	s_add_u32 s68, s92, 0x40000
	s_addc_u32 s69, s93, 0
	s_mov_b32 m0, s19
	v_lshl_add_u64 v[228:229], s[68:69], 0, v[142:143]
	ds_read_b128 v[190:193], v180 offset:32768
	ds_read_b128 v[194:197], v180 offset:33792
	ds_read_b128 v[198:201], v180 offset:34816
	ds_read_b128 v[202:205], v180 offset:35840
	ds_read_b128 v[206:209], v180 offset:36864
	ds_read_b128 v[210:213], v180 offset:37888
	ds_read_b128 v[214:217], v180 offset:38912
	ds_read_b128 v[218:221], v180 offset:39936
	global_load_lds_dwordx4 v[228:229], off
	s_mov_b32 m0, s20
	v_lshl_add_u64 v[228:229], s[68:69], 0, v[138:139]
	global_load_lds_dwordx4 v[228:229], off
	s_waitcnt vmcnt(8) lgkmcnt(0)
	s_barrier
	s_setprio 1
	v_mfma_f32_16x16x32_bf16 v[124:127], v[128:131], v[190:193], v[124:127]
	v_mfma_f32_16x16x32_bf16 v[116:119], v[154:157], v[190:193], v[116:119]
	v_mfma_f32_16x16x32_bf16 v[124:127], v[132:135], v[194:197], v[124:127]
	v_mfma_f32_16x16x32_bf16 v[116:119], v[158:161], v[194:197], v[116:119]
	v_mfma_f32_16x16x32_bf16 v[108:111], v[128:131], v[198:201], v[108:111]
	v_mfma_f32_16x16x32_bf16 v[100:103], v[154:157], v[198:201], v[100:103]
	v_mfma_f32_16x16x32_bf16 v[108:111], v[132:135], v[202:205], v[108:111]
	v_mfma_f32_16x16x32_bf16 v[100:103], v[158:161], v[202:205], v[100:103]
	v_mfma_f32_16x16x32_bf16 v[92:95], v[128:131], v[206:209], v[92:95]
	v_mfma_f32_16x16x32_bf16 v[84:87], v[154:157], v[206:209], v[84:87]
	v_mfma_f32_16x16x32_bf16 v[92:95], v[132:135], v[210:213], v[92:95]
	v_mfma_f32_16x16x32_bf16 v[84:87], v[158:161], v[210:213], v[84:87]
	v_mfma_f32_16x16x32_bf16 v[76:79], v[128:131], v[214:217], v[76:79]
	v_mfma_f32_16x16x32_bf16 v[68:71], v[154:157], v[214:217], v[68:71]
	v_mfma_f32_16x16x32_bf16 v[76:79], v[132:135], v[218:221], v[76:79]
	v_mfma_f32_16x16x32_bf16 v[68:71], v[158:161], v[218:221], v[68:71]
	v_mfma_f32_16x16x32_bf16 v[120:123], v[162:165], v[190:193], v[120:123]
	v_mfma_f32_16x16x32_bf16 v[112:115], v[182:185], v[190:193], v[112:115]
	v_mfma_f32_16x16x32_bf16 v[120:123], v[166:169], v[194:197], v[120:123]
	v_mfma_f32_16x16x32_bf16 v[112:115], v[186:189], v[194:197], v[112:115]
	v_mfma_f32_16x16x32_bf16 v[104:107], v[162:165], v[198:201], v[104:107]
	v_mfma_f32_16x16x32_bf16 v[96:99], v[182:185], v[198:201], v[96:99]
	v_mfma_f32_16x16x32_bf16 v[104:107], v[166:169], v[202:205], v[104:107]
	v_mfma_f32_16x16x32_bf16 v[96:99], v[186:189], v[202:205], v[96:99]
	v_mfma_f32_16x16x32_bf16 v[88:91], v[162:165], v[206:209], v[88:91]
	v_mfma_f32_16x16x32_bf16 v[80:83], v[182:185], v[206:209], v[80:83]
	v_mfma_f32_16x16x32_bf16 v[88:91], v[166:169], v[210:213], v[88:91]
	v_mfma_f32_16x16x32_bf16 v[80:83], v[186:189], v[210:213], v[80:83]
	v_mfma_f32_16x16x32_bf16 v[72:75], v[162:165], v[214:217], v[72:75]
	v_mfma_f32_16x16x32_bf16 v[64:67], v[182:185], v[214:217], v[64:67]
	s_setprio 3
	s_barrier
	v_mfma_f32_16x16x32_bf16 v[72:75], v[166:169], v[218:221], v[72:75]
	v_mfma_f32_16x16x32_bf16 v[64:67], v[186:189], v[218:221], v[64:67]
	s_setprio 0
	s_add_i32 s67, s67, s16
	v_lshl_add_u64 v[170:171], v[170:171], 0, s[74:75]
	s_mov_b32 m0, s67
	ds_read_b128 v[190:193], v180 offset:49152
	ds_read_b128 v[194:197], v180 offset:50176
	ds_read_b128 v[198:201], v180 offset:51200
	ds_read_b128 v[202:205], v180 offset:52224
	ds_read_b128 v[206:209], v180 offset:53248
	ds_read_b128 v[210:213], v180 offset:54272
	ds_read_b128 v[214:217], v180 offset:55296
	ds_read_b128 v[218:221], v180 offset:56320
	global_load_lds_dwordx4 v[170:171], off
	s_add_i32 m0, s67, 0x2000
	s_add_u32 s68, s90, 0x40080
	v_lshl_add_u64 v[170:171], v[222:223], 0, s[74:75]
	s_addc_u32 s69, s91, 0
	s_add_i32 s67, s73, s16
	global_load_lds_dwordx4 v[170:171], off
	s_mov_b32 m0, s67
	v_lshl_add_u64 v[170:171], s[68:69], 0, v[140:141]
	global_load_lds_dwordx4 v[170:171], off
	s_add_i32 m0, s67, 0x2000
	v_lshl_add_u64 v[170:171], s[68:69], 0, v[136:137]
	global_load_lds_dwordx4 v[170:171], off
	s_mov_b32 m0, s23
	v_lshl_add_u64 v[170:171], v[224:225], 0, s[74:75]
	global_load_lds_dwordx4 v[170:171], off
	s_mov_b32 m0, s24
	v_lshl_add_u64 v[170:171], v[226:227], 0, s[74:75]
	global_load_lds_dwordx4 v[170:171], off
	s_waitcnt vmcnt(8) lgkmcnt(0)
	s_barrier
	s_setprio 1
	v_mfma_f32_16x16x32_bf16 v[60:63], v[128:131], v[190:193], v[60:63]
	v_mfma_f32_16x16x32_bf16 v[52:55], v[154:157], v[190:193], v[52:55]
	v_mfma_f32_16x16x32_bf16 v[60:63], v[132:135], v[194:197], v[60:63]
	v_mfma_f32_16x16x32_bf16 v[52:55], v[158:161], v[194:197], v[52:55]
	v_mfma_f32_16x16x32_bf16 v[44:47], v[128:131], v[198:201], v[44:47]
	v_mfma_f32_16x16x32_bf16 v[36:39], v[154:157], v[198:201], v[36:39]
	v_mfma_f32_16x16x32_bf16 v[44:47], v[132:135], v[202:205], v[44:47]
	v_mfma_f32_16x16x32_bf16 v[36:39], v[158:161], v[202:205], v[36:39]
	v_mfma_f32_16x16x32_bf16 v[28:31], v[128:131], v[206:209], v[28:31]
	v_mfma_f32_16x16x32_bf16 v[20:23], v[154:157], v[206:209], v[20:23]
	v_mfma_f32_16x16x32_bf16 v[28:31], v[132:135], v[210:213], v[28:31]
	v_mfma_f32_16x16x32_bf16 v[20:23], v[158:161], v[210:213], v[20:23]
	v_mfma_f32_16x16x32_bf16 v[12:15], v[128:131], v[214:217], v[12:15]
	v_mfma_f32_16x16x32_bf16 v[4:7], v[154:157], v[214:217], v[4:7]
	v_mfma_f32_16x16x32_bf16 v[12:15], v[132:135], v[218:221], v[12:15]
	v_mfma_f32_16x16x32_bf16 v[4:7], v[158:161], v[218:221], v[4:7]
	v_mfma_f32_16x16x32_bf16 v[56:59], v[162:165], v[190:193], v[56:59]
	v_mfma_f32_16x16x32_bf16 v[48:51], v[182:185], v[190:193], v[48:51]
	v_mfma_f32_16x16x32_bf16 v[56:59], v[166:169], v[194:197], v[56:59]
	v_mfma_f32_16x16x32_bf16 v[48:51], v[186:189], v[194:197], v[48:51]
	v_mfma_f32_16x16x32_bf16 v[40:43], v[162:165], v[198:201], v[40:43]
	v_mfma_f32_16x16x32_bf16 v[32:35], v[182:185], v[198:201], v[32:35]
	v_mfma_f32_16x16x32_bf16 v[40:43], v[166:169], v[202:205], v[40:43]
	v_mfma_f32_16x16x32_bf16 v[32:35], v[186:189], v[202:205], v[32:35]
	v_mfma_f32_16x16x32_bf16 v[24:27], v[162:165], v[206:209], v[24:27]
	v_mfma_f32_16x16x32_bf16 v[16:19], v[182:185], v[206:209], v[16:19]
	v_mfma_f32_16x16x32_bf16 v[24:27], v[166:169], v[210:213], v[24:27]
	v_mfma_f32_16x16x32_bf16 v[16:19], v[186:189], v[210:213], v[16:19]
	v_mfma_f32_16x16x32_bf16 v[8:11], v[162:165], v[214:217], v[8:11]
	v_mfma_f32_16x16x32_bf16 v[0:3], v[182:185], v[214:217], v[0:3]
	s_setprio 3
	s_barrier
	v_mfma_f32_16x16x32_bf16 v[8:11], v[166:169], v[218:221], v[8:11]
	v_mfma_f32_16x16x32_bf16 v[0:3], v[186:189], v[218:221], v[0:3]
	s_setprio 0
	s_add_i32 s66, s66, 2
	s_add_u32 s88, s88, 0x100
	s_addc_u32 s89, s89, 0
	s_add_u32 s58, s58, 0x100
	s_addc_u32 s59, s59, 0
	s_cmp_gt_u32 s66, 13
	s_cbranch_scc0 .LBB0_120
	s_branch .Lzskip_0
.Lzv_0_0:
	v_mfma_f32_16x16x32_bf16 v[124:127], v[128:131], v[190:193], 0
	v_mfma_f32_16x16x32_bf16 v[116:119], v[154:157], v[190:193], 0
	v_mfma_f32_16x16x32_bf16 v[124:127], v[132:135], v[194:197], v[124:127]
	v_mfma_f32_16x16x32_bf16 v[116:119], v[158:161], v[194:197], v[116:119]
	v_mfma_f32_16x16x32_bf16 v[108:111], v[128:131], v[198:201], 0
	v_mfma_f32_16x16x32_bf16 v[100:103], v[154:157], v[198:201], 0
	v_mfma_f32_16x16x32_bf16 v[108:111], v[132:135], v[202:205], v[108:111]
	v_mfma_f32_16x16x32_bf16 v[100:103], v[158:161], v[202:205], v[100:103]
	v_mfma_f32_16x16x32_bf16 v[92:95], v[128:131], v[206:209], 0
	v_mfma_f32_16x16x32_bf16 v[84:87], v[154:157], v[206:209], 0
	v_mfma_f32_16x16x32_bf16 v[92:95], v[132:135], v[210:213], v[92:95]
	v_mfma_f32_16x16x32_bf16 v[84:87], v[158:161], v[210:213], v[84:87]
	v_mfma_f32_16x16x32_bf16 v[76:79], v[128:131], v[214:217], 0
	v_mfma_f32_16x16x32_bf16 v[68:71], v[154:157], v[214:217], 0
	v_mfma_f32_16x16x32_bf16 v[76:79], v[132:135], v[218:221], v[76:79]
	v_mfma_f32_16x16x32_bf16 v[68:71], v[158:161], v[218:221], v[68:71]
	v_mfma_f32_16x16x32_bf16 v[120:123], v[162:165], v[190:193], 0
	v_mfma_f32_16x16x32_bf16 v[112:115], v[182:185], v[190:193], 0
	v_mfma_f32_16x16x32_bf16 v[120:123], v[166:169], v[194:197], v[120:123]
	v_mfma_f32_16x16x32_bf16 v[112:115], v[186:189], v[194:197], v[112:115]
	v_mfma_f32_16x16x32_bf16 v[104:107], v[162:165], v[198:201], 0
	v_mfma_f32_16x16x32_bf16 v[96:99], v[182:185], v[198:201], 0
	v_mfma_f32_16x16x32_bf16 v[104:107], v[166:169], v[202:205], v[104:107]
	v_mfma_f32_16x16x32_bf16 v[96:99], v[186:189], v[202:205], v[96:99]
	v_mfma_f32_16x16x32_bf16 v[88:91], v[162:165], v[206:209], 0
	v_mfma_f32_16x16x32_bf16 v[80:83], v[182:185], v[206:209], 0
	v_mfma_f32_16x16x32_bf16 v[88:91], v[166:169], v[210:213], v[88:91]
	v_mfma_f32_16x16x32_bf16 v[80:83], v[186:189], v[210:213], v[80:83]
	v_mfma_f32_16x16x32_bf16 v[72:75], v[162:165], v[214:217], 0
	v_mfma_f32_16x16x32_bf16 v[64:67], v[182:185], v[214:217], 0
	s_setprio 3
	s_barrier
	v_mfma_f32_16x16x32_bf16 v[72:75], v[166:169], v[218:221], v[72:75]
	v_mfma_f32_16x16x32_bf16 v[64:67], v[186:189], v[218:221], v[64:67]
	s_setprio 0
	s_branch .Lzj_0_0
.Lzv_0_1:
	v_mfma_f32_16x16x32_bf16 v[60:63], v[128:131], v[190:193], 0
	v_mfma_f32_16x16x32_bf16 v[52:55], v[154:157], v[190:193], 0
	v_mfma_f32_16x16x32_bf16 v[60:63], v[132:135], v[194:197], v[60:63]
	v_mfma_f32_16x16x32_bf16 v[52:55], v[158:161], v[194:197], v[52:55]
	v_mfma_f32_16x16x32_bf16 v[44:47], v[128:131], v[198:201], 0
	v_mfma_f32_16x16x32_bf16 v[36:39], v[154:157], v[198:201], 0
	v_mfma_f32_16x16x32_bf16 v[44:47], v[132:135], v[202:205], v[44:47]
	v_mfma_f32_16x16x32_bf16 v[36:39], v[158:161], v[202:205], v[36:39]
	v_mfma_f32_16x16x32_bf16 v[28:31], v[128:131], v[206:209], 0
	v_mfma_f32_16x16x32_bf16 v[20:23], v[154:157], v[206:209], 0
	v_mfma_f32_16x16x32_bf16 v[28:31], v[132:135], v[210:213], v[28:31]
	v_mfma_f32_16x16x32_bf16 v[20:23], v[158:161], v[210:213], v[20:23]
	v_mfma_f32_16x16x32_bf16 v[12:15], v[128:131], v[214:217], 0
	v_mfma_f32_16x16x32_bf16 v[4:7], v[154:157], v[214:217], 0
	v_mfma_f32_16x16x32_bf16 v[12:15], v[132:135], v[218:221], v[12:15]
	v_mfma_f32_16x16x32_bf16 v[4:7], v[158:161], v[218:221], v[4:7]
	v_mfma_f32_16x16x32_bf16 v[56:59], v[162:165], v[190:193], 0
	v_mfma_f32_16x16x32_bf16 v[48:51], v[182:185], v[190:193], 0
	v_mfma_f32_16x16x32_bf16 v[56:59], v[166:169], v[194:197], v[56:59]
	v_mfma_f32_16x16x32_bf16 v[48:51], v[186:189], v[194:197], v[48:51]
	v_mfma_f32_16x16x32_bf16 v[40:43], v[162:165], v[198:201], 0
	v_mfma_f32_16x16x32_bf16 v[32:35], v[182:185], v[198:201], 0
	v_mfma_f32_16x16x32_bf16 v[40:43], v[166:169], v[202:205], v[40:43]
	v_mfma_f32_16x16x32_bf16 v[32:35], v[186:189], v[202:205], v[32:35]
	v_mfma_f32_16x16x32_bf16 v[24:27], v[162:165], v[206:209], 0
	v_mfma_f32_16x16x32_bf16 v[16:19], v[182:185], v[206:209], 0
	v_mfma_f32_16x16x32_bf16 v[24:27], v[166:169], v[210:213], v[24:27]
	v_mfma_f32_16x16x32_bf16 v[16:19], v[186:189], v[210:213], v[16:19]
	v_mfma_f32_16x16x32_bf16 v[8:11], v[162:165], v[214:217], 0
	v_mfma_f32_16x16x32_bf16 v[0:3], v[182:185], v[214:217], 0
	s_setprio 3
	s_barrier
	v_mfma_f32_16x16x32_bf16 v[8:11], v[166:169], v[218:221], v[8:11]
	v_mfma_f32_16x16x32_bf16 v[0:3], v[186:189], v[218:221], v[0:3]
	s_setprio 0
	s_branch .Lzj_0_1

.LBB0_272:
	ds_read_b128 v[120:123], v245
	ds_read_b128 v[124:127], v245 offset:1024
	ds_read_b128 v[128:131], v245 offset:2048
	ds_read_b128 v[132:135], v245 offset:3072
	ds_read_b128 v[144:147], v246
	ds_read_b128 v[148:151], v246 offset:1024
	ds_read_b128 v[152:155], v246 offset:2048
	ds_read_b128 v[156:159], v246 offset:3072
	s_add_u32 s59, s86, 0xfff50080
	s_addc_u32 s66, s87, -1
	s_cmp_eq_u32 s58, 40
	s_cselect_b32 s91, s11, s66
	s_cselect_b32 s90, s10, s59
	s_cselect_b32 s89, s85, s57
	s_cselect_b32 s88, s84, s56
	v_lshl_add_u64 v[204:205], s[86:87], 0, v[200:201]
	s_add_i32 m0, s16, 0xc000
	ds_read_b128 v[160:163], v247
	ds_read_b128 v[164:167], v247 offset:1024
	ds_read_b128 v[168:171], v247 offset:2048
	ds_read_b128 v[172:175], v247 offset:3072
	ds_read_b128 v[176:179], v247 offset:4096
	ds_read_b128 v[180:183], v247 offset:5120
	ds_read_b128 v[184:187], v247 offset:6144
	ds_read_b128 v[188:191], v247 offset:7168
	global_load_lds_dwordx4 v[204:205], off
	s_add_i32 m0, s16, 0xe000
	v_lshl_add_u64 v[204:205], s[86:87], 0, v[202:203]
	global_load_lds_dwordx4 v[204:205], off
	s_cmp_eq_u32 s58, -2
	s_waitcnt vmcnt(8) lgkmcnt(0)
	s_barrier
	s_setprio 1
	s_cbranch_scc1 .Lzv_1_0
	v_mfma_f32_16x16x32_bf16 v[140:143], v[120:123], v[160:163], v[140:143]
	v_mfma_f32_16x16x32_bf16 v[136:139], v[128:131], v[160:163], v[136:139]
	v_mfma_f32_16x16x32_bf16 v[140:143], v[124:127], v[164:167], v[140:143]
	v_mfma_f32_16x16x32_bf16 v[136:139], v[132:135], v[164:167], v[136:139]
	v_mfma_f32_16x16x32_bf16 v[108:111], v[120:123], v[168:171], v[108:111]
	v_mfma_f32_16x16x32_bf16 v[104:107], v[128:131], v[168:171], v[104:107]
	v_mfma_f32_16x16x32_bf16 v[108:111], v[124:127], v[172:175], v[108:111]
	v_mfma_f32_16x16x32_bf16 v[104:107], v[132:135], v[172:175], v[104:107]
	v_mfma_f32_16x16x32_bf16 v[92:95], v[120:123], v[176:179], v[92:95]
	v_mfma_f32_16x16x32_bf16 v[88:91], v[128:131], v[176:179], v[88:91]
	v_mfma_f32_16x16x32_bf16 v[92:95], v[124:127], v[180:183], v[92:95]
	v_mfma_f32_16x16x32_bf16 v[88:91], v[132:135], v[180:183], v[88:91]
	v_mfma_f32_16x16x32_bf16 v[76:79], v[120:123], v[184:187], v[76:79]
	v_mfma_f32_16x16x32_bf16 v[72:75], v[128:131], v[184:187], v[72:75]
	v_mfma_f32_16x16x32_bf16 v[76:79], v[124:127], v[188:191], v[76:79]
	v_mfma_f32_16x16x32_bf16 v[72:75], v[132:135], v[188:191], v[72:75]
	v_mfma_f32_16x16x32_bf16 v[116:119], v[144:147], v[160:163], v[116:119]
	v_mfma_f32_16x16x32_bf16 v[112:115], v[152:155], v[160:163], v[112:115]
	v_mfma_f32_16x16x32_bf16 v[116:119], v[148:151], v[164:167], v[116:119]
	v_mfma_f32_16x16x32_bf16 v[112:115], v[156:159], v[164:167], v[112:115]
	v_mfma_f32_16x16x32_bf16 v[100:103], v[144:147], v[168:171], v[100:103]
	v_mfma_f32_16x16x32_bf16 v[96:99], v[152:155], v[168:171], v[96:99]
	v_mfma_f32_16x16x32_bf16 v[100:103], v[148:151], v[172:175], v[100:103]
	v_mfma_f32_16x16x32_bf16 v[96:99], v[156:159], v[172:175], v[96:99]
	v_mfma_f32_16x16x32_bf16 v[84:87], v[144:147], v[176:179], v[84:87]
	v_mfma_f32_16x16x32_bf16 v[80:83], v[152:155], v[176:179], v[80:83]
	v_mfma_f32_16x16x32_bf16 v[84:87], v[148:151], v[180:183], v[84:87]
	v_mfma_f32_16x16x32_bf16 v[80:83], v[156:159], v[180:183], v[80:83]
	v_mfma_f32_16x16x32_bf16 v[68:71], v[144:147], v[184:187], v[68:71]
	v_mfma_f32_16x16x32_bf16 v[64:67], v[152:155], v[184:187], v[64:67]
	s_setprio 3
	s_barrier
	v_mfma_f32_16x16x32_bf16 v[68:71], v[148:151], v[188:191], v[68:71]
	v_mfma_f32_16x16x32_bf16 v[64:67], v[156:159], v[188:191], v[64:67]
	s_setprio 0
.Lzj_1_0:
	s_add_i32 s59, s26, s15
	v_lshl_add_u64 v[204:205], s[88:89], 0, v[194:195]
	s_mov_b32 m0, s59
	ds_read_b128 v[160:163], v247 offset:16384
	ds_read_b128 v[164:167], v247 offset:17408
	ds_read_b128 v[168:171], v247 offset:18432
	ds_read_b128 v[172:175], v247 offset:19456
	ds_read_b128 v[176:179], v247 offset:20480
	ds_read_b128 v[180:183], v247 offset:21504
	ds_read_b128 v[184:187], v247 offset:22528
	ds_read_b128 v[188:191], v247 offset:23552
	global_load_lds_dwordx4 v[204:205], off
	s_add_i32 m0, s59, 0x2000
	s_add_u32 s66, s88, 0xb0000
	v_lshl_add_u64 v[206:207], s[88:89], 0, v[198:199]
	s_addc_u32 s67, s89, 0
	s_add_i32 s59, s27, s15
	global_load_lds_dwordx4 v[206:207], off
	v_lshl_add_u64 v[208:209], s[66:67], 0, v[194:195]
	s_mov_b32 m0, s59
	global_load_lds_dwordx4 v[208:209], off
	s_add_i32 m0, s59, 0x2000
	v_lshl_add_u64 v[208:209], s[66:67], 0, v[198:199]
	global_load_lds_dwordx4 v[208:209], off
	s_mov_b32 m0, s16
	v_lshl_add_u64 v[208:209], s[90:91], 0, v[192:193]
	global_load_lds_dwordx4 v[208:209], off
	s_mov_b32 m0, s17
	v_lshl_add_u64 v[210:211], s[90:91], 0, v[196:197]
	global_load_lds_dwordx4 v[210:211], off
	s_cmp_eq_u32 s58, -2
	s_waitcnt vmcnt(8) lgkmcnt(0)
	s_barrier
	s_setprio 1
	s_cbranch_scc1 .Lzv_1_1
	v_mfma_f32_16x16x32_bf16 v[60:63], v[120:123], v[160:163], v[60:63]
	v_mfma_f32_16x16x32_bf16 v[56:59], v[128:131], v[160:163], v[56:59]
	v_mfma_f32_16x16x32_bf16 v[60:63], v[124:127], v[164:167], v[60:63]
	v_mfma_f32_16x16x32_bf16 v[56:59], v[132:135], v[164:167], v[56:59]
	v_mfma_f32_16x16x32_bf16 v[44:47], v[120:123], v[168:171], v[44:47]
	v_mfma_f32_16x16x32_bf16 v[40:43], v[128:131], v[168:171], v[40:43]
	v_mfma_f32_16x16x32_bf16 v[44:47], v[124:127], v[172:175], v[44:47]
	v_mfma_f32_16x16x32_bf16 v[40:43], v[132:135], v[172:175], v[40:43]
	v_mfma_f32_16x16x32_bf16 v[28:31], v[120:123], v[176:179], v[28:31]
	v_mfma_f32_16x16x32_bf16 v[24:27], v[128:131], v[176:179], v[24:27]
	v_mfma_f32_16x16x32_bf16 v[28:31], v[124:127], v[180:183], v[28:31]
	v_mfma_f32_16x16x32_bf16 v[24:27], v[132:135], v[180:183], v[24:27]
	v_mfma_f32_16x16x32_bf16 v[12:15], v[120:123], v[184:187], v[12:15]
	v_mfma_f32_16x16x32_bf16 v[8:11], v[128:131], v[184:187], v[8:11]
	v_mfma_f32_16x16x32_bf16 v[12:15], v[124:127], v[188:191], v[12:15]
	v_mfma_f32_16x16x32_bf16 v[8:11], v[132:135], v[188:191], v[8:11]
	v_mfma_f32_16x16x32_bf16 v[52:55], v[144:147], v[160:163], v[52:55]
	v_mfma_f32_16x16x32_bf16 v[48:51], v[152:155], v[160:163], v[48:51]
	v_mfma_f32_16x16x32_bf16 v[52:55], v[148:151], v[164:167], v[52:55]
	v_mfma_f32_16x16x32_bf16 v[48:51], v[156:159], v[164:167], v[48:51]
	v_mfma_f32_16x16x32_bf16 v[36:39], v[144:147], v[168:171], v[36:39]
	v_mfma_f32_16x16x32_bf16 v[32:35], v[152:155], v[168:171], v[32:35]
	v_mfma_f32_16x16x32_bf16 v[36:39], v[148:151], v[172:175], v[36:39]
	v_mfma_f32_16x16x32_bf16 v[32:35], v[156:159], v[172:175], v[32:35]
	v_mfma_f32_16x16x32_bf16 v[20:23], v[144:147], v[176:179], v[20:23]
	v_mfma_f32_16x16x32_bf16 v[16:19], v[152:155], v[176:179], v[16:19]
	v_mfma_f32_16x16x32_bf16 v[20:23], v[148:151], v[180:183], v[20:23]
	v_mfma_f32_16x16x32_bf16 v[16:19], v[156:159], v[180:183], v[16:19]
	v_mfma_f32_16x16x32_bf16 v[4:7], v[144:147], v[184:187], v[4:7]
	v_mfma_f32_16x16x32_bf16 v[0:3], v[152:155], v[184:187], v[0:3]
	s_setprio 3
	s_barrier
	v_mfma_f32_16x16x32_bf16 v[4:7], v[148:151], v[188:191], v[4:7]
	v_mfma_f32_16x16x32_bf16 v[0:3], v[156:159], v[188:191], v[0:3]
	s_setprio 0
.Lzj_1_1:
	s_add_i32 s59, 0, 0x18000
	s_add_i32 s68, 0, 0x1c000
	v_add_u32_e32 v132, s59, v243
	v_add_u32_e32 v156, s68, v243
	ds_read_b128 v[120:123], v132
	ds_read_b128 v[124:127], v132 offset:1024
	ds_read_b128 v[128:131], v132 offset:2048
	ds_read_b128 v[132:135], v132 offset:3072
	ds_read_b128 v[144:147], v156
	ds_read_b128 v[148:151], v156 offset:1024
	ds_read_b128 v[152:155], v156 offset:2048
	ds_read_b128 v[156:159], v156 offset:3072
	s_add_u32 s66, s90, 0xb0000
	s_addc_u32 s67, s91, 0
	s_mov_b32 m0, s18
	v_lshl_add_u64 v[212:213], s[66:67], 0, v[192:193]
	ds_read_b128 v[160:163], v247 offset:32768
	ds_read_b128 v[164:167], v247 offset:33792
	ds_read_b128 v[168:171], v247 offset:34816
	ds_read_b128 v[172:175], v247 offset:35840
	ds_read_b128 v[176:179], v247 offset:36864
	ds_read_b128 v[180:183], v247 offset:37888
	ds_read_b128 v[184:187], v247 offset:38912
	ds_read_b128 v[188:191], v247 offset:39936
	global_load_lds_dwordx4 v[212:213], off
	s_mov_b32 m0, s19
	v_lshl_add_u64 v[212:213], s[66:67], 0, v[196:197]
	global_load_lds_dwordx4 v[212:213], off
	s_waitcnt vmcnt(8) lgkmcnt(0)
	s_barrier
	s_setprio 1
	v_mfma_f32_16x16x32_bf16 v[140:143], v[120:123], v[160:163], v[140:143]
	v_mfma_f32_16x16x32_bf16 v[136:139], v[128:131], v[160:163], v[136:139]
	v_mfma_f32_16x16x32_bf16 v[140:143], v[124:127], v[164:167], v[140:143]
	v_mfma_f32_16x16x32_bf16 v[136:139], v[132:135], v[164:167], v[136:139]
	v_mfma_f32_16x16x32_bf16 v[108:111], v[120:123], v[168:171], v[108:111]
	v_mfma_f32_16x16x32_bf16 v[104:107], v[128:131], v[168:171], v[104:107]
	v_mfma_f32_16x16x32_bf16 v[108:111], v[124:127], v[172:175], v[108:111]
	v_mfma_f32_16x16x32_bf16 v[104:107], v[132:135], v[172:175], v[104:107]
	v_mfma_f32_16x16x32_bf16 v[92:95], v[120:123], v[176:179], v[92:95]
	v_mfma_f32_16x16x32_bf16 v[88:91], v[128:131], v[176:179], v[88:91]
	v_mfma_f32_16x16x32_bf16 v[92:95], v[124:127], v[180:183], v[92:95]
	v_mfma_f32_16x16x32_bf16 v[88:91], v[132:135], v[180:183], v[88:91]
	v_mfma_f32_16x16x32_bf16 v[76:79], v[120:123], v[184:187], v[76:79]
	v_mfma_f32_16x16x32_bf16 v[72:75], v[128:131], v[184:187], v[72:75]
	v_mfma_f32_16x16x32_bf16 v[76:79], v[124:127], v[188:191], v[76:79]
	v_mfma_f32_16x16x32_bf16 v[72:75], v[132:135], v[188:191], v[72:75]
	v_mfma_f32_16x16x32_bf16 v[116:119], v[144:147], v[160:163], v[116:119]
	v_mfma_f32_16x16x32_bf16 v[112:115], v[152:155], v[160:163], v[112:115]
	v_mfma_f32_16x16x32_bf16 v[116:119], v[148:151], v[164:167], v[116:119]
	v_mfma_f32_16x16x32_bf16 v[112:115], v[156:159], v[164:167], v[112:115]
	v_mfma_f32_16x16x32_bf16 v[100:103], v[144:147], v[168:171], v[100:103]
	v_mfma_f32_16x16x32_bf16 v[96:99], v[152:155], v[168:171], v[96:99]
	v_mfma_f32_16x16x32_bf16 v[100:103], v[148:151], v[172:175], v[100:103]
	v_mfma_f32_16x16x32_bf16 v[96:99], v[156:159], v[172:175], v[96:99]
	v_mfma_f32_16x16x32_bf16 v[84:87], v[144:147], v[176:179], v[84:87]
	v_mfma_f32_16x16x32_bf16 v[80:83], v[152:155], v[176:179], v[80:83]
	v_mfma_f32_16x16x32_bf16 v[84:87], v[148:151], v[180:183], v[84:87]
	v_mfma_f32_16x16x32_bf16 v[80:83], v[156:159], v[180:183], v[80:83]
	v_mfma_f32_16x16x32_bf16 v[68:71], v[144:147], v[184:187], v[68:71]
	v_mfma_f32_16x16x32_bf16 v[64:67], v[152:155], v[184:187], v[64:67]
	s_setprio 3
	s_barrier
	v_mfma_f32_16x16x32_bf16 v[68:71], v[148:151], v[188:191], v[68:71]
	v_mfma_f32_16x16x32_bf16 v[64:67], v[156:159], v[188:191], v[64:67]
	s_setprio 0
	s_add_i32 s59, s59, s15
	v_lshl_add_u64 v[204:205], v[204:205], 0, s[80:81]
	s_mov_b32 m0, s59
	ds_read_b128 v[160:163], v247 offset:49152
	ds_read_b128 v[164:167], v247 offset:50176
	ds_read_b128 v[168:171], v247 offset:51200
	ds_read_b128 v[172:175], v247 offset:52224
	ds_read_b128 v[176:179], v247 offset:53248
	ds_read_b128 v[180:183], v247 offset:54272
	ds_read_b128 v[184:187], v247 offset:55296
	ds_read_b128 v[188:191], v247 offset:56320
	global_load_lds_dwordx4 v[204:205], off
	s_add_i32 m0, s59, 0x2000
	s_add_u32 s66, s88, 0xb0080
	v_lshl_add_u64 v[204:205], v[206:207], 0, s[80:81]
	s_addc_u32 s67, s89, 0
	s_add_i32 s59, s68, s15
	global_load_lds_dwordx4 v[204:205], off
	s_mov_b32 m0, s59
	v_lshl_add_u64 v[204:205], s[66:67], 0, v[194:195]
	global_load_lds_dwordx4 v[204:205], off
	s_add_i32 m0, s59, 0x2000
	v_lshl_add_u64 v[204:205], s[66:67], 0, v[198:199]
	global_load_lds_dwordx4 v[204:205], off
	s_mov_b32 m0, s21
	v_lshl_add_u64 v[204:205], v[208:209], 0, s[80:81]
	global_load_lds_dwordx4 v[204:205], off
	s_mov_b32 m0, s22
	v_lshl_add_u64 v[204:205], v[210:211], 0, s[80:81]
	global_load_lds_dwordx4 v[204:205], off
	s_waitcnt vmcnt(8) lgkmcnt(0)
	s_barrier
	s_setprio 1
	v_mfma_f32_16x16x32_bf16 v[60:63], v[120:123], v[160:163], v[60:63]
	v_mfma_f32_16x16x32_bf16 v[56:59], v[128:131], v[160:163], v[56:59]
	v_mfma_f32_16x16x32_bf16 v[60:63], v[124:127], v[164:167], v[60:63]
	v_mfma_f32_16x16x32_bf16 v[56:59], v[132:135], v[164:167], v[56:59]
	v_mfma_f32_16x16x32_bf16 v[44:47], v[120:123], v[168:171], v[44:47]
	v_mfma_f32_16x16x32_bf16 v[40:43], v[128:131], v[168:171], v[40:43]
	v_mfma_f32_16x16x32_bf16 v[44:47], v[124:127], v[172:175], v[44:47]
	v_mfma_f32_16x16x32_bf16 v[40:43], v[132:135], v[172:175], v[40:43]
	v_mfma_f32_16x16x32_bf16 v[28:31], v[120:123], v[176:179], v[28:31]
	v_mfma_f32_16x16x32_bf16 v[24:27], v[128:131], v[176:179], v[24:27]
	v_mfma_f32_16x16x32_bf16 v[28:31], v[124:127], v[180:183], v[28:31]
	v_mfma_f32_16x16x32_bf16 v[24:27], v[132:135], v[180:183], v[24:27]
	v_mfma_f32_16x16x32_bf16 v[12:15], v[120:123], v[184:187], v[12:15]
	v_mfma_f32_16x16x32_bf16 v[8:11], v[128:131], v[184:187], v[8:11]
	v_mfma_f32_16x16x32_bf16 v[12:15], v[124:127], v[188:191], v[12:15]
	v_mfma_f32_16x16x32_bf16 v[8:11], v[132:135], v[188:191], v[8:11]
	v_mfma_f32_16x16x32_bf16 v[52:55], v[144:147], v[160:163], v[52:55]
	v_mfma_f32_16x16x32_bf16 v[48:51], v[152:155], v[160:163], v[48:51]
	v_mfma_f32_16x16x32_bf16 v[52:55], v[148:151], v[164:167], v[52:55]
	v_mfma_f32_16x16x32_bf16 v[48:51], v[156:159], v[164:167], v[48:51]
	v_mfma_f32_16x16x32_bf16 v[36:39], v[144:147], v[168:171], v[36:39]
	v_mfma_f32_16x16x32_bf16 v[32:35], v[152:155], v[168:171], v[32:35]
	v_mfma_f32_16x16x32_bf16 v[36:39], v[148:151], v[172:175], v[36:39]
	v_mfma_f32_16x16x32_bf16 v[32:35], v[156:159], v[172:175], v[32:35]
	v_mfma_f32_16x16x32_bf16 v[20:23], v[144:147], v[176:179], v[20:23]
	v_mfma_f32_16x16x32_bf16 v[16:19], v[152:155], v[176:179], v[16:19]
	v_mfma_f32_16x16x32_bf16 v[20:23], v[148:151], v[180:183], v[20:23]
	v_mfma_f32_16x16x32_bf16 v[16:19], v[156:159], v[180:183], v[16:19]
	v_mfma_f32_16x16x32_bf16 v[4:7], v[144:147], v[184:187], v[4:7]
	v_mfma_f32_16x16x32_bf16 v[0:3], v[152:155], v[184:187], v[0:3]
	s_setprio 3
	s_barrier
	v_mfma_f32_16x16x32_bf16 v[4:7], v[148:151], v[188:191], v[4:7]
	v_mfma_f32_16x16x32_bf16 v[0:3], v[156:159], v[188:191], v[0:3]
	s_setprio 0
	s_add_i32 s58, s58, 2
	s_add_u32 s86, s86, 0x100
	s_addc_u32 s87, s87, 0
	s_add_u32 s56, s56, 0x100
	s_addc_u32 s57, s57, 0
	s_cmp_gt_u32 s58, 41
	s_cbranch_scc0 .LBB0_272
	s_branch .Lzskip_1
.Lzv_1_0:
	v_mfma_f32_16x16x32_bf16 v[140:143], v[120:123], v[160:163], 0
	v_mfma_f32_16x16x32_bf16 v[136:139], v[128:131], v[160:163], 0
	v_mfma_f32_16x16x32_bf16 v[140:143], v[124:127], v[164:167], v[140:143]
	v_mfma_f32_16x16x32_bf16 v[136:139], v[132:135], v[164:167], v[136:139]
	v_mfma_f32_16x16x32_bf16 v[108:111], v[120:123], v[168:171], 0
	v_mfma_f32_16x16x32_bf16 v[104:107], v[128:131], v[168:171], 0
	v_mfma_f32_16x16x32_bf16 v[108:111], v[124:127], v[172:175], v[108:111]
	v_mfma_f32_16x16x32_bf16 v[104:107], v[132:135], v[172:175], v[104:107]
	v_mfma_f32_16x16x32_bf16 v[92:95], v[120:123], v[176:179], 0
	v_mfma_f32_16x16x32_bf16 v[88:91], v[128:131], v[176:179], 0
	v_mfma_f32_16x16x32_bf16 v[92:95], v[124:127], v[180:183], v[92:95]
	v_mfma_f32_16x16x32_bf16 v[88:91], v[132:135], v[180:183], v[88:91]
	v_mfma_f32_16x16x32_bf16 v[76:79], v[120:123], v[184:187], 0
	v_mfma_f32_16x16x32_bf16 v[72:75], v[128:131], v[184:187], 0
	v_mfma_f32_16x16x32_bf16 v[76:79], v[124:127], v[188:191], v[76:79]
	v_mfma_f32_16x16x32_bf16 v[72:75], v[132:135], v[188:191], v[72:75]
	v_mfma_f32_16x16x32_bf16 v[116:119], v[144:147], v[160:163], 0
	v_mfma_f32_16x16x32_bf16 v[112:115], v[152:155], v[160:163], 0
	v_mfma_f32_16x16x32_bf16 v[116:119], v[148:151], v[164:167], v[116:119]
	v_mfma_f32_16x16x32_bf16 v[112:115], v[156:159], v[164:167], v[112:115]
	v_mfma_f32_16x16x32_bf16 v[100:103], v[144:147], v[168:171], 0
	v_mfma_f32_16x16x32_bf16 v[96:99], v[152:155], v[168:171], 0
	v_mfma_f32_16x16x32_bf16 v[100:103], v[148:151], v[172:175], v[100:103]
	v_mfma_f32_16x16x32_bf16 v[96:99], v[156:159], v[172:175], v[96:99]
	v_mfma_f32_16x16x32_bf16 v[84:87], v[144:147], v[176:179], 0
	v_mfma_f32_16x16x32_bf16 v[80:83], v[152:155], v[176:179], 0
	v_mfma_f32_16x16x32_bf16 v[84:87], v[148:151], v[180:183], v[84:87]
	v_mfma_f32_16x16x32_bf16 v[80:83], v[156:159], v[180:183], v[80:83]
	v_mfma_f32_16x16x32_bf16 v[68:71], v[144:147], v[184:187], 0
	v_mfma_f32_16x16x32_bf16 v[64:67], v[152:155], v[184:187], 0
	s_setprio 3
	s_barrier
	v_mfma_f32_16x16x32_bf16 v[68:71], v[148:151], v[188:191], v[68:71]
	v_mfma_f32_16x16x32_bf16 v[64:67], v[156:159], v[188:191], v[64:67]
	s_setprio 0
	s_branch .Lzj_1_0
.Lzv_1_1:
	v_mfma_f32_16x16x32_bf16 v[60:63], v[120:123], v[160:163], 0
	v_mfma_f32_16x16x32_bf16 v[56:59], v[128:131], v[160:163], 0
	v_mfma_f32_16x16x32_bf16 v[60:63], v[124:127], v[164:167], v[60:63]
	v_mfma_f32_16x16x32_bf16 v[56:59], v[132:135], v[164:167], v[56:59]
	v_mfma_f32_16x16x32_bf16 v[44:47], v[120:123], v[168:171], 0
	v_mfma_f32_16x16x32_bf16 v[40:43], v[128:131], v[168:171], 0
	v_mfma_f32_16x16x32_bf16 v[44:47], v[124:127], v[172:175], v[44:47]
	v_mfma_f32_16x16x32_bf16 v[40:43], v[132:135], v[172:175], v[40:43]
	v_mfma_f32_16x16x32_bf16 v[28:31], v[120:123], v[176:179], 0
	v_mfma_f32_16x16x32_bf16 v[24:27], v[128:131], v[176:179], 0
	v_mfma_f32_16x16x32_bf16 v[28:31], v[124:127], v[180:183], v[28:31]
	v_mfma_f32_16x16x32_bf16 v[24:27], v[132:135], v[180:183], v[24:27]
	v_mfma_f32_16x16x32_bf16 v[12:15], v[120:123], v[184:187], 0
	v_mfma_f32_16x16x32_bf16 v[8:11], v[128:131], v[184:187], 0
	v_mfma_f32_16x16x32_bf16 v[12:15], v[124:127], v[188:191], v[12:15]
	v_mfma_f32_16x16x32_bf16 v[8:11], v[132:135], v[188:191], v[8:11]
	v_mfma_f32_16x16x32_bf16 v[52:55], v[144:147], v[160:163], 0
	v_mfma_f32_16x16x32_bf16 v[48:51], v[152:155], v[160:163], 0
	v_mfma_f32_16x16x32_bf16 v[52:55], v[148:151], v[164:167], v[52:55]
	v_mfma_f32_16x16x32_bf16 v[48:51], v[156:159], v[164:167], v[48:51]
	v_mfma_f32_16x16x32_bf16 v[36:39], v[144:147], v[168:171], 0
	v_mfma_f32_16x16x32_bf16 v[32:35], v[152:155], v[168:171], 0
	v_mfma_f32_16x16x32_bf16 v[36:39], v[148:151], v[172:175], v[36:39]
	v_mfma_f32_16x16x32_bf16 v[32:35], v[156:159], v[172:175], v[32:35]
	v_mfma_f32_16x16x32_bf16 v[20:23], v[144:147], v[176:179], 0
	v_mfma_f32_16x16x32_bf16 v[16:19], v[152:155], v[176:179], 0
	v_mfma_f32_16x16x32_bf16 v[20:23], v[148:151], v[180:183], v[20:23]
	v_mfma_f32_16x16x32_bf16 v[16:19], v[156:159], v[180:183], v[16:19]
	v_mfma_f32_16x16x32_bf16 v[4:7], v[144:147], v[184:187], 0
	v_mfma_f32_16x16x32_bf16 v[0:3], v[152:155], v[184:187], 0
	s_setprio 3
	s_barrier
	v_mfma_f32_16x16x32_bf16 v[4:7], v[148:151], v[188:191], v[4:7]
	v_mfma_f32_16x16x32_bf16 v[0:3], v[156:159], v[188:191], v[0:3]
	s_setprio 0
	s_branch .Lzj_1_1

.LBB0_429:
	ds_read_b128 v[128:131], v203
	ds_read_b128 v[132:135], v203 offset:1024
	ds_read_b128 v[136:139], v203 offset:2048
	ds_read_b128 v[164:167], v203 offset:3072
	ds_read_b128 v[168:171], v204
	ds_read_b128 v[172:175], v204 offset:1024
	ds_read_b128 v[176:179], v204 offset:2048
	ds_read_b128 v[180:183], v204 offset:3072
	s_add_u32 s6, s88, 0xfffc0080
	s_addc_u32 s7, s89, -1
	s_cmp_eq_u32 s21, 12
	s_cselect_b32 vcc_hi, s15, s7
	s_cselect_b32 vcc_lo, s16, s6
	s_cselect_b32 s7, s17, s20
	s_cselect_b32 s6, s18, s19
	v_lshl_add_u64 v[196:197], s[88:89], 0, v[156:157]
	s_add_i32 m0, s58, 0xc000
	ds_read_b128 v[184:187], v205
	ds_read_b128 v[188:191], v205 offset:1024
	ds_read_b128 v[192:195], v205 offset:2048
	ds_read_b128 v[212:215], v205 offset:3072
	ds_read_b128 v[216:219], v205 offset:4096
	ds_read_b128 v[220:223], v205 offset:5120
	ds_read_b128 v[224:227], v205 offset:6144
	ds_read_b128 v[228:231], v205 offset:7168
	global_load_lds_dwordx4 v[196:197], off
	s_add_i32 m0, s58, 0xe000
	v_lshl_add_u64 v[196:197], s[88:89], 0, v[158:159]
	global_load_lds_dwordx4 v[196:197], off
	s_cmp_eq_u32 s21, -2
	s_waitcnt vmcnt(8) lgkmcnt(0)
	s_barrier
	s_setprio 1
	s_cbranch_scc1 .Lzv_2_0
	v_mfma_f32_16x16x32_bf16 v[124:127], v[128:131], v[184:187], v[124:127]
	v_mfma_f32_16x16x32_bf16 v[116:119], v[136:139], v[184:187], v[116:119]
	v_mfma_f32_16x16x32_bf16 v[124:127], v[132:135], v[188:191], v[124:127]
	v_mfma_f32_16x16x32_bf16 v[116:119], v[164:167], v[188:191], v[116:119]
	v_mfma_f32_16x16x32_bf16 v[108:111], v[128:131], v[192:195], v[108:111]
	v_mfma_f32_16x16x32_bf16 v[100:103], v[136:139], v[192:195], v[100:103]
	v_mfma_f32_16x16x32_bf16 v[108:111], v[132:135], v[212:215], v[108:111]
	v_mfma_f32_16x16x32_bf16 v[100:103], v[164:167], v[212:215], v[100:103]
	v_mfma_f32_16x16x32_bf16 v[92:95], v[128:131], v[216:219], v[92:95]
	v_mfma_f32_16x16x32_bf16 v[84:87], v[136:139], v[216:219], v[84:87]
	v_mfma_f32_16x16x32_bf16 v[92:95], v[132:135], v[220:223], v[92:95]
	v_mfma_f32_16x16x32_bf16 v[84:87], v[164:167], v[220:223], v[84:87]
	v_mfma_f32_16x16x32_bf16 v[76:79], v[128:131], v[224:227], v[76:79]
	v_mfma_f32_16x16x32_bf16 v[68:71], v[136:139], v[224:227], v[68:71]
	v_mfma_f32_16x16x32_bf16 v[76:79], v[132:135], v[228:231], v[76:79]
	v_mfma_f32_16x16x32_bf16 v[68:71], v[164:167], v[228:231], v[68:71]
	v_mfma_f32_16x16x32_bf16 v[120:123], v[168:171], v[184:187], v[120:123]
	v_mfma_f32_16x16x32_bf16 v[112:115], v[176:179], v[184:187], v[112:115]
	v_mfma_f32_16x16x32_bf16 v[120:123], v[172:175], v[188:191], v[120:123]
	v_mfma_f32_16x16x32_bf16 v[112:115], v[180:183], v[188:191], v[112:115]
	v_mfma_f32_16x16x32_bf16 v[104:107], v[168:171], v[192:195], v[104:107]
	v_mfma_f32_16x16x32_bf16 v[96:99], v[176:179], v[192:195], v[96:99]
	v_mfma_f32_16x16x32_bf16 v[104:107], v[172:175], v[212:215], v[104:107]
	v_mfma_f32_16x16x32_bf16 v[96:99], v[180:183], v[212:215], v[96:99]
	v_mfma_f32_16x16x32_bf16 v[88:91], v[168:171], v[216:219], v[88:91]
	v_mfma_f32_16x16x32_bf16 v[80:83], v[176:179], v[216:219], v[80:83]
	v_mfma_f32_16x16x32_bf16 v[88:91], v[172:175], v[220:223], v[88:91]
	v_mfma_f32_16x16x32_bf16 v[80:83], v[180:183], v[220:223], v[80:83]
	v_mfma_f32_16x16x32_bf16 v[72:75], v[168:171], v[224:227], v[72:75]
	v_mfma_f32_16x16x32_bf16 v[64:67], v[176:179], v[224:227], v[64:67]
	s_setprio 3
	s_barrier
	v_mfma_f32_16x16x32_bf16 v[72:75], v[172:175], v[228:231], v[72:75]
	v_mfma_f32_16x16x32_bf16 v[64:67], v[180:183], v[228:231], v[64:67]
	s_setprio 0
.Lzj_2_0:
	s_add_i32 s22, s76, s57
	v_lshl_add_u64 v[196:197], s[6:7], 0, v[142:143]
	s_mov_b32 m0, s22
	ds_read_b128 v[184:187], v205 offset:16384
	ds_read_b128 v[188:191], v205 offset:17408
	ds_read_b128 v[192:195], v205 offset:18432
	ds_read_b128 v[212:215], v205 offset:19456
	ds_read_b128 v[216:219], v205 offset:20480
	ds_read_b128 v[220:223], v205 offset:21504
	ds_read_b128 v[224:227], v205 offset:22528
	ds_read_b128 v[228:231], v205 offset:23552
	global_load_lds_dwordx4 v[196:197], off
	s_add_i32 m0, s22, 0x2000
	s_add_u32 s22, s6, 0x40000
	v_lshl_add_u64 v[232:233], s[6:7], 0, v[146:147]
	s_addc_u32 s23, s7, 0
	s_add_i32 s24, s77, s57
	global_load_lds_dwordx4 v[232:233], off
	v_lshl_add_u64 v[234:235], s[22:23], 0, v[142:143]
	s_mov_b32 m0, s24
	global_load_lds_dwordx4 v[234:235], off
	s_add_i32 m0, s24, 0x2000
	v_lshl_add_u64 v[234:235], s[22:23], 0, v[146:147]
	global_load_lds_dwordx4 v[234:235], off
	s_mov_b32 m0, s58
	v_lshl_add_u64 v[234:235], vcc, 0, v[140:141]
	global_load_lds_dwordx4 v[234:235], off
	s_mov_b32 m0, s59
	v_lshl_add_u64 v[236:237], vcc, 0, v[144:145]
	global_load_lds_dwordx4 v[236:237], off
	s_cmp_eq_u32 s21, -2
	s_waitcnt vmcnt(8) lgkmcnt(0)
	s_barrier
	s_setprio 1
	s_cbranch_scc1 .Lzv_2_1
	v_mfma_f32_16x16x32_bf16 v[60:63], v[128:131], v[184:187], v[60:63]
	v_mfma_f32_16x16x32_bf16 v[52:55], v[136:139], v[184:187], v[52:55]
	v_mfma_f32_16x16x32_bf16 v[60:63], v[132:135], v[188:191], v[60:63]
	v_mfma_f32_16x16x32_bf16 v[52:55], v[164:167], v[188:191], v[52:55]
	v_mfma_f32_16x16x32_bf16 v[44:47], v[128:131], v[192:195], v[44:47]
	v_mfma_f32_16x16x32_bf16 v[36:39], v[136:139], v[192:195], v[36:39]
	v_mfma_f32_16x16x32_bf16 v[44:47], v[132:135], v[212:215], v[44:47]
	v_mfma_f32_16x16x32_bf16 v[36:39], v[164:167], v[212:215], v[36:39]
	v_mfma_f32_16x16x32_bf16 v[28:31], v[128:131], v[216:219], v[28:31]
	v_mfma_f32_16x16x32_bf16 v[20:23], v[136:139], v[216:219], v[20:23]
	v_mfma_f32_16x16x32_bf16 v[28:31], v[132:135], v[220:223], v[28:31]
	v_mfma_f32_16x16x32_bf16 v[20:23], v[164:167], v[220:223], v[20:23]
	v_mfma_f32_16x16x32_bf16 v[12:15], v[128:131], v[224:227], v[12:15]
	v_mfma_f32_16x16x32_bf16 v[4:7], v[136:139], v[224:227], v[4:7]
	v_mfma_f32_16x16x32_bf16 v[12:15], v[132:135], v[228:231], v[12:15]
	v_mfma_f32_16x16x32_bf16 v[4:7], v[164:167], v[228:231], v[4:7]
	v_mfma_f32_16x16x32_bf16 v[56:59], v[168:171], v[184:187], v[56:59]
	v_mfma_f32_16x16x32_bf16 v[48:51], v[176:179], v[184:187], v[48:51]
	v_mfma_f32_16x16x32_bf16 v[56:59], v[172:175], v[188:191], v[56:59]
	v_mfma_f32_16x16x32_bf16 v[48:51], v[180:183], v[188:191], v[48:51]
	v_mfma_f32_16x16x32_bf16 v[40:43], v[168:171], v[192:195], v[40:43]
	v_mfma_f32_16x16x32_bf16 v[32:35], v[176:179], v[192:195], v[32:35]
	v_mfma_f32_16x16x32_bf16 v[40:43], v[172:175], v[212:215], v[40:43]
	v_mfma_f32_16x16x32_bf16 v[32:35], v[180:183], v[212:215], v[32:35]
	v_mfma_f32_16x16x32_bf16 v[24:27], v[168:171], v[216:219], v[24:27]
	v_mfma_f32_16x16x32_bf16 v[16:19], v[176:179], v[216:219], v[16:19]
	v_mfma_f32_16x16x32_bf16 v[24:27], v[172:175], v[220:223], v[24:27]
	v_mfma_f32_16x16x32_bf16 v[16:19], v[180:183], v[220:223], v[16:19]
	v_mfma_f32_16x16x32_bf16 v[8:11], v[168:171], v[224:227], v[8:11]
	v_mfma_f32_16x16x32_bf16 v[0:3], v[176:179], v[224:227], v[0:3]
	s_setprio 3
	s_barrier
	v_mfma_f32_16x16x32_bf16 v[8:11], v[172:175], v[228:231], v[8:11]
	v_mfma_f32_16x16x32_bf16 v[0:3], v[180:183], v[228:231], v[0:3]
	s_setprio 0
.Lzj_2_1:
	s_add_i32 s24, 0, 0x18000
	v_add_u32_e32 v150, s24, v200
	s_add_i32 s25, 0, 0x1c000
	ds_read_b128 v[128:131], v150
	ds_read_b128 v[132:135], v150 offset:1024
	ds_read_b128 v[136:139], v150 offset:2048
	ds_read_b128 v[164:167], v150 offset:3072
	v_add_u32_e32 v150, s25, v200
	ds_read_b128 v[168:171], v150
	ds_read_b128 v[172:175], v150 offset:1024
	ds_read_b128 v[176:179], v150 offset:2048
	ds_read_b128 v[180:183], v150 offset:3072
	s_add_u32 s22, vcc_lo, 0x40000
	s_addc_u32 s23, vcc_hi, 0
	s_mov_b32 m0, s66
	v_lshl_add_u64 v[238:239], s[22:23], 0, v[140:141]
	ds_read_b128 v[184:187], v205 offset:32768
	ds_read_b128 v[188:191], v205 offset:33792
	ds_read_b128 v[192:195], v205 offset:34816
	ds_read_b128 v[212:215], v205 offset:35840
	ds_read_b128 v[216:219], v205 offset:36864
	ds_read_b128 v[220:223], v205 offset:37888
	ds_read_b128 v[224:227], v205 offset:38912
	ds_read_b128 v[228:231], v205 offset:39936
	global_load_lds_dwordx4 v[238:239], off
	s_mov_b32 m0, s67
	v_lshl_add_u64 v[238:239], s[22:23], 0, v[144:145]
	global_load_lds_dwordx4 v[238:239], off
	s_waitcnt vmcnt(8) lgkmcnt(0)
	s_barrier
	s_setprio 1
	v_mfma_f32_16x16x32_bf16 v[124:127], v[128:131], v[184:187], v[124:127]
	v_mfma_f32_16x16x32_bf16 v[116:119], v[136:139], v[184:187], v[116:119]
	v_mfma_f32_16x16x32_bf16 v[124:127], v[132:135], v[188:191], v[124:127]
	v_mfma_f32_16x16x32_bf16 v[116:119], v[164:167], v[188:191], v[116:119]
	v_mfma_f32_16x16x32_bf16 v[108:111], v[128:131], v[192:195], v[108:111]
	v_mfma_f32_16x16x32_bf16 v[100:103], v[136:139], v[192:195], v[100:103]
	v_mfma_f32_16x16x32_bf16 v[108:111], v[132:135], v[212:215], v[108:111]
	v_mfma_f32_16x16x32_bf16 v[100:103], v[164:167], v[212:215], v[100:103]
	v_mfma_f32_16x16x32_bf16 v[92:95], v[128:131], v[216:219], v[92:95]
	v_mfma_f32_16x16x32_bf16 v[84:87], v[136:139], v[216:219], v[84:87]
	v_mfma_f32_16x16x32_bf16 v[92:95], v[132:135], v[220:223], v[92:95]
	v_mfma_f32_16x16x32_bf16 v[84:87], v[164:167], v[220:223], v[84:87]
	v_mfma_f32_16x16x32_bf16 v[76:79], v[128:131], v[224:227], v[76:79]
	v_mfma_f32_16x16x32_bf16 v[68:71], v[136:139], v[224:227], v[68:71]
	v_mfma_f32_16x16x32_bf16 v[76:79], v[132:135], v[228:231], v[76:79]
	v_mfma_f32_16x16x32_bf16 v[68:71], v[164:167], v[228:231], v[68:71]
	v_mfma_f32_16x16x32_bf16 v[120:123], v[168:171], v[184:187], v[120:123]
	v_mfma_f32_16x16x32_bf16 v[112:115], v[176:179], v[184:187], v[112:115]
	v_mfma_f32_16x16x32_bf16 v[120:123], v[172:175], v[188:191], v[120:123]
	v_mfma_f32_16x16x32_bf16 v[112:115], v[180:183], v[188:191], v[112:115]
	v_mfma_f32_16x16x32_bf16 v[104:107], v[168:171], v[192:195], v[104:107]
	v_mfma_f32_16x16x32_bf16 v[96:99], v[176:179], v[192:195], v[96:99]
	v_mfma_f32_16x16x32_bf16 v[104:107], v[172:175], v[212:215], v[104:107]
	v_mfma_f32_16x16x32_bf16 v[96:99], v[180:183], v[212:215], v[96:99]
	v_mfma_f32_16x16x32_bf16 v[88:91], v[168:171], v[216:219], v[88:91]
	v_mfma_f32_16x16x32_bf16 v[80:83], v[176:179], v[216:219], v[80:83]
	v_mfma_f32_16x16x32_bf16 v[88:91], v[172:175], v[220:223], v[88:91]
	v_mfma_f32_16x16x32_bf16 v[80:83], v[180:183], v[220:223], v[80:83]
	v_mfma_f32_16x16x32_bf16 v[72:75], v[168:171], v[224:227], v[72:75]
	v_mfma_f32_16x16x32_bf16 v[64:67], v[176:179], v[224:227], v[64:67]
	s_setprio 3
	s_barrier
	v_mfma_f32_16x16x32_bf16 v[72:75], v[172:175], v[228:231], v[72:75]
	v_mfma_f32_16x16x32_bf16 v[64:67], v[180:183], v[228:231], v[64:67]
	s_setprio 0
	s_add_i32 s22, s24, s57
	v_lshl_add_u64 v[196:197], v[196:197], 0, s[80:81]
	s_mov_b32 m0, s22
	ds_read_b128 v[184:187], v205 offset:49152
	ds_read_b128 v[188:191], v205 offset:50176
	ds_read_b128 v[192:195], v205 offset:51200
	ds_read_b128 v[212:215], v205 offset:52224
	ds_read_b128 v[216:219], v205 offset:53248
	ds_read_b128 v[220:223], v205 offset:54272
	ds_read_b128 v[224:227], v205 offset:55296
	ds_read_b128 v[228:231], v205 offset:56320
	global_load_lds_dwordx4 v[196:197], off
	s_add_i32 m0, s22, 0x2000
	s_add_u32 s6, s6, 0x40080
	v_lshl_add_u64 v[196:197], v[232:233], 0, s[80:81]
	s_addc_u32 s7, s7, 0
	s_add_i32 s22, s25, s57
	global_load_lds_dwordx4 v[196:197], off
	s_mov_b32 m0, s22
	v_lshl_add_u64 v[196:197], s[6:7], 0, v[142:143]
	global_load_lds_dwordx4 v[196:197], off
	s_add_i32 m0, s22, 0x2000
	v_lshl_add_u64 v[196:197], s[6:7], 0, v[146:147]
	global_load_lds_dwordx4 v[196:197], off
	s_mov_b32 m0, s93
	v_lshl_add_u64 v[196:197], v[234:235], 0, s[80:81]
	global_load_lds_dwordx4 v[196:197], off
	s_mov_b32 m0, s69
	v_lshl_add_u64 v[196:197], v[236:237], 0, s[80:81]
	global_load_lds_dwordx4 v[196:197], off
	s_waitcnt vmcnt(8) lgkmcnt(0)
	s_barrier
	s_setprio 1
	v_mfma_f32_16x16x32_bf16 v[60:63], v[128:131], v[184:187], v[60:63]
	v_mfma_f32_16x16x32_bf16 v[52:55], v[136:139], v[184:187], v[52:55]
	v_mfma_f32_16x16x32_bf16 v[60:63], v[132:135], v[188:191], v[60:63]
	v_mfma_f32_16x16x32_bf16 v[52:55], v[164:167], v[188:191], v[52:55]
	v_mfma_f32_16x16x32_bf16 v[44:47], v[128:131], v[192:195], v[44:47]
	v_mfma_f32_16x16x32_bf16 v[36:39], v[136:139], v[192:195], v[36:39]
	v_mfma_f32_16x16x32_bf16 v[44:47], v[132:135], v[212:215], v[44:47]
	v_mfma_f32_16x16x32_bf16 v[36:39], v[164:167], v[212:215], v[36:39]
	v_mfma_f32_16x16x32_bf16 v[28:31], v[128:131], v[216:219], v[28:31]
	v_mfma_f32_16x16x32_bf16 v[20:23], v[136:139], v[216:219], v[20:23]
	v_mfma_f32_16x16x32_bf16 v[28:31], v[132:135], v[220:223], v[28:31]
	v_mfma_f32_16x16x32_bf16 v[20:23], v[164:167], v[220:223], v[20:23]
	v_mfma_f32_16x16x32_bf16 v[12:15], v[128:131], v[224:227], v[12:15]
	v_mfma_f32_16x16x32_bf16 v[4:7], v[136:139], v[224:227], v[4:7]
	v_mfma_f32_16x16x32_bf16 v[12:15], v[132:135], v[228:231], v[12:15]
	v_mfma_f32_16x16x32_bf16 v[4:7], v[164:167], v[228:231], v[4:7]
	v_mfma_f32_16x16x32_bf16 v[56:59], v[168:171], v[184:187], v[56:59]
	v_mfma_f32_16x16x32_bf16 v[48:51], v[176:179], v[184:187], v[48:51]
	v_mfma_f32_16x16x32_bf16 v[56:59], v[172:175], v[188:191], v[56:59]
	v_mfma_f32_16x16x32_bf16 v[48:51], v[180:183], v[188:191], v[48:51]
	v_mfma_f32_16x16x32_bf16 v[40:43], v[168:171], v[192:195], v[40:43]
	v_mfma_f32_16x16x32_bf16 v[32:35], v[176:179], v[192:195], v[32:35]
	v_mfma_f32_16x16x32_bf16 v[40:43], v[172:175], v[212:215], v[40:43]
	v_mfma_f32_16x16x32_bf16 v[32:35], v[180:183], v[212:215], v[32:35]
	v_mfma_f32_16x16x32_bf16 v[24:27], v[168:171], v[216:219], v[24:27]
	v_mfma_f32_16x16x32_bf16 v[16:19], v[176:179], v[216:219], v[16:19]
	v_mfma_f32_16x16x32_bf16 v[24:27], v[172:175], v[220:223], v[24:27]
	v_mfma_f32_16x16x32_bf16 v[16:19], v[180:183], v[220:223], v[16:19]
	v_mfma_f32_16x16x32_bf16 v[8:11], v[168:171], v[224:227], v[8:11]
	v_mfma_f32_16x16x32_bf16 v[0:3], v[176:179], v[224:227], v[0:3]
	s_setprio 3
	s_barrier
	v_mfma_f32_16x16x32_bf16 v[8:11], v[172:175], v[228:231], v[8:11]
	v_mfma_f32_16x16x32_bf16 v[0:3], v[180:183], v[228:231], v[0:3]
	s_setprio 0
	s_add_i32 s21, s21, 2
	s_add_u32 s88, s88, 0x100
	s_addc_u32 s89, s89, 0
	s_add_u32 s19, s19, 0x100
	s_addc_u32 s20, s20, 0
	s_cmp_gt_u32 s21, 13
	s_cbranch_scc0 .LBB0_429
	s_branch .Lzskip_2
.Lzv_2_0:
	v_mfma_f32_16x16x32_bf16 v[124:127], v[128:131], v[184:187], 0
	v_mfma_f32_16x16x32_bf16 v[116:119], v[136:139], v[184:187], 0
	v_mfma_f32_16x16x32_bf16 v[124:127], v[132:135], v[188:191], v[124:127]
	v_mfma_f32_16x16x32_bf16 v[116:119], v[164:167], v[188:191], v[116:119]
	v_mfma_f32_16x16x32_bf16 v[108:111], v[128:131], v[192:195], 0
	v_mfma_f32_16x16x32_bf16 v[100:103], v[136:139], v[192:195], 0
	v_mfma_f32_16x16x32_bf16 v[108:111], v[132:135], v[212:215], v[108:111]
	v_mfma_f32_16x16x32_bf16 v[100:103], v[164:167], v[212:215], v[100:103]
	v_mfma_f32_16x16x32_bf16 v[92:95], v[128:131], v[216:219], 0
	v_mfma_f32_16x16x32_bf16 v[84:87], v[136:139], v[216:219], 0
	v_mfma_f32_16x16x32_bf16 v[92:95], v[132:135], v[220:223], v[92:95]
	v_mfma_f32_16x16x32_bf16 v[84:87], v[164:167], v[220:223], v[84:87]
	v_mfma_f32_16x16x32_bf16 v[76:79], v[128:131], v[224:227], 0
	v_mfma_f32_16x16x32_bf16 v[68:71], v[136:139], v[224:227], 0
	v_mfma_f32_16x16x32_bf16 v[76:79], v[132:135], v[228:231], v[76:79]
	v_mfma_f32_16x16x32_bf16 v[68:71], v[164:167], v[228:231], v[68:71]
	v_mfma_f32_16x16x32_bf16 v[120:123], v[168:171], v[184:187], 0
	v_mfma_f32_16x16x32_bf16 v[112:115], v[176:179], v[184:187], 0
	v_mfma_f32_16x16x32_bf16 v[120:123], v[172:175], v[188:191], v[120:123]
	v_mfma_f32_16x16x32_bf16 v[112:115], v[180:183], v[188:191], v[112:115]
	v_mfma_f32_16x16x32_bf16 v[104:107], v[168:171], v[192:195], 0
	v_mfma_f32_16x16x32_bf16 v[96:99], v[176:179], v[192:195], 0
	v_mfma_f32_16x16x32_bf16 v[104:107], v[172:175], v[212:215], v[104:107]
	v_mfma_f32_16x16x32_bf16 v[96:99], v[180:183], v[212:215], v[96:99]
	v_mfma_f32_16x16x32_bf16 v[88:91], v[168:171], v[216:219], 0
	v_mfma_f32_16x16x32_bf16 v[80:83], v[176:179], v[216:219], 0
	v_mfma_f32_16x16x32_bf16 v[88:91], v[172:175], v[220:223], v[88:91]
	v_mfma_f32_16x16x32_bf16 v[80:83], v[180:183], v[220:223], v[80:83]
	v_mfma_f32_16x16x32_bf16 v[72:75], v[168:171], v[224:227], 0
	v_mfma_f32_16x16x32_bf16 v[64:67], v[176:179], v[224:227], 0
	s_setprio 3
	s_barrier
	v_mfma_f32_16x16x32_bf16 v[72:75], v[172:175], v[228:231], v[72:75]
	v_mfma_f32_16x16x32_bf16 v[64:67], v[180:183], v[228:231], v[64:67]
	s_setprio 0
	s_branch .Lzj_2_0
.Lzv_2_1:
	v_mfma_f32_16x16x32_bf16 v[60:63], v[128:131], v[184:187], 0
	v_mfma_f32_16x16x32_bf16 v[52:55], v[136:139], v[184:187], 0
	v_mfma_f32_16x16x32_bf16 v[60:63], v[132:135], v[188:191], v[60:63]
	v_mfma_f32_16x16x32_bf16 v[52:55], v[164:167], v[188:191], v[52:55]
	v_mfma_f32_16x16x32_bf16 v[44:47], v[128:131], v[192:195], 0
	v_mfma_f32_16x16x32_bf16 v[36:39], v[136:139], v[192:195], 0
	v_mfma_f32_16x16x32_bf16 v[44:47], v[132:135], v[212:215], v[44:47]
	v_mfma_f32_16x16x32_bf16 v[36:39], v[164:167], v[212:215], v[36:39]
	v_mfma_f32_16x16x32_bf16 v[28:31], v[128:131], v[216:219], 0
	v_mfma_f32_16x16x32_bf16 v[20:23], v[136:139], v[216:219], 0
	v_mfma_f32_16x16x32_bf16 v[28:31], v[132:135], v[220:223], v[28:31]
	v_mfma_f32_16x16x32_bf16 v[20:23], v[164:167], v[220:223], v[20:23]
	v_mfma_f32_16x16x32_bf16 v[12:15], v[128:131], v[224:227], 0
	v_mfma_f32_16x16x32_bf16 v[4:7], v[136:139], v[224:227], 0
	v_mfma_f32_16x16x32_bf16 v[12:15], v[132:135], v[228:231], v[12:15]
	v_mfma_f32_16x16x32_bf16 v[4:7], v[164:167], v[228:231], v[4:7]
	v_mfma_f32_16x16x32_bf16 v[56:59], v[168:171], v[184:187], 0
	v_mfma_f32_16x16x32_bf16 v[48:51], v[176:179], v[184:187], 0
	v_mfma_f32_16x16x32_bf16 v[56:59], v[172:175], v[188:191], v[56:59]
	v_mfma_f32_16x16x32_bf16 v[48:51], v[180:183], v[188:191], v[48:51]
	v_mfma_f32_16x16x32_bf16 v[40:43], v[168:171], v[192:195], 0
	v_mfma_f32_16x16x32_bf16 v[32:35], v[176:179], v[192:195], 0
	v_mfma_f32_16x16x32_bf16 v[40:43], v[172:175], v[212:215], v[40:43]
	v_mfma_f32_16x16x32_bf16 v[32:35], v[180:183], v[212:215], v[32:35]
	v_mfma_f32_16x16x32_bf16 v[24:27], v[168:171], v[216:219], 0
	v_mfma_f32_16x16x32_bf16 v[16:19], v[176:179], v[216:219], 0
	v_mfma_f32_16x16x32_bf16 v[24:27], v[172:175], v[220:223], v[24:27]
	v_mfma_f32_16x16x32_bf16 v[16:19], v[180:183], v[220:223], v[16:19]
	v_mfma_f32_16x16x32_bf16 v[8:11], v[168:171], v[224:227], 0
	v_mfma_f32_16x16x32_bf16 v[0:3], v[176:179], v[224:227], 0
	s_setprio 3
	s_barrier
	v_mfma_f32_16x16x32_bf16 v[8:11], v[172:175], v[228:231], v[8:11]
	v_mfma_f32_16x16x32_bf16 v[0:3], v[180:183], v[228:231], v[0:3]
	s_setprio 0
	s_branch .Lzj_2_1

.LBB0_993:
	ds_read_b128 v[120:123], v245
	ds_read_b128 v[124:127], v245 offset:1024
	ds_read_b128 v[128:131], v245 offset:2048
	ds_read_b128 v[132:135], v245 offset:3072
	ds_read_b128 v[144:147], v246
	ds_read_b128 v[148:151], v246 offset:1024
	ds_read_b128 v[152:155], v246 offset:2048
	ds_read_b128 v[156:159], v246 offset:3072
	s_add_u32 s59, s82, 0xfffc0080
	s_addc_u32 s66, s83, -1
	s_cmp_eq_u32 s58, 12
	s_cselect_b32 s87, s53, s66
	s_cselect_b32 s86, s54, s59
	s_cselect_b32 s85, s51, s57
	s_cselect_b32 s84, s55, s56
	v_lshl_add_u64 v[204:205], s[82:83], 0, v[200:201]
	s_add_i32 m0, s16, 0xc000
	ds_read_b128 v[160:163], v247
	ds_read_b128 v[164:167], v247 offset:1024
	ds_read_b128 v[168:171], v247 offset:2048
	ds_read_b128 v[172:175], v247 offset:3072
	ds_read_b128 v[176:179], v247 offset:4096
	ds_read_b128 v[180:183], v247 offset:5120
	ds_read_b128 v[184:187], v247 offset:6144
	ds_read_b128 v[188:191], v247 offset:7168
	global_load_lds_dwordx4 v[204:205], off
	s_add_i32 m0, s16, 0xe000
	v_lshl_add_u64 v[204:205], s[82:83], 0, v[202:203]
	global_load_lds_dwordx4 v[204:205], off
	s_cmp_eq_u32 s58, -2
	s_waitcnt vmcnt(8) lgkmcnt(0)
	s_barrier
	s_setprio 1
	s_cbranch_scc1 .Lzv_3_0
	v_mfma_f32_16x16x32_bf16 v[140:143], v[120:123], v[160:163], v[140:143]
	v_mfma_f32_16x16x32_bf16 v[136:139], v[128:131], v[160:163], v[136:139]
	v_mfma_f32_16x16x32_bf16 v[140:143], v[124:127], v[164:167], v[140:143]
	v_mfma_f32_16x16x32_bf16 v[136:139], v[132:135], v[164:167], v[136:139]
	v_mfma_f32_16x16x32_bf16 v[108:111], v[120:123], v[168:171], v[108:111]
	v_mfma_f32_16x16x32_bf16 v[104:107], v[128:131], v[168:171], v[104:107]
	v_mfma_f32_16x16x32_bf16 v[108:111], v[124:127], v[172:175], v[108:111]
	v_mfma_f32_16x16x32_bf16 v[104:107], v[132:135], v[172:175], v[104:107]
	v_mfma_f32_16x16x32_bf16 v[92:95], v[120:123], v[176:179], v[92:95]
	v_mfma_f32_16x16x32_bf16 v[88:91], v[128:131], v[176:179], v[88:91]
	v_mfma_f32_16x16x32_bf16 v[92:95], v[124:127], v[180:183], v[92:95]
	v_mfma_f32_16x16x32_bf16 v[88:91], v[132:135], v[180:183], v[88:91]
	v_mfma_f32_16x16x32_bf16 v[76:79], v[120:123], v[184:187], v[76:79]
	v_mfma_f32_16x16x32_bf16 v[72:75], v[128:131], v[184:187], v[72:75]
	v_mfma_f32_16x16x32_bf16 v[76:79], v[124:127], v[188:191], v[76:79]
	v_mfma_f32_16x16x32_bf16 v[72:75], v[132:135], v[188:191], v[72:75]
	v_mfma_f32_16x16x32_bf16 v[116:119], v[144:147], v[160:163], v[116:119]
	v_mfma_f32_16x16x32_bf16 v[112:115], v[152:155], v[160:163], v[112:115]
	v_mfma_f32_16x16x32_bf16 v[116:119], v[148:151], v[164:167], v[116:119]
	v_mfma_f32_16x16x32_bf16 v[112:115], v[156:159], v[164:167], v[112:115]
	v_mfma_f32_16x16x32_bf16 v[100:103], v[144:147], v[168:171], v[100:103]
	v_mfma_f32_16x16x32_bf16 v[96:99], v[152:155], v[168:171], v[96:99]
	v_mfma_f32_16x16x32_bf16 v[100:103], v[148:151], v[172:175], v[100:103]
	v_mfma_f32_16x16x32_bf16 v[96:99], v[156:159], v[172:175], v[96:99]
	v_mfma_f32_16x16x32_bf16 v[84:87], v[144:147], v[176:179], v[84:87]
	v_mfma_f32_16x16x32_bf16 v[80:83], v[152:155], v[176:179], v[80:83]
	v_mfma_f32_16x16x32_bf16 v[84:87], v[148:151], v[180:183], v[84:87]
	v_mfma_f32_16x16x32_bf16 v[80:83], v[156:159], v[180:183], v[80:83]
	v_mfma_f32_16x16x32_bf16 v[68:71], v[144:147], v[184:187], v[68:71]
	v_mfma_f32_16x16x32_bf16 v[64:67], v[152:155], v[184:187], v[64:67]
	s_setprio 3
	s_barrier
	v_mfma_f32_16x16x32_bf16 v[68:71], v[148:151], v[188:191], v[68:71]
	v_mfma_f32_16x16x32_bf16 v[64:67], v[156:159], v[188:191], v[64:67]
	s_setprio 0
.Lzj_3_0:
	s_add_i32 s59, s26, s15
	v_lshl_add_u64 v[204:205], s[84:85], 0, v[194:195]
	s_mov_b32 m0, s59
	ds_read_b128 v[160:163], v247 offset:16384
	ds_read_b128 v[164:167], v247 offset:17408
	ds_read_b128 v[168:171], v247 offset:18432
	ds_read_b128 v[172:175], v247 offset:19456
	ds_read_b128 v[176:179], v247 offset:20480
	ds_read_b128 v[180:183], v247 offset:21504
	ds_read_b128 v[184:187], v247 offset:22528
	ds_read_b128 v[188:191], v247 offset:23552
	global_load_lds_dwordx4 v[204:205], off
	s_add_i32 m0, s59, 0x2000
	s_add_u32 s66, s84, 0x40000
	v_lshl_add_u64 v[206:207], s[84:85], 0, v[198:199]
	s_addc_u32 s67, s85, 0
	s_add_i32 s59, s27, s15
	global_load_lds_dwordx4 v[206:207], off
	v_lshl_add_u64 v[208:209], s[66:67], 0, v[194:195]
	s_mov_b32 m0, s59
	global_load_lds_dwordx4 v[208:209], off
	s_add_i32 m0, s59, 0x2000
	v_lshl_add_u64 v[208:209], s[66:67], 0, v[198:199]
	global_load_lds_dwordx4 v[208:209], off
	s_mov_b32 m0, s16
	v_lshl_add_u64 v[208:209], s[86:87], 0, v[192:193]
	global_load_lds_dwordx4 v[208:209], off
	s_mov_b32 m0, s17
	v_lshl_add_u64 v[210:211], s[86:87], 0, v[196:197]
	global_load_lds_dwordx4 v[210:211], off
	s_cmp_eq_u32 s58, -2
	s_waitcnt vmcnt(8) lgkmcnt(0)
	s_barrier
	s_setprio 1
	s_cbranch_scc1 .Lzv_3_1
	v_mfma_f32_16x16x32_bf16 v[60:63], v[120:123], v[160:163], v[60:63]
	v_mfma_f32_16x16x32_bf16 v[56:59], v[128:131], v[160:163], v[56:59]
	v_mfma_f32_16x16x32_bf16 v[60:63], v[124:127], v[164:167], v[60:63]
	v_mfma_f32_16x16x32_bf16 v[56:59], v[132:135], v[164:167], v[56:59]
	v_mfma_f32_16x16x32_bf16 v[44:47], v[120:123], v[168:171], v[44:47]
	v_mfma_f32_16x16x32_bf16 v[40:43], v[128:131], v[168:171], v[40:43]
	v_mfma_f32_16x16x32_bf16 v[44:47], v[124:127], v[172:175], v[44:47]
	v_mfma_f32_16x16x32_bf16 v[40:43], v[132:135], v[172:175], v[40:43]
	v_mfma_f32_16x16x32_bf16 v[28:31], v[120:123], v[176:179], v[28:31]
	v_mfma_f32_16x16x32_bf16 v[24:27], v[128:131], v[176:179], v[24:27]
	v_mfma_f32_16x16x32_bf16 v[28:31], v[124:127], v[180:183], v[28:31]
	v_mfma_f32_16x16x32_bf16 v[24:27], v[132:135], v[180:183], v[24:27]
	v_mfma_f32_16x16x32_bf16 v[12:15], v[120:123], v[184:187], v[12:15]
	v_mfma_f32_16x16x32_bf16 v[8:11], v[128:131], v[184:187], v[8:11]
	v_mfma_f32_16x16x32_bf16 v[12:15], v[124:127], v[188:191], v[12:15]
	v_mfma_f32_16x16x32_bf16 v[8:11], v[132:135], v[188:191], v[8:11]
	v_mfma_f32_16x16x32_bf16 v[52:55], v[144:147], v[160:163], v[52:55]
	v_mfma_f32_16x16x32_bf16 v[48:51], v[152:155], v[160:163], v[48:51]
	v_mfma_f32_16x16x32_bf16 v[52:55], v[148:151], v[164:167], v[52:55]
	v_mfma_f32_16x16x32_bf16 v[48:51], v[156:159], v[164:167], v[48:51]
	v_mfma_f32_16x16x32_bf16 v[36:39], v[144:147], v[168:171], v[36:39]
	v_mfma_f32_16x16x32_bf16 v[32:35], v[152:155], v[168:171], v[32:35]
	v_mfma_f32_16x16x32_bf16 v[36:39], v[148:151], v[172:175], v[36:39]
	v_mfma_f32_16x16x32_bf16 v[32:35], v[156:159], v[172:175], v[32:35]
	v_mfma_f32_16x16x32_bf16 v[20:23], v[144:147], v[176:179], v[20:23]
	v_mfma_f32_16x16x32_bf16 v[16:19], v[152:155], v[176:179], v[16:19]
	v_mfma_f32_16x16x32_bf16 v[20:23], v[148:151], v[180:183], v[20:23]
	v_mfma_f32_16x16x32_bf16 v[16:19], v[156:159], v[180:183], v[16:19]
	v_mfma_f32_16x16x32_bf16 v[4:7], v[144:147], v[184:187], v[4:7]
	v_mfma_f32_16x16x32_bf16 v[0:3], v[152:155], v[184:187], v[0:3]
	s_setprio 3
	s_barrier
	v_mfma_f32_16x16x32_bf16 v[4:7], v[148:151], v[188:191], v[4:7]
	v_mfma_f32_16x16x32_bf16 v[0:3], v[156:159], v[188:191], v[0:3]
	s_setprio 0
.Lzj_3_1:
	s_add_i32 s59, 0, 0x18000
	s_add_i32 s68, 0, 0x1c000
	v_add_u32_e32 v132, s59, v243
	v_add_u32_e32 v156, s68, v243
	ds_read_b128 v[120:123], v132
	ds_read_b128 v[124:127], v132 offset:1024
	ds_read_b128 v[128:131], v132 offset:2048
	ds_read_b128 v[132:135], v132 offset:3072
	ds_read_b128 v[144:147], v156
	ds_read_b128 v[148:151], v156 offset:1024
	ds_read_b128 v[152:155], v156 offset:2048
	ds_read_b128 v[156:159], v156 offset:3072
	s_add_u32 s66, s86, 0x40000
	s_addc_u32 s67, s87, 0
	s_mov_b32 m0, s18
	v_lshl_add_u64 v[212:213], s[66:67], 0, v[192:193]
	ds_read_b128 v[160:163], v247 offset:32768
	ds_read_b128 v[164:167], v247 offset:33792
	ds_read_b128 v[168:171], v247 offset:34816
	ds_read_b128 v[172:175], v247 offset:35840
	ds_read_b128 v[176:179], v247 offset:36864
	ds_read_b128 v[180:183], v247 offset:37888
	ds_read_b128 v[184:187], v247 offset:38912
	ds_read_b128 v[188:191], v247 offset:39936
	global_load_lds_dwordx4 v[212:213], off
	s_mov_b32 m0, s19
	v_lshl_add_u64 v[212:213], s[66:67], 0, v[196:197]
	global_load_lds_dwordx4 v[212:213], off
	s_waitcnt vmcnt(8) lgkmcnt(0)
	s_barrier
	s_setprio 1
	v_mfma_f32_16x16x32_bf16 v[140:143], v[120:123], v[160:163], v[140:143]
	v_mfma_f32_16x16x32_bf16 v[136:139], v[128:131], v[160:163], v[136:139]
	v_mfma_f32_16x16x32_bf16 v[140:143], v[124:127], v[164:167], v[140:143]
	v_mfma_f32_16x16x32_bf16 v[136:139], v[132:135], v[164:167], v[136:139]
	v_mfma_f32_16x16x32_bf16 v[108:111], v[120:123], v[168:171], v[108:111]
	v_mfma_f32_16x16x32_bf16 v[104:107], v[128:131], v[168:171], v[104:107]
	v_mfma_f32_16x16x32_bf16 v[108:111], v[124:127], v[172:175], v[108:111]
	v_mfma_f32_16x16x32_bf16 v[104:107], v[132:135], v[172:175], v[104:107]
	v_mfma_f32_16x16x32_bf16 v[92:95], v[120:123], v[176:179], v[92:95]
	v_mfma_f32_16x16x32_bf16 v[88:91], v[128:131], v[176:179], v[88:91]
	v_mfma_f32_16x16x32_bf16 v[92:95], v[124:127], v[180:183], v[92:95]
	v_mfma_f32_16x16x32_bf16 v[88:91], v[132:135], v[180:183], v[88:91]
	v_mfma_f32_16x16x32_bf16 v[76:79], v[120:123], v[184:187], v[76:79]
	v_mfma_f32_16x16x32_bf16 v[72:75], v[128:131], v[184:187], v[72:75]
	v_mfma_f32_16x16x32_bf16 v[76:79], v[124:127], v[188:191], v[76:79]
	v_mfma_f32_16x16x32_bf16 v[72:75], v[132:135], v[188:191], v[72:75]
	v_mfma_f32_16x16x32_bf16 v[116:119], v[144:147], v[160:163], v[116:119]
	v_mfma_f32_16x16x32_bf16 v[112:115], v[152:155], v[160:163], v[112:115]
	v_mfma_f32_16x16x32_bf16 v[116:119], v[148:151], v[164:167], v[116:119]
	v_mfma_f32_16x16x32_bf16 v[112:115], v[156:159], v[164:167], v[112:115]
	v_mfma_f32_16x16x32_bf16 v[100:103], v[144:147], v[168:171], v[100:103]
	v_mfma_f32_16x16x32_bf16 v[96:99], v[152:155], v[168:171], v[96:99]
	v_mfma_f32_16x16x32_bf16 v[100:103], v[148:151], v[172:175], v[100:103]
	v_mfma_f32_16x16x32_bf16 v[96:99], v[156:159], v[172:175], v[96:99]
	v_mfma_f32_16x16x32_bf16 v[84:87], v[144:147], v[176:179], v[84:87]
	v_mfma_f32_16x16x32_bf16 v[80:83], v[152:155], v[176:179], v[80:83]
	v_mfma_f32_16x16x32_bf16 v[84:87], v[148:151], v[180:183], v[84:87]
	v_mfma_f32_16x16x32_bf16 v[80:83], v[156:159], v[180:183], v[80:83]
	v_mfma_f32_16x16x32_bf16 v[68:71], v[144:147], v[184:187], v[68:71]
	v_mfma_f32_16x16x32_bf16 v[64:67], v[152:155], v[184:187], v[64:67]
	s_setprio 3
	s_barrier
	v_mfma_f32_16x16x32_bf16 v[68:71], v[148:151], v[188:191], v[68:71]
	v_mfma_f32_16x16x32_bf16 v[64:67], v[156:159], v[188:191], v[64:67]
	s_setprio 0
	s_add_i32 s59, s59, s15
	v_lshl_add_u64 v[204:205], v[204:205], 0, s[46:47]
	s_mov_b32 m0, s59
	ds_read_b128 v[160:163], v247 offset:49152
	ds_read_b128 v[164:167], v247 offset:50176
	ds_read_b128 v[168:171], v247 offset:51200
	ds_read_b128 v[172:175], v247 offset:52224
	ds_read_b128 v[176:179], v247 offset:53248
	ds_read_b128 v[180:183], v247 offset:54272
	ds_read_b128 v[184:187], v247 offset:55296
	ds_read_b128 v[188:191], v247 offset:56320
	global_load_lds_dwordx4 v[204:205], off
	s_add_i32 m0, s59, 0x2000
	s_add_u32 s66, s84, 0x40080
	v_lshl_add_u64 v[204:205], v[206:207], 0, s[46:47]
	s_addc_u32 s67, s85, 0
	s_add_i32 s59, s68, s15
	global_load_lds_dwordx4 v[204:205], off
	s_mov_b32 m0, s59
	v_lshl_add_u64 v[204:205], s[66:67], 0, v[194:195]
	global_load_lds_dwordx4 v[204:205], off
	s_add_i32 m0, s59, 0x2000
	v_lshl_add_u64 v[204:205], s[66:67], 0, v[198:199]
	global_load_lds_dwordx4 v[204:205], off
	s_mov_b32 m0, s21
	v_lshl_add_u64 v[204:205], v[208:209], 0, s[46:47]
	global_load_lds_dwordx4 v[204:205], off
	s_mov_b32 m0, s22
	v_lshl_add_u64 v[204:205], v[210:211], 0, s[46:47]
	global_load_lds_dwordx4 v[204:205], off
	s_waitcnt vmcnt(8) lgkmcnt(0)
	s_barrier
	s_setprio 1
	v_mfma_f32_16x16x32_bf16 v[60:63], v[120:123], v[160:163], v[60:63]
	v_mfma_f32_16x16x32_bf16 v[56:59], v[128:131], v[160:163], v[56:59]
	v_mfma_f32_16x16x32_bf16 v[60:63], v[124:127], v[164:167], v[60:63]
	v_mfma_f32_16x16x32_bf16 v[56:59], v[132:135], v[164:167], v[56:59]
	v_mfma_f32_16x16x32_bf16 v[44:47], v[120:123], v[168:171], v[44:47]
	v_mfma_f32_16x16x32_bf16 v[40:43], v[128:131], v[168:171], v[40:43]
	v_mfma_f32_16x16x32_bf16 v[44:47], v[124:127], v[172:175], v[44:47]
	v_mfma_f32_16x16x32_bf16 v[40:43], v[132:135], v[172:175], v[40:43]
	v_mfma_f32_16x16x32_bf16 v[28:31], v[120:123], v[176:179], v[28:31]
	v_mfma_f32_16x16x32_bf16 v[24:27], v[128:131], v[176:179], v[24:27]
	v_mfma_f32_16x16x32_bf16 v[28:31], v[124:127], v[180:183], v[28:31]
	v_mfma_f32_16x16x32_bf16 v[24:27], v[132:135], v[180:183], v[24:27]
	v_mfma_f32_16x16x32_bf16 v[12:15], v[120:123], v[184:187], v[12:15]
	v_mfma_f32_16x16x32_bf16 v[8:11], v[128:131], v[184:187], v[8:11]
	v_mfma_f32_16x16x32_bf16 v[12:15], v[124:127], v[188:191], v[12:15]
	v_mfma_f32_16x16x32_bf16 v[8:11], v[132:135], v[188:191], v[8:11]
	v_mfma_f32_16x16x32_bf16 v[52:55], v[144:147], v[160:163], v[52:55]
	v_mfma_f32_16x16x32_bf16 v[48:51], v[152:155], v[160:163], v[48:51]
	v_mfma_f32_16x16x32_bf16 v[52:55], v[148:151], v[164:167], v[52:55]
	v_mfma_f32_16x16x32_bf16 v[48:51], v[156:159], v[164:167], v[48:51]
	v_mfma_f32_16x16x32_bf16 v[36:39], v[144:147], v[168:171], v[36:39]
	v_mfma_f32_16x16x32_bf16 v[32:35], v[152:155], v[168:171], v[32:35]
	v_mfma_f32_16x16x32_bf16 v[36:39], v[148:151], v[172:175], v[36:39]
	v_mfma_f32_16x16x32_bf16 v[32:35], v[156:159], v[172:175], v[32:35]
	v_mfma_f32_16x16x32_bf16 v[20:23], v[144:147], v[176:179], v[20:23]
	v_mfma_f32_16x16x32_bf16 v[16:19], v[152:155], v[176:179], v[16:19]
	v_mfma_f32_16x16x32_bf16 v[20:23], v[148:151], v[180:183], v[20:23]
	v_mfma_f32_16x16x32_bf16 v[16:19], v[156:159], v[180:183], v[16:19]
	v_mfma_f32_16x16x32_bf16 v[4:7], v[144:147], v[184:187], v[4:7]
	v_mfma_f32_16x16x32_bf16 v[0:3], v[152:155], v[184:187], v[0:3]
	s_setprio 3
	s_barrier
	v_mfma_f32_16x16x32_bf16 v[4:7], v[148:151], v[188:191], v[4:7]
	v_mfma_f32_16x16x32_bf16 v[0:3], v[156:159], v[188:191], v[0:3]
	s_setprio 0
	s_add_i32 s58, s58, 2
	s_add_u32 s82, s82, 0x100
	s_addc_u32 s83, s83, 0
	s_add_u32 s56, s56, 0x100
	s_addc_u32 s57, s57, 0
	s_cmp_gt_u32 s58, 13
	s_cbranch_scc0 .LBB0_993
	s_branch .Lzskip_3

.LBB0_1148:
	ds_read_b128 v[146:149], v174
	ds_read_b128 v[150:153], v174 offset:1024
	ds_read_b128 v[154:157], v174 offset:2048
	ds_read_b128 v[158:161], v174 offset:3072
	ds_read_b128 v[162:165], v175
	ds_read_b128 v[178:181], v175 offset:1024
	ds_read_b128 v[182:185], v175 offset:2048
	ds_read_b128 v[186:189], v175 offset:3072
	s_add_u32 s67, s78, 0xfffc0080
	s_addc_u32 s68, s79, -1
	s_cmp_eq_u32 s66, 12
	s_cselect_b32 s83, s49, s68
	s_cselect_b32 s82, s54, s67
	s_cselect_b32 s81, s47, s59
	s_cselect_b32 s80, s55, s58
	v_lshl_add_u64 v[166:167], s[78:79], 0, v[136:137]
	s_add_i32 m0, s17, 0xc000
	ds_read_b128 v[190:193], v176
	ds_read_b128 v[194:197], v176 offset:1024
	ds_read_b128 v[198:201], v176 offset:2048
	ds_read_b128 v[202:205], v176 offset:3072
	ds_read_b128 v[206:209], v176 offset:4096
	ds_read_b128 v[210:213], v176 offset:5120
	ds_read_b128 v[214:217], v176 offset:6144
	ds_read_b128 v[218:221], v176 offset:7168
	global_load_lds_dwordx4 v[166:167], off
	s_add_i32 m0, s17, 0xe000
	v_lshl_add_u64 v[166:167], s[78:79], 0, v[140:141]
	global_load_lds_dwordx4 v[166:167], off
	s_cmp_eq_u32 s66, -2
	s_waitcnt vmcnt(8) lgkmcnt(0)
	s_barrier
	s_setprio 1
	s_cbranch_scc1 .Lzv_4_0
	v_mfma_f32_16x16x32_bf16 v[124:127], v[146:149], v[190:193], v[124:127]
	v_mfma_f32_16x16x32_bf16 v[116:119], v[154:157], v[190:193], v[116:119]
	v_mfma_f32_16x16x32_bf16 v[124:127], v[150:153], v[194:197], v[124:127]
	v_mfma_f32_16x16x32_bf16 v[116:119], v[158:161], v[194:197], v[116:119]
	v_mfma_f32_16x16x32_bf16 v[108:111], v[146:149], v[198:201], v[108:111]
	v_mfma_f32_16x16x32_bf16 v[100:103], v[154:157], v[198:201], v[100:103]
	v_mfma_f32_16x16x32_bf16 v[108:111], v[150:153], v[202:205], v[108:111]
	v_mfma_f32_16x16x32_bf16 v[100:103], v[158:161], v[202:205], v[100:103]
	v_mfma_f32_16x16x32_bf16 v[92:95], v[146:149], v[206:209], v[92:95]
	v_mfma_f32_16x16x32_bf16 v[84:87], v[154:157], v[206:209], v[84:87]
	v_mfma_f32_16x16x32_bf16 v[92:95], v[150:153], v[210:213], v[92:95]
	v_mfma_f32_16x16x32_bf16 v[84:87], v[158:161], v[210:213], v[84:87]
	v_mfma_f32_16x16x32_bf16 v[76:79], v[146:149], v[214:217], v[76:79]
	v_mfma_f32_16x16x32_bf16 v[68:71], v[154:157], v[214:217], v[68:71]
	v_mfma_f32_16x16x32_bf16 v[76:79], v[150:153], v[218:221], v[76:79]
	v_mfma_f32_16x16x32_bf16 v[68:71], v[158:161], v[218:221], v[68:71]
	v_mfma_f32_16x16x32_bf16 v[120:123], v[162:165], v[190:193], v[120:123]
	v_mfma_f32_16x16x32_bf16 v[112:115], v[182:185], v[190:193], v[112:115]
	v_mfma_f32_16x16x32_bf16 v[120:123], v[178:181], v[194:197], v[120:123]
	v_mfma_f32_16x16x32_bf16 v[112:115], v[186:189], v[194:197], v[112:115]
	v_mfma_f32_16x16x32_bf16 v[104:107], v[162:165], v[198:201], v[104:107]
	v_mfma_f32_16x16x32_bf16 v[96:99], v[182:185], v[198:201], v[96:99]
	v_mfma_f32_16x16x32_bf16 v[104:107], v[178:181], v[202:205], v[104:107]
	v_mfma_f32_16x16x32_bf16 v[96:99], v[186:189], v[202:205], v[96:99]
	v_mfma_f32_16x16x32_bf16 v[88:91], v[162:165], v[206:209], v[88:91]
	v_mfma_f32_16x16x32_bf16 v[80:83], v[182:185], v[206:209], v[80:83]
	v_mfma_f32_16x16x32_bf16 v[88:91], v[178:181], v[210:213], v[88:91]
	v_mfma_f32_16x16x32_bf16 v[80:83], v[186:189], v[210:213], v[80:83]
	v_mfma_f32_16x16x32_bf16 v[72:75], v[162:165], v[214:217], v[72:75]
	v_mfma_f32_16x16x32_bf16 v[64:67], v[182:185], v[214:217], v[64:67]
	s_setprio 3
	s_barrier
	v_mfma_f32_16x16x32_bf16 v[72:75], v[178:181], v[218:221], v[72:75]
	v_mfma_f32_16x16x32_bf16 v[64:67], v[186:189], v[218:221], v[64:67]
	s_setprio 0
.Lzj_4_0:
	s_add_i32 s67, s25, s16
	v_lshl_add_u64 v[166:167], s[80:81], 0, v[132:133]
	s_mov_b32 m0, s67
	ds_read_b128 v[190:193], v176 offset:16384
	ds_read_b128 v[194:197], v176 offset:17408
	ds_read_b128 v[198:201], v176 offset:18432
	ds_read_b128 v[202:205], v176 offset:19456
	ds_read_b128 v[206:209], v176 offset:20480
	ds_read_b128 v[210:213], v176 offset:21504
	ds_read_b128 v[214:217], v176 offset:22528
	ds_read_b128 v[218:221], v176 offset:23552
	global_load_lds_dwordx4 v[166:167], off
	s_add_i32 m0, s67, 0x2000
	s_add_u32 s68, s80, 0x40000
	v_lshl_add_u64 v[222:223], s[80:81], 0, v[128:129]
	s_addc_u32 s69, s81, 0
	s_add_i32 s67, s26, s16
	global_load_lds_dwordx4 v[222:223], off
	v_lshl_add_u64 v[224:225], s[68:69], 0, v[132:133]
	s_mov_b32 m0, s67
	global_load_lds_dwordx4 v[224:225], off
	s_add_i32 m0, s67, 0x2000
	v_lshl_add_u64 v[224:225], s[68:69], 0, v[128:129]
	global_load_lds_dwordx4 v[224:225], off
	s_mov_b32 m0, s17
	v_lshl_add_u64 v[224:225], s[82:83], 0, v[134:135]
	global_load_lds_dwordx4 v[224:225], off
	s_mov_b32 m0, s18
	v_lshl_add_u64 v[226:227], s[82:83], 0, v[130:131]
	global_load_lds_dwordx4 v[226:227], off
	s_cmp_eq_u32 s66, -2
	s_waitcnt vmcnt(8) lgkmcnt(0)
	s_barrier
	s_setprio 1
	s_cbranch_scc1 .Lzv_4_1
	v_mfma_f32_16x16x32_bf16 v[60:63], v[146:149], v[190:193], v[60:63]
	v_mfma_f32_16x16x32_bf16 v[52:55], v[154:157], v[190:193], v[52:55]
	v_mfma_f32_16x16x32_bf16 v[60:63], v[150:153], v[194:197], v[60:63]
	v_mfma_f32_16x16x32_bf16 v[52:55], v[158:161], v[194:197], v[52:55]
	v_mfma_f32_16x16x32_bf16 v[44:47], v[146:149], v[198:201], v[44:47]
	v_mfma_f32_16x16x32_bf16 v[36:39], v[154:157], v[198:201], v[36:39]
	v_mfma_f32_16x16x32_bf16 v[44:47], v[150:153], v[202:205], v[44:47]
	v_mfma_f32_16x16x32_bf16 v[36:39], v[158:161], v[202:205], v[36:39]
	v_mfma_f32_16x16x32_bf16 v[28:31], v[146:149], v[206:209], v[28:31]
	v_mfma_f32_16x16x32_bf16 v[20:23], v[154:157], v[206:209], v[20:23]
	v_mfma_f32_16x16x32_bf16 v[28:31], v[150:153], v[210:213], v[28:31]
	v_mfma_f32_16x16x32_bf16 v[20:23], v[158:161], v[210:213], v[20:23]
	v_mfma_f32_16x16x32_bf16 v[12:15], v[146:149], v[214:217], v[12:15]
	v_mfma_f32_16x16x32_bf16 v[4:7], v[154:157], v[214:217], v[4:7]
	v_mfma_f32_16x16x32_bf16 v[12:15], v[150:153], v[218:221], v[12:15]
	v_mfma_f32_16x16x32_bf16 v[4:7], v[158:161], v[218:221], v[4:7]
	v_mfma_f32_16x16x32_bf16 v[56:59], v[162:165], v[190:193], v[56:59]
	v_mfma_f32_16x16x32_bf16 v[48:51], v[182:185], v[190:193], v[48:51]
	v_mfma_f32_16x16x32_bf16 v[56:59], v[178:181], v[194:197], v[56:59]
	v_mfma_f32_16x16x32_bf16 v[48:51], v[186:189], v[194:197], v[48:51]
	v_mfma_f32_16x16x32_bf16 v[40:43], v[162:165], v[198:201], v[40:43]
	v_mfma_f32_16x16x32_bf16 v[32:35], v[182:185], v[198:201], v[32:35]
	v_mfma_f32_16x16x32_bf16 v[40:43], v[178:181], v[202:205], v[40:43]
	v_mfma_f32_16x16x32_bf16 v[32:35], v[186:189], v[202:205], v[32:35]
	v_mfma_f32_16x16x32_bf16 v[24:27], v[162:165], v[206:209], v[24:27]
	v_mfma_f32_16x16x32_bf16 v[16:19], v[182:185], v[206:209], v[16:19]
	v_mfma_f32_16x16x32_bf16 v[24:27], v[178:181], v[210:213], v[24:27]
	v_mfma_f32_16x16x32_bf16 v[16:19], v[186:189], v[210:213], v[16:19]
	v_mfma_f32_16x16x32_bf16 v[8:11], v[162:165], v[214:217], v[8:11]
	v_mfma_f32_16x16x32_bf16 v[0:3], v[182:185], v[214:217], v[0:3]
	s_setprio 3
	s_barrier
	v_mfma_f32_16x16x32_bf16 v[8:11], v[178:181], v[218:221], v[8:11]
	v_mfma_f32_16x16x32_bf16 v[0:3], v[186:189], v[218:221], v[0:3]
	s_setprio 0
.Lzj_4_1:
	s_add_i32 s67, 0, 0x18000
	s_add_i32 s73, 0, 0x1c000
	v_add_u32_e32 v158, s67, v171
	v_add_u32_e32 v186, s73, v171
	ds_read_b128 v[146:149], v158
	ds_read_b128 v[150:153], v158 offset:1024
	ds_read_b128 v[154:157], v158 offset:2048
	ds_read_b128 v[158:161], v158 offset:3072
	ds_read_b128 v[162:165], v186
	ds_read_b128 v[178:181], v186 offset:1024
	ds_read_b128 v[182:185], v186 offset:2048
	ds_read_b128 v[186:189], v186 offset:3072
	s_add_u32 s68, s82, 0x40000
	s_addc_u32 s69, s83, 0
	s_mov_b32 m0, s19
	v_lshl_add_u64 v[228:229], s[68:69], 0, v[134:135]
	ds_read_b128 v[190:193], v176 offset:32768
	ds_read_b128 v[194:197], v176 offset:33792
	ds_read_b128 v[198:201], v176 offset:34816
	ds_read_b128 v[202:205], v176 offset:35840
	ds_read_b128 v[206:209], v176 offset:36864
	ds_read_b128 v[210:213], v176 offset:37888
	ds_read_b128 v[214:217], v176 offset:38912
	ds_read_b128 v[218:221], v176 offset:39936
	global_load_lds_dwordx4 v[228:229], off
	s_mov_b32 m0, s20
	v_lshl_add_u64 v[228:229], s[68:69], 0, v[130:131]
	global_load_lds_dwordx4 v[228:229], off
	s_waitcnt vmcnt(8) lgkmcnt(0)
	s_barrier
	s_setprio 1
	v_mfma_f32_16x16x32_bf16 v[124:127], v[146:149], v[190:193], v[124:127]
	v_mfma_f32_16x16x32_bf16 v[116:119], v[154:157], v[190:193], v[116:119]
	v_mfma_f32_16x16x32_bf16 v[124:127], v[150:153], v[194:197], v[124:127]
	v_mfma_f32_16x16x32_bf16 v[116:119], v[158:161], v[194:197], v[116:119]
	v_mfma_f32_16x16x32_bf16 v[108:111], v[146:149], v[198:201], v[108:111]
	v_mfma_f32_16x16x32_bf16 v[100:103], v[154:157], v[198:201], v[100:103]
	v_mfma_f32_16x16x32_bf16 v[108:111], v[150:153], v[202:205], v[108:111]
	v_mfma_f32_16x16x32_bf16 v[100:103], v[158:161], v[202:205], v[100:103]
	v_mfma_f32_16x16x32_bf16 v[92:95], v[146:149], v[206:209], v[92:95]
	v_mfma_f32_16x16x32_bf16 v[84:87], v[154:157], v[206:209], v[84:87]
	v_mfma_f32_16x16x32_bf16 v[92:95], v[150:153], v[210:213], v[92:95]
	v_mfma_f32_16x16x32_bf16 v[84:87], v[158:161], v[210:213], v[84:87]
	v_mfma_f32_16x16x32_bf16 v[76:79], v[146:149], v[214:217], v[76:79]
	v_mfma_f32_16x16x32_bf16 v[68:71], v[154:157], v[214:217], v[68:71]
	v_mfma_f32_16x16x32_bf16 v[76:79], v[150:153], v[218:221], v[76:79]
	v_mfma_f32_16x16x32_bf16 v[68:71], v[158:161], v[218:221], v[68:71]
	v_mfma_f32_16x16x32_bf16 v[120:123], v[162:165], v[190:193], v[120:123]
	v_mfma_f32_16x16x32_bf16 v[112:115], v[182:185], v[190:193], v[112:115]
	v_mfma_f32_16x16x32_bf16 v[120:123], v[178:181], v[194:197], v[120:123]
	v_mfma_f32_16x16x32_bf16 v[112:115], v[186:189], v[194:197], v[112:115]
	v_mfma_f32_16x16x32_bf16 v[104:107], v[162:165], v[198:201], v[104:107]
	v_mfma_f32_16x16x32_bf16 v[96:99], v[182:185], v[198:201], v[96:99]
	v_mfma_f32_16x16x32_bf16 v[104:107], v[178:181], v[202:205], v[104:107]
	v_mfma_f32_16x16x32_bf16 v[96:99], v[186:189], v[202:205], v[96:99]
	v_mfma_f32_16x16x32_bf16 v[88:91], v[162:165], v[206:209], v[88:91]
	v_mfma_f32_16x16x32_bf16 v[80:83], v[182:185], v[206:209], v[80:83]
	v_mfma_f32_16x16x32_bf16 v[88:91], v[178:181], v[210:213], v[88:91]
	v_mfma_f32_16x16x32_bf16 v[80:83], v[186:189], v[210:213], v[80:83]
	v_mfma_f32_16x16x32_bf16 v[72:75], v[162:165], v[214:217], v[72:75]
	v_mfma_f32_16x16x32_bf16 v[64:67], v[182:185], v[214:217], v[64:67]
	s_setprio 3
	s_barrier
	v_mfma_f32_16x16x32_bf16 v[72:75], v[178:181], v[218:221], v[72:75]
	v_mfma_f32_16x16x32_bf16 v[64:67], v[186:189], v[218:221], v[64:67]
	s_setprio 0
	s_add_i32 s67, s67, s16
	v_lshl_add_u64 v[166:167], v[166:167], 0, s[10:11]
	s_mov_b32 m0, s67
	ds_read_b128 v[190:193], v176 offset:49152
	ds_read_b128 v[194:197], v176 offset:50176
	ds_read_b128 v[198:201], v176 offset:51200
	ds_read_b128 v[202:205], v176 offset:52224
	ds_read_b128 v[206:209], v176 offset:53248
	ds_read_b128 v[210:213], v176 offset:54272
	ds_read_b128 v[214:217], v176 offset:55296
	ds_read_b128 v[218:221], v176 offset:56320
	global_load_lds_dwordx4 v[166:167], off
	s_add_i32 m0, s67, 0x2000
	s_add_u32 s68, s80, 0x40080
	v_lshl_add_u64 v[166:167], v[222:223], 0, s[10:11]
	s_addc_u32 s69, s81, 0
	s_add_i32 s67, s73, s16
	global_load_lds_dwordx4 v[166:167], off
	s_mov_b32 m0, s67
	v_lshl_add_u64 v[166:167], s[68:69], 0, v[132:133]
	global_load_lds_dwordx4 v[166:167], off
	s_add_i32 m0, s67, 0x2000
	v_lshl_add_u64 v[166:167], s[68:69], 0, v[128:129]
	global_load_lds_dwordx4 v[166:167], off
	s_mov_b32 m0, s23
	v_lshl_add_u64 v[166:167], v[224:225], 0, s[10:11]
	global_load_lds_dwordx4 v[166:167], off
	s_mov_b32 m0, s24
	v_lshl_add_u64 v[166:167], v[226:227], 0, s[10:11]
	global_load_lds_dwordx4 v[166:167], off
	s_waitcnt vmcnt(8) lgkmcnt(0)
	s_barrier
	s_setprio 1
	v_mfma_f32_16x16x32_bf16 v[60:63], v[146:149], v[190:193], v[60:63]
	v_mfma_f32_16x16x32_bf16 v[52:55], v[154:157], v[190:193], v[52:55]
	v_mfma_f32_16x16x32_bf16 v[60:63], v[150:153], v[194:197], v[60:63]
	v_mfma_f32_16x16x32_bf16 v[52:55], v[158:161], v[194:197], v[52:55]
	v_mfma_f32_16x16x32_bf16 v[44:47], v[146:149], v[198:201], v[44:47]
	v_mfma_f32_16x16x32_bf16 v[36:39], v[154:157], v[198:201], v[36:39]
	v_mfma_f32_16x16x32_bf16 v[44:47], v[150:153], v[202:205], v[44:47]
	v_mfma_f32_16x16x32_bf16 v[36:39], v[158:161], v[202:205], v[36:39]
	v_mfma_f32_16x16x32_bf16 v[28:31], v[146:149], v[206:209], v[28:31]
	v_mfma_f32_16x16x32_bf16 v[20:23], v[154:157], v[206:209], v[20:23]
	v_mfma_f32_16x16x32_bf16 v[28:31], v[150:153], v[210:213], v[28:31]
	v_mfma_f32_16x16x32_bf16 v[20:23], v[158:161], v[210:213], v[20:23]
	v_mfma_f32_16x16x32_bf16 v[12:15], v[146:149], v[214:217], v[12:15]
	v_mfma_f32_16x16x32_bf16 v[4:7], v[154:157], v[214:217], v[4:7]
	v_mfma_f32_16x16x32_bf16 v[12:15], v[150:153], v[218:221], v[12:15]
	v_mfma_f32_16x16x32_bf16 v[4:7], v[158:161], v[218:221], v[4:7]
	v_mfma_f32_16x16x32_bf16 v[56:59], v[162:165], v[190:193], v[56:59]
	v_mfma_f32_16x16x32_bf16 v[48:51], v[182:185], v[190:193], v[48:51]
	v_mfma_f32_16x16x32_bf16 v[56:59], v[178:181], v[194:197], v[56:59]
	v_mfma_f32_16x16x32_bf16 v[48:51], v[186:189], v[194:197], v[48:51]
	v_mfma_f32_16x16x32_bf16 v[40:43], v[162:165], v[198:201], v[40:43]
	v_mfma_f32_16x16x32_bf16 v[32:35], v[182:185], v[198:201], v[32:35]
	v_mfma_f32_16x16x32_bf16 v[40:43], v[178:181], v[202:205], v[40:43]
	v_mfma_f32_16x16x32_bf16 v[32:35], v[186:189], v[202:205], v[32:35]
	v_mfma_f32_16x16x32_bf16 v[24:27], v[162:165], v[206:209], v[24:27]
	v_mfma_f32_16x16x32_bf16 v[16:19], v[182:185], v[206:209], v[16:19]
	v_mfma_f32_16x16x32_bf16 v[24:27], v[178:181], v[210:213], v[24:27]
	v_mfma_f32_16x16x32_bf16 v[16:19], v[186:189], v[210:213], v[16:19]
	v_mfma_f32_16x16x32_bf16 v[8:11], v[162:165], v[214:217], v[8:11]
	v_mfma_f32_16x16x32_bf16 v[0:3], v[182:185], v[214:217], v[0:3]
	s_setprio 3
	s_barrier
	v_mfma_f32_16x16x32_bf16 v[8:11], v[178:181], v[218:221], v[8:11]
	v_mfma_f32_16x16x32_bf16 v[0:3], v[186:189], v[218:221], v[0:3]
	s_setprio 0
	s_add_i32 s66, s66, 2
	s_add_u32 s78, s78, 0x100
	s_addc_u32 s79, s79, 0
	s_add_u32 s58, s58, 0x100
	s_addc_u32 s59, s59, 0
	s_cmp_gt_u32 s66, 13
	s_cbranch_scc0 .LBB0_1148
	s_branch .Lzskip_4
.Lzv_4_0:
	v_mfma_f32_16x16x32_bf16 v[124:127], v[146:149], v[190:193], 0
	v_mfma_f32_16x16x32_bf16 v[116:119], v[154:157], v[190:193], 0
	v_mfma_f32_16x16x32_bf16 v[124:127], v[150:153], v[194:197], v[124:127]
	v_mfma_f32_16x16x32_bf16 v[116:119], v[158:161], v[194:197], v[116:119]
	v_mfma_f32_16x16x32_bf16 v[108:111], v[146:149], v[198:201], 0
	v_mfma_f32_16x16x32_bf16 v[100:103], v[154:157], v[198:201], 0
	v_mfma_f32_16x16x32_bf16 v[108:111], v[150:153], v[202:205], v[108:111]
	v_mfma_f32_16x16x32_bf16 v[100:103], v[158:161], v[202:205], v[100:103]
	v_mfma_f32_16x16x32_bf16 v[92:95], v[146:149], v[206:209], 0
	v_mfma_f32_16x16x32_bf16 v[84:87], v[154:157], v[206:209], 0
	v_mfma_f32_16x16x32_bf16 v[92:95], v[150:153], v[210:213], v[92:95]
	v_mfma_f32_16x16x32_bf16 v[84:87], v[158:161], v[210:213], v[84:87]
	v_mfma_f32_16x16x32_bf16 v[76:79], v[146:149], v[214:217], 0
	v_mfma_f32_16x16x32_bf16 v[68:71], v[154:157], v[214:217], 0
	v_mfma_f32_16x16x32_bf16 v[76:79], v[150:153], v[218:221], v[76:79]
	v_mfma_f32_16x16x32_bf16 v[68:71], v[158:161], v[218:221], v[68:71]
	v_mfma_f32_16x16x32_bf16 v[120:123], v[162:165], v[190:193], 0
	v_mfma_f32_16x16x32_bf16 v[112:115], v[182:185], v[190:193], 0
	v_mfma_f32_16x16x32_bf16 v[120:123], v[178:181], v[194:197], v[120:123]
	v_mfma_f32_16x16x32_bf16 v[112:115], v[186:189], v[194:197], v[112:115]
	v_mfma_f32_16x16x32_bf16 v[104:107], v[162:165], v[198:201], 0
	v_mfma_f32_16x16x32_bf16 v[96:99], v[182:185], v[198:201], 0
	v_mfma_f32_16x16x32_bf16 v[104:107], v[178:181], v[202:205], v[104:107]
	v_mfma_f32_16x16x32_bf16 v[96:99], v[186:189], v[202:205], v[96:99]
	v_mfma_f32_16x16x32_bf16 v[88:91], v[162:165], v[206:209], 0
	v_mfma_f32_16x16x32_bf16 v[80:83], v[182:185], v[206:209], 0
	v_mfma_f32_16x16x32_bf16 v[88:91], v[178:181], v[210:213], v[88:91]
	v_mfma_f32_16x16x32_bf16 v[80:83], v[186:189], v[210:213], v[80:83]
	v_mfma_f32_16x16x32_bf16 v[72:75], v[162:165], v[214:217], 0
	v_mfma_f32_16x16x32_bf16 v[64:67], v[182:185], v[214:217], 0
	s_setprio 3
	s_barrier
	v_mfma_f32_16x16x32_bf16 v[72:75], v[178:181], v[218:221], v[72:75]
	v_mfma_f32_16x16x32_bf16 v[64:67], v[186:189], v[218:221], v[64:67]
	s_setprio 0
	s_branch .Lzj_4_0
.Lzv_4_1:
	v_mfma_f32_16x16x32_bf16 v[60:63], v[146:149], v[190:193], 0
	v_mfma_f32_16x16x32_bf16 v[52:55], v[154:157], v[190:193], 0
	v_mfma_f32_16x16x32_bf16 v[60:63], v[150:153], v[194:197], v[60:63]
	v_mfma_f32_16x16x32_bf16 v[52:55], v[158:161], v[194:197], v[52:55]
	v_mfma_f32_16x16x32_bf16 v[44:47], v[146:149], v[198:201], 0
	v_mfma_f32_16x16x32_bf16 v[36:39], v[154:157], v[198:201], 0
	v_mfma_f32_16x16x32_bf16 v[44:47], v[150:153], v[202:205], v[44:47]
	v_mfma_f32_16x16x32_bf16 v[36:39], v[158:161], v[202:205], v[36:39]
	v_mfma_f32_16x16x32_bf16 v[28:31], v[146:149], v[206:209], 0
	v_mfma_f32_16x16x32_bf16 v[20:23], v[154:157], v[206:209], 0
	v_mfma_f32_16x16x32_bf16 v[28:31], v[150:153], v[210:213], v[28:31]
	v_mfma_f32_16x16x32_bf16 v[20:23], v[158:161], v[210:213], v[20:23]
	v_mfma_f32_16x16x32_bf16 v[12:15], v[146:149], v[214:217], 0
	v_mfma_f32_16x16x32_bf16 v[4:7], v[154:157], v[214:217], 0
	v_mfma_f32_16x16x32_bf16 v[12:15], v[150:153], v[218:221], v[12:15]
	v_mfma_f32_16x16x32_bf16 v[4:7], v[158:161], v[218:221], v[4:7]
	v_mfma_f32_16x16x32_bf16 v[56:59], v[162:165], v[190:193], 0
	v_mfma_f32_16x16x32_bf16 v[48:51], v[182:185], v[190:193], 0
	v_mfma_f32_16x16x32_bf16 v[56:59], v[178:181], v[194:197], v[56:59]
	v_mfma_f32_16x16x32_bf16 v[48:51], v[186:189], v[194:197], v[48:51]
	v_mfma_f32_16x16x32_bf16 v[40:43], v[162:165], v[198:201], 0
	v_mfma_f32_16x16x32_bf16 v[32:35], v[182:185], v[198:201], 0
	v_mfma_f32_16x16x32_bf16 v[40:43], v[178:181], v[202:205], v[40:43]
	v_mfma_f32_16x16x32_bf16 v[32:35], v[186:189], v[202:205], v[32:35]
	v_mfma_f32_16x16x32_bf16 v[24:27], v[162:165], v[206:209], 0
	v_mfma_f32_16x16x32_bf16 v[16:19], v[182:185], v[206:209], 0
	v_mfma_f32_16x16x32_bf16 v[24:27], v[178:181], v[210:213], v[24:27]
	v_mfma_f32_16x16x32_bf16 v[16:19], v[186:189], v[210:213], v[16:19]
	v_mfma_f32_16x16x32_bf16 v[8:11], v[162:165], v[214:217], 0
	v_mfma_f32_16x16x32_bf16 v[0:3], v[182:185], v[214:217], 0
	s_setprio 3
	s_barrier
	v_mfma_f32_16x16x32_bf16 v[8:11], v[178:181], v[218:221], v[8:11]
	v_mfma_f32_16x16x32_bf16 v[0:3], v[186:189], v[218:221], v[0:3]
	s_setprio 0
	s_branch .Lzj_4_1

.LBB0_1299:
	ds_read_b128 v[120:123], v245
	ds_read_b128 v[124:127], v245 offset:1024
	ds_read_b128 v[128:131], v245 offset:2048
	ds_read_b128 v[132:135], v245 offset:3072
	ds_read_b128 v[144:147], v246
	ds_read_b128 v[148:151], v246 offset:1024
	ds_read_b128 v[152:155], v246 offset:2048
	ds_read_b128 v[156:159], v246 offset:3072
	s_add_u32 s66, s76, 0xfff50080
	s_addc_u32 s67, s77, -1
	s_cmp_eq_u32 s59, 40
	s_cselect_b32 s81, s9, s67
	s_cselect_b32 s80, s8, s66
	s_cselect_b32 s79, s53, s58
	s_cselect_b32 s78, s52, s55
	v_lshl_add_u64 v[204:205], s[76:77], 0, v[200:201]
	s_add_i32 m0, s16, 0xc000
	ds_read_b128 v[160:163], v247
	ds_read_b128 v[164:167], v247 offset:1024
	ds_read_b128 v[168:171], v247 offset:2048
	ds_read_b128 v[172:175], v247 offset:3072
	ds_read_b128 v[176:179], v247 offset:4096
	ds_read_b128 v[180:183], v247 offset:5120
	ds_read_b128 v[184:187], v247 offset:6144
	ds_read_b128 v[188:191], v247 offset:7168
	global_load_lds_dwordx4 v[204:205], off
	s_add_i32 m0, s16, 0xe000
	v_lshl_add_u64 v[204:205], s[76:77], 0, v[202:203]
	global_load_lds_dwordx4 v[204:205], off
	s_cmp_eq_u32 s59, -2
	s_waitcnt vmcnt(8) lgkmcnt(0)
	s_barrier
	s_setprio 1
	s_cbranch_scc1 .Lzv_5_0
	v_mfma_f32_16x16x32_bf16 v[140:143], v[120:123], v[160:163], v[140:143]
	v_mfma_f32_16x16x32_bf16 v[136:139], v[128:131], v[160:163], v[136:139]
	v_mfma_f32_16x16x32_bf16 v[140:143], v[124:127], v[164:167], v[140:143]
	v_mfma_f32_16x16x32_bf16 v[136:139], v[132:135], v[164:167], v[136:139]
	v_mfma_f32_16x16x32_bf16 v[108:111], v[120:123], v[168:171], v[108:111]
	v_mfma_f32_16x16x32_bf16 v[104:107], v[128:131], v[168:171], v[104:107]
	v_mfma_f32_16x16x32_bf16 v[108:111], v[124:127], v[172:175], v[108:111]
	v_mfma_f32_16x16x32_bf16 v[104:107], v[132:135], v[172:175], v[104:107]
	v_mfma_f32_16x16x32_bf16 v[92:95], v[120:123], v[176:179], v[92:95]
	v_mfma_f32_16x16x32_bf16 v[88:91], v[128:131], v[176:179], v[88:91]
	v_mfma_f32_16x16x32_bf16 v[92:95], v[124:127], v[180:183], v[92:95]
	v_mfma_f32_16x16x32_bf16 v[88:91], v[132:135], v[180:183], v[88:91]
	v_mfma_f32_16x16x32_bf16 v[76:79], v[120:123], v[184:187], v[76:79]
	v_mfma_f32_16x16x32_bf16 v[72:75], v[128:131], v[184:187], v[72:75]
	v_mfma_f32_16x16x32_bf16 v[76:79], v[124:127], v[188:191], v[76:79]
	v_mfma_f32_16x16x32_bf16 v[72:75], v[132:135], v[188:191], v[72:75]
	v_mfma_f32_16x16x32_bf16 v[116:119], v[144:147], v[160:163], v[116:119]
	v_mfma_f32_16x16x32_bf16 v[112:115], v[152:155], v[160:163], v[112:115]
	v_mfma_f32_16x16x32_bf16 v[116:119], v[148:151], v[164:167], v[116:119]
	v_mfma_f32_16x16x32_bf16 v[112:115], v[156:159], v[164:167], v[112:115]
	v_mfma_f32_16x16x32_bf16 v[100:103], v[144:147], v[168:171], v[100:103]
	v_mfma_f32_16x16x32_bf16 v[96:99], v[152:155], v[168:171], v[96:99]
	v_mfma_f32_16x16x32_bf16 v[100:103], v[148:151], v[172:175], v[100:103]
	v_mfma_f32_16x16x32_bf16 v[96:99], v[156:159], v[172:175], v[96:99]
	v_mfma_f32_16x16x32_bf16 v[84:87], v[144:147], v[176:179], v[84:87]
	v_mfma_f32_16x16x32_bf16 v[80:83], v[152:155], v[176:179], v[80:83]
	v_mfma_f32_16x16x32_bf16 v[84:87], v[148:151], v[180:183], v[84:87]
	v_mfma_f32_16x16x32_bf16 v[80:83], v[156:159], v[180:183], v[80:83]
	v_mfma_f32_16x16x32_bf16 v[68:71], v[144:147], v[184:187], v[68:71]
	v_mfma_f32_16x16x32_bf16 v[64:67], v[152:155], v[184:187], v[64:67]
	s_setprio 3
	s_barrier
	v_mfma_f32_16x16x32_bf16 v[68:71], v[148:151], v[188:191], v[68:71]
	v_mfma_f32_16x16x32_bf16 v[64:67], v[156:159], v[188:191], v[64:67]
	s_setprio 0
.Lzj_5_0:
	s_add_i32 s66, s26, s15
	v_lshl_add_u64 v[204:205], s[78:79], 0, v[194:195]
	s_mov_b32 m0, s66
	ds_read_b128 v[160:163], v247 offset:16384
	ds_read_b128 v[164:167], v247 offset:17408
	ds_read_b128 v[168:171], v247 offset:18432
	ds_read_b128 v[172:175], v247 offset:19456
	ds_read_b128 v[176:179], v247 offset:20480
	ds_read_b128 v[180:183], v247 offset:21504
	ds_read_b128 v[184:187], v247 offset:22528
	ds_read_b128 v[188:191], v247 offset:23552
	global_load_lds_dwordx4 v[204:205], off
	s_add_i32 m0, s66, 0x2000
	s_add_u32 s66, s78, 0xb0000
	v_lshl_add_u64 v[206:207], s[78:79], 0, v[198:199]
	s_addc_u32 s67, s79, 0
	s_add_i32 s68, s27, s15
	global_load_lds_dwordx4 v[206:207], off
	v_lshl_add_u64 v[208:209], s[66:67], 0, v[194:195]
	s_mov_b32 m0, s68
	global_load_lds_dwordx4 v[208:209], off
	s_add_i32 m0, s68, 0x2000
	v_lshl_add_u64 v[208:209], s[66:67], 0, v[198:199]
	global_load_lds_dwordx4 v[208:209], off
	s_mov_b32 m0, s16
	v_lshl_add_u64 v[208:209], s[80:81], 0, v[192:193]
	global_load_lds_dwordx4 v[208:209], off
	s_mov_b32 m0, s17
	v_lshl_add_u64 v[210:211], s[80:81], 0, v[196:197]
	global_load_lds_dwordx4 v[210:211], off
	s_cmp_eq_u32 s59, -2
	s_waitcnt vmcnt(8) lgkmcnt(0)
	s_barrier
	s_setprio 1
	s_cbranch_scc1 .Lzv_5_1
	v_mfma_f32_16x16x32_bf16 v[60:63], v[120:123], v[160:163], v[60:63]
	v_mfma_f32_16x16x32_bf16 v[56:59], v[128:131], v[160:163], v[56:59]
	v_mfma_f32_16x16x32_bf16 v[60:63], v[124:127], v[164:167], v[60:63]
	v_mfma_f32_16x16x32_bf16 v[56:59], v[132:135], v[164:167], v[56:59]
	v_mfma_f32_16x16x32_bf16 v[44:47], v[120:123], v[168:171], v[44:47]
	v_mfma_f32_16x16x32_bf16 v[40:43], v[128:131], v[168:171], v[40:43]
	v_mfma_f32_16x16x32_bf16 v[44:47], v[124:127], v[172:175], v[44:47]
	v_mfma_f32_16x16x32_bf16 v[40:43], v[132:135], v[172:175], v[40:43]
	v_mfma_f32_16x16x32_bf16 v[28:31], v[120:123], v[176:179], v[28:31]
	v_mfma_f32_16x16x32_bf16 v[24:27], v[128:131], v[176:179], v[24:27]
	v_mfma_f32_16x16x32_bf16 v[28:31], v[124:127], v[180:183], v[28:31]
	v_mfma_f32_16x16x32_bf16 v[24:27], v[132:135], v[180:183], v[24:27]
	v_mfma_f32_16x16x32_bf16 v[12:15], v[120:123], v[184:187], v[12:15]
	v_mfma_f32_16x16x32_bf16 v[8:11], v[128:131], v[184:187], v[8:11]
	v_mfma_f32_16x16x32_bf16 v[12:15], v[124:127], v[188:191], v[12:15]
	v_mfma_f32_16x16x32_bf16 v[8:11], v[132:135], v[188:191], v[8:11]
	v_mfma_f32_16x16x32_bf16 v[52:55], v[144:147], v[160:163], v[52:55]
	v_mfma_f32_16x16x32_bf16 v[48:51], v[152:155], v[160:163], v[48:51]
	v_mfma_f32_16x16x32_bf16 v[52:55], v[148:151], v[164:167], v[52:55]
	v_mfma_f32_16x16x32_bf16 v[48:51], v[156:159], v[164:167], v[48:51]
	v_mfma_f32_16x16x32_bf16 v[36:39], v[144:147], v[168:171], v[36:39]
	v_mfma_f32_16x16x32_bf16 v[32:35], v[152:155], v[168:171], v[32:35]
	v_mfma_f32_16x16x32_bf16 v[36:39], v[148:151], v[172:175], v[36:39]
	v_mfma_f32_16x16x32_bf16 v[32:35], v[156:159], v[172:175], v[32:35]
	v_mfma_f32_16x16x32_bf16 v[20:23], v[144:147], v[176:179], v[20:23]
	v_mfma_f32_16x16x32_bf16 v[16:19], v[152:155], v[176:179], v[16:19]
	v_mfma_f32_16x16x32_bf16 v[20:23], v[148:151], v[180:183], v[20:23]
	v_mfma_f32_16x16x32_bf16 v[16:19], v[156:159], v[180:183], v[16:19]
	v_mfma_f32_16x16x32_bf16 v[4:7], v[144:147], v[184:187], v[4:7]
	v_mfma_f32_16x16x32_bf16 v[0:3], v[152:155], v[184:187], v[0:3]
	s_setprio 3
	s_barrier
	v_mfma_f32_16x16x32_bf16 v[4:7], v[148:151], v[188:191], v[4:7]
	v_mfma_f32_16x16x32_bf16 v[0:3], v[156:159], v[188:191], v[0:3]
	s_setprio 0
.Lzj_5_1:
	s_add_i32 s68, 0, 0x18000
	s_add_i32 s69, 0, 0x1c000
	v_add_u32_e32 v132, s68, v243
	v_add_u32_e32 v156, s69, v243
	ds_read_b128 v[120:123], v132
	ds_read_b128 v[124:127], v132 offset:1024
	ds_read_b128 v[128:131], v132 offset:2048
	ds_read_b128 v[132:135], v132 offset:3072
	ds_read_b128 v[144:147], v156
	ds_read_b128 v[148:151], v156 offset:1024
	ds_read_b128 v[152:155], v156 offset:2048
	ds_read_b128 v[156:159], v156 offset:3072
	s_add_u32 s66, s80, 0xb0000
	s_addc_u32 s67, s81, 0
	s_mov_b32 m0, s18
	v_lshl_add_u64 v[212:213], s[66:67], 0, v[192:193]
	ds_read_b128 v[160:163], v247 offset:32768
	ds_read_b128 v[164:167], v247 offset:33792
	ds_read_b128 v[168:171], v247 offset:34816
	ds_read_b128 v[172:175], v247 offset:35840
	ds_read_b128 v[176:179], v247 offset:36864
	ds_read_b128 v[180:183], v247 offset:37888
	ds_read_b128 v[184:187], v247 offset:38912
	ds_read_b128 v[188:191], v247 offset:39936
	global_load_lds_dwordx4 v[212:213], off
	s_mov_b32 m0, s19
	v_lshl_add_u64 v[212:213], s[66:67], 0, v[196:197]
	global_load_lds_dwordx4 v[212:213], off
	s_waitcnt vmcnt(8) lgkmcnt(0)
	s_barrier
	s_setprio 1
	v_mfma_f32_16x16x32_bf16 v[140:143], v[120:123], v[160:163], v[140:143]
	v_mfma_f32_16x16x32_bf16 v[136:139], v[128:131], v[160:163], v[136:139]
	v_mfma_f32_16x16x32_bf16 v[140:143], v[124:127], v[164:167], v[140:143]
	v_mfma_f32_16x16x32_bf16 v[136:139], v[132:135], v[164:167], v[136:139]
	v_mfma_f32_16x16x32_bf16 v[108:111], v[120:123], v[168:171], v[108:111]
	v_mfma_f32_16x16x32_bf16 v[104:107], v[128:131], v[168:171], v[104:107]
	v_mfma_f32_16x16x32_bf16 v[108:111], v[124:127], v[172:175], v[108:111]
	v_mfma_f32_16x16x32_bf16 v[104:107], v[132:135], v[172:175], v[104:107]
	v_mfma_f32_16x16x32_bf16 v[92:95], v[120:123], v[176:179], v[92:95]
	v_mfma_f32_16x16x32_bf16 v[88:91], v[128:131], v[176:179], v[88:91]
	v_mfma_f32_16x16x32_bf16 v[92:95], v[124:127], v[180:183], v[92:95]
	v_mfma_f32_16x16x32_bf16 v[88:91], v[132:135], v[180:183], v[88:91]
	v_mfma_f32_16x16x32_bf16 v[76:79], v[120:123], v[184:187], v[76:79]
	v_mfma_f32_16x16x32_bf16 v[72:75], v[128:131], v[184:187], v[72:75]
	v_mfma_f32_16x16x32_bf16 v[76:79], v[124:127], v[188:191], v[76:79]
	v_mfma_f32_16x16x32_bf16 v[72:75], v[132:135], v[188:191], v[72:75]
	v_mfma_f32_16x16x32_bf16 v[116:119], v[144:147], v[160:163], v[116:119]
	v_mfma_f32_16x16x32_bf16 v[112:115], v[152:155], v[160:163], v[112:115]
	v_mfma_f32_16x16x32_bf16 v[116:119], v[148:151], v[164:167], v[116:119]
	v_mfma_f32_16x16x32_bf16 v[112:115], v[156:159], v[164:167], v[112:115]
	v_mfma_f32_16x16x32_bf16 v[100:103], v[144:147], v[168:171], v[100:103]
	v_mfma_f32_16x16x32_bf16 v[96:99], v[152:155], v[168:171], v[96:99]
	v_mfma_f32_16x16x32_bf16 v[100:103], v[148:151], v[172:175], v[100:103]
	v_mfma_f32_16x16x32_bf16 v[96:99], v[156:159], v[172:175], v[96:99]
	v_mfma_f32_16x16x32_bf16 v[84:87], v[144:147], v[176:179], v[84:87]
	v_mfma_f32_16x16x32_bf16 v[80:83], v[152:155], v[176:179], v[80:83]
	v_mfma_f32_16x16x32_bf16 v[84:87], v[148:151], v[180:183], v[84:87]
	v_mfma_f32_16x16x32_bf16 v[80:83], v[156:159], v[180:183], v[80:83]
	v_mfma_f32_16x16x32_bf16 v[68:71], v[144:147], v[184:187], v[68:71]
	v_mfma_f32_16x16x32_bf16 v[64:67], v[152:155], v[184:187], v[64:67]
	s_setprio 3
	s_barrier
	v_mfma_f32_16x16x32_bf16 v[68:71], v[148:151], v[188:191], v[68:71]
	v_mfma_f32_16x16x32_bf16 v[64:67], v[156:159], v[188:191], v[64:67]
	s_setprio 0
	s_add_i32 s66, s68, s15
	v_lshl_add_u64 v[204:205], v[204:205], 0, s[48:49]
	s_mov_b32 m0, s66
	ds_read_b128 v[160:163], v247 offset:49152
	ds_read_b128 v[164:167], v247 offset:50176
	ds_read_b128 v[168:171], v247 offset:51200
	ds_read_b128 v[172:175], v247 offset:52224
	ds_read_b128 v[176:179], v247 offset:53248
	ds_read_b128 v[180:183], v247 offset:54272
	ds_read_b128 v[184:187], v247 offset:55296
	ds_read_b128 v[188:191], v247 offset:56320
	global_load_lds_dwordx4 v[204:205], off
	s_add_i32 m0, s66, 0x2000
	s_add_u32 s66, s78, 0xb0080
	v_lshl_add_u64 v[204:205], v[206:207], 0, s[48:49]
	s_addc_u32 s67, s79, 0
	s_add_i32 s68, s69, s15
	global_load_lds_dwordx4 v[204:205], off
	s_mov_b32 m0, s68
	v_lshl_add_u64 v[204:205], s[66:67], 0, v[194:195]
	global_load_lds_dwordx4 v[204:205], off
	s_add_i32 m0, s68, 0x2000
	v_lshl_add_u64 v[204:205], s[66:67], 0, v[198:199]
	global_load_lds_dwordx4 v[204:205], off
	s_mov_b32 m0, s21
	v_lshl_add_u64 v[204:205], v[208:209], 0, s[48:49]
	global_load_lds_dwordx4 v[204:205], off
	s_mov_b32 m0, s22
	v_lshl_add_u64 v[204:205], v[210:211], 0, s[48:49]
	global_load_lds_dwordx4 v[204:205], off
	s_waitcnt vmcnt(8) lgkmcnt(0)
	s_barrier
	s_setprio 1
	v_mfma_f32_16x16x32_bf16 v[60:63], v[120:123], v[160:163], v[60:63]
	v_mfma_f32_16x16x32_bf16 v[56:59], v[128:131], v[160:163], v[56:59]
	v_mfma_f32_16x16x32_bf16 v[60:63], v[124:127], v[164:167], v[60:63]
	v_mfma_f32_16x16x32_bf16 v[56:59], v[132:135], v[164:167], v[56:59]
	v_mfma_f32_16x16x32_bf16 v[44:47], v[120:123], v[168:171], v[44:47]
	v_mfma_f32_16x16x32_bf16 v[40:43], v[128:131], v[168:171], v[40:43]
	v_mfma_f32_16x16x32_bf16 v[44:47], v[124:127], v[172:175], v[44:47]
	v_mfma_f32_16x16x32_bf16 v[40:43], v[132:135], v[172:175], v[40:43]
	v_mfma_f32_16x16x32_bf16 v[28:31], v[120:123], v[176:179], v[28:31]
	v_mfma_f32_16x16x32_bf16 v[24:27], v[128:131], v[176:179], v[24:27]
	v_mfma_f32_16x16x32_bf16 v[28:31], v[124:127], v[180:183], v[28:31]
	v_mfma_f32_16x16x32_bf16 v[24:27], v[132:135], v[180:183], v[24:27]
	v_mfma_f32_16x16x32_bf16 v[12:15], v[120:123], v[184:187], v[12:15]
	v_mfma_f32_16x16x32_bf16 v[8:11], v[128:131], v[184:187], v[8:11]
	v_mfma_f32_16x16x32_bf16 v[12:15], v[124:127], v[188:191], v[12:15]
	v_mfma_f32_16x16x32_bf16 v[8:11], v[132:135], v[188:191], v[8:11]
	v_mfma_f32_16x16x32_bf16 v[52:55], v[144:147], v[160:163], v[52:55]
	v_mfma_f32_16x16x32_bf16 v[48:51], v[152:155], v[160:163], v[48:51]
	v_mfma_f32_16x16x32_bf16 v[52:55], v[148:151], v[164:167], v[52:55]
	v_mfma_f32_16x16x32_bf16 v[48:51], v[156:159], v[164:167], v[48:51]
	v_mfma_f32_16x16x32_bf16 v[36:39], v[144:147], v[168:171], v[36:39]
	v_mfma_f32_16x16x32_bf16 v[32:35], v[152:155], v[168:171], v[32:35]
	v_mfma_f32_16x16x32_bf16 v[36:39], v[148:151], v[172:175], v[36:39]
	v_mfma_f32_16x16x32_bf16 v[32:35], v[156:159], v[172:175], v[32:35]
	v_mfma_f32_16x16x32_bf16 v[20:23], v[144:147], v[176:179], v[20:23]
	v_mfma_f32_16x16x32_bf16 v[16:19], v[152:155], v[176:179], v[16:19]
	v_mfma_f32_16x16x32_bf16 v[20:23], v[148:151], v[180:183], v[20:23]
	v_mfma_f32_16x16x32_bf16 v[16:19], v[156:159], v[180:183], v[16:19]
	v_mfma_f32_16x16x32_bf16 v[4:7], v[144:147], v[184:187], v[4:7]
	v_mfma_f32_16x16x32_bf16 v[0:3], v[152:155], v[184:187], v[0:3]
	s_setprio 3
	s_barrier
	v_mfma_f32_16x16x32_bf16 v[4:7], v[148:151], v[188:191], v[4:7]
	v_mfma_f32_16x16x32_bf16 v[0:3], v[156:159], v[188:191], v[0:3]
	s_setprio 0
	s_add_i32 s59, s59, 2
	s_add_u32 s76, s76, 0x100
	s_addc_u32 s77, s77, 0
	s_add_u32 s55, s55, 0x100
	s_addc_u32 s58, s58, 0
	s_cmp_gt_u32 s59, 41
	s_cbranch_scc0 .LBB0_1299
	s_branch .Lzskip_5

.LBB0_1760:
	ds_read_b128 v[128:131], v181
	ds_read_b128 v[132:135], v181 offset:1024
	ds_read_b128 v[136:139], v181 offset:2048
	ds_read_b128 v[160:163], v181 offset:3072
	ds_read_b128 v[164:167], v182
	ds_read_b128 v[168:171], v182 offset:1024
	ds_read_b128 v[186:189], v182 offset:2048
	ds_read_b128 v[190:193], v182 offset:3072
	s_add_u32 s69, s78, 0xfffc0080
	s_addc_u32 s73, s79, -1
	s_cmp_eq_u32 s68, 12
	s_cselect_b32 s83, s49, s73
	s_cselect_b32 s82, s54, s69
	s_cselect_b32 s81, s47, s67
	s_cselect_b32 s80, s55, s66
	v_lshl_add_u64 v[172:173], s[78:79], 0, v[152:153]
	s_add_i32 m0, s18, 0xc000
	ds_read_b128 v[194:197], v183
	ds_read_b128 v[198:201], v183 offset:1024
	ds_read_b128 v[202:205], v183 offset:2048
	ds_read_b128 v[206:209], v183 offset:3072
	ds_read_b128 v[210:213], v183 offset:4096
	ds_read_b128 v[214:217], v183 offset:5120
	ds_read_b128 v[218:221], v183 offset:6144
	ds_read_b128 v[222:225], v183 offset:7168
	global_load_lds_dwordx4 v[172:173], off
	s_add_i32 m0, s18, 0xe000
	v_lshl_add_u64 v[172:173], s[78:79], 0, v[154:155]
	global_load_lds_dwordx4 v[172:173], off
	s_cmp_eq_u32 s68, -2
	s_waitcnt vmcnt(8) lgkmcnt(0)
	s_barrier
	s_setprio 1
	s_cbranch_scc1 .Lzv_8_0
	v_mfma_f32_16x16x32_bf16 v[124:127], v[128:131], v[194:197], v[124:127]
	v_mfma_f32_16x16x32_bf16 v[120:123], v[136:139], v[194:197], v[120:123]
	v_mfma_f32_16x16x32_bf16 v[124:127], v[132:135], v[198:201], v[124:127]
	v_mfma_f32_16x16x32_bf16 v[120:123], v[160:163], v[198:201], v[120:123]
	v_mfma_f32_16x16x32_bf16 v[108:111], v[128:131], v[202:205], v[108:111]
	v_mfma_f32_16x16x32_bf16 v[104:107], v[136:139], v[202:205], v[104:107]
	v_mfma_f32_16x16x32_bf16 v[108:111], v[132:135], v[206:209], v[108:111]
	v_mfma_f32_16x16x32_bf16 v[104:107], v[160:163], v[206:209], v[104:107]
	v_mfma_f32_16x16x32_bf16 v[92:95], v[128:131], v[210:213], v[92:95]
	v_mfma_f32_16x16x32_bf16 v[88:91], v[136:139], v[210:213], v[88:91]
	v_mfma_f32_16x16x32_bf16 v[92:95], v[132:135], v[214:217], v[92:95]
	v_mfma_f32_16x16x32_bf16 v[88:91], v[160:163], v[214:217], v[88:91]
	v_mfma_f32_16x16x32_bf16 v[76:79], v[128:131], v[218:221], v[76:79]
	v_mfma_f32_16x16x32_bf16 v[72:75], v[136:139], v[218:221], v[72:75]
	v_mfma_f32_16x16x32_bf16 v[76:79], v[132:135], v[222:225], v[76:79]
	v_mfma_f32_16x16x32_bf16 v[72:75], v[160:163], v[222:225], v[72:75]
	v_mfma_f32_16x16x32_bf16 v[116:119], v[164:167], v[194:197], v[116:119]
	v_mfma_f32_16x16x32_bf16 v[112:115], v[186:189], v[194:197], v[112:115]
	v_mfma_f32_16x16x32_bf16 v[116:119], v[168:171], v[198:201], v[116:119]
	v_mfma_f32_16x16x32_bf16 v[112:115], v[190:193], v[198:201], v[112:115]
	v_mfma_f32_16x16x32_bf16 v[100:103], v[164:167], v[202:205], v[100:103]
	v_mfma_f32_16x16x32_bf16 v[96:99], v[186:189], v[202:205], v[96:99]
	v_mfma_f32_16x16x32_bf16 v[100:103], v[168:171], v[206:209], v[100:103]
	v_mfma_f32_16x16x32_bf16 v[96:99], v[190:193], v[206:209], v[96:99]
	v_mfma_f32_16x16x32_bf16 v[84:87], v[164:167], v[210:213], v[84:87]
	v_mfma_f32_16x16x32_bf16 v[80:83], v[186:189], v[210:213], v[80:83]
	v_mfma_f32_16x16x32_bf16 v[84:87], v[168:171], v[214:217], v[84:87]
	v_mfma_f32_16x16x32_bf16 v[80:83], v[190:193], v[214:217], v[80:83]
	v_mfma_f32_16x16x32_bf16 v[68:71], v[164:167], v[218:221], v[68:71]
	v_mfma_f32_16x16x32_bf16 v[64:67], v[186:189], v[218:221], v[64:67]
	s_setprio 3
	s_barrier
	v_mfma_f32_16x16x32_bf16 v[68:71], v[168:171], v[222:225], v[68:71]
	v_mfma_f32_16x16x32_bf16 v[64:67], v[190:193], v[222:225], v[64:67]
	s_setprio 0
.Lzj_8_0:
	s_add_i32 s69, s25, s17
	v_lshl_add_u64 v[172:173], s[80:81], 0, v[142:143]
	s_mov_b32 m0, s69
	ds_read_b128 v[194:197], v183 offset:16384
	ds_read_b128 v[198:201], v183 offset:17408
	ds_read_b128 v[202:205], v183 offset:18432
	ds_read_b128 v[206:209], v183 offset:19456
	ds_read_b128 v[210:213], v183 offset:20480
	ds_read_b128 v[214:217], v183 offset:21504
	ds_read_b128 v[218:221], v183 offset:22528
	ds_read_b128 v[222:225], v183 offset:23552
	global_load_lds_dwordx4 v[172:173], off
	s_add_i32 m0, s69, 0x2000
	s_add_u32 s84, s80, 0x40000
	v_lshl_add_u64 v[226:227], s[80:81], 0, v[146:147]
	s_addc_u32 s85, s81, 0
	s_add_i32 s69, s26, s17
	global_load_lds_dwordx4 v[226:227], off
	v_lshl_add_u64 v[228:229], s[84:85], 0, v[142:143]
	s_mov_b32 m0, s69
	global_load_lds_dwordx4 v[228:229], off
	s_add_i32 m0, s69, 0x2000
	v_lshl_add_u64 v[228:229], s[84:85], 0, v[146:147]
	global_load_lds_dwordx4 v[228:229], off
	s_mov_b32 m0, s18
	v_lshl_add_u64 v[228:229], s[82:83], 0, v[140:141]
	global_load_lds_dwordx4 v[228:229], off
	s_mov_b32 m0, s19
	v_lshl_add_u64 v[230:231], s[82:83], 0, v[144:145]
	global_load_lds_dwordx4 v[230:231], off
	s_cmp_eq_u32 s68, -2
	s_waitcnt vmcnt(8) lgkmcnt(0)
	s_barrier
	s_setprio 1
	s_cbranch_scc1 .Lzv_8_1
	v_mfma_f32_16x16x32_bf16 v[60:63], v[128:131], v[194:197], v[60:63]
	v_mfma_f32_16x16x32_bf16 v[56:59], v[136:139], v[194:197], v[56:59]
	v_mfma_f32_16x16x32_bf16 v[60:63], v[132:135], v[198:201], v[60:63]
	v_mfma_f32_16x16x32_bf16 v[56:59], v[160:163], v[198:201], v[56:59]
	v_mfma_f32_16x16x32_bf16 v[44:47], v[128:131], v[202:205], v[44:47]
	v_mfma_f32_16x16x32_bf16 v[40:43], v[136:139], v[202:205], v[40:43]
	v_mfma_f32_16x16x32_bf16 v[44:47], v[132:135], v[206:209], v[44:47]
	v_mfma_f32_16x16x32_bf16 v[40:43], v[160:163], v[206:209], v[40:43]
	v_mfma_f32_16x16x32_bf16 v[28:31], v[128:131], v[210:213], v[28:31]
	v_mfma_f32_16x16x32_bf16 v[24:27], v[136:139], v[210:213], v[24:27]
	v_mfma_f32_16x16x32_bf16 v[28:31], v[132:135], v[214:217], v[28:31]
	v_mfma_f32_16x16x32_bf16 v[24:27], v[160:163], v[214:217], v[24:27]
	v_mfma_f32_16x16x32_bf16 v[12:15], v[128:131], v[218:221], v[12:15]
	v_mfma_f32_16x16x32_bf16 v[8:11], v[136:139], v[218:221], v[8:11]
	v_mfma_f32_16x16x32_bf16 v[12:15], v[132:135], v[222:225], v[12:15]
	v_mfma_f32_16x16x32_bf16 v[8:11], v[160:163], v[222:225], v[8:11]
	v_mfma_f32_16x16x32_bf16 v[52:55], v[164:167], v[194:197], v[52:55]
	v_mfma_f32_16x16x32_bf16 v[48:51], v[186:189], v[194:197], v[48:51]
	v_mfma_f32_16x16x32_bf16 v[52:55], v[168:171], v[198:201], v[52:55]
	v_mfma_f32_16x16x32_bf16 v[48:51], v[190:193], v[198:201], v[48:51]
	v_mfma_f32_16x16x32_bf16 v[36:39], v[164:167], v[202:205], v[36:39]
	v_mfma_f32_16x16x32_bf16 v[32:35], v[186:189], v[202:205], v[32:35]
	v_mfma_f32_16x16x32_bf16 v[36:39], v[168:171], v[206:209], v[36:39]
	v_mfma_f32_16x16x32_bf16 v[32:35], v[190:193], v[206:209], v[32:35]
	v_mfma_f32_16x16x32_bf16 v[20:23], v[164:167], v[210:213], v[20:23]
	v_mfma_f32_16x16x32_bf16 v[16:19], v[186:189], v[210:213], v[16:19]
	v_mfma_f32_16x16x32_bf16 v[20:23], v[168:171], v[214:217], v[20:23]
	v_mfma_f32_16x16x32_bf16 v[16:19], v[190:193], v[214:217], v[16:19]
	v_mfma_f32_16x16x32_bf16 v[4:7], v[164:167], v[218:221], v[4:7]
	v_mfma_f32_16x16x32_bf16 v[0:3], v[186:189], v[218:221], v[0:3]
	s_setprio 3
	s_barrier
	v_mfma_f32_16x16x32_bf16 v[4:7], v[168:171], v[222:225], v[4:7]
	v_mfma_f32_16x16x32_bf16 v[0:3], v[190:193], v[222:225], v[0:3]
	s_setprio 0
.Lzj_8_1:
	s_add_i32 s69, 0, 0x18000
	v_add_u32_e32 v148, s69, v177
	s_add_i32 s73, 0, 0x1c000
	ds_read_b128 v[128:131], v148
	ds_read_b128 v[132:135], v148 offset:1024
	ds_read_b128 v[136:139], v148 offset:2048
	ds_read_b128 v[160:163], v148 offset:3072
	v_add_u32_e32 v148, s73, v177
	ds_read_b128 v[164:167], v148
	ds_read_b128 v[168:171], v148 offset:1024
	ds_read_b128 v[186:189], v148 offset:2048
	ds_read_b128 v[190:193], v148 offset:3072
	s_add_u32 s82, s82, 0x40000
	s_addc_u32 s83, s83, 0
	s_mov_b32 m0, s20
	v_lshl_add_u64 v[232:233], s[82:83], 0, v[140:141]
	ds_read_b128 v[194:197], v183 offset:32768
	ds_read_b128 v[198:201], v183 offset:33792
	ds_read_b128 v[202:205], v183 offset:34816
	ds_read_b128 v[206:209], v183 offset:35840
	ds_read_b128 v[210:213], v183 offset:36864
	ds_read_b128 v[214:217], v183 offset:37888
	ds_read_b128 v[218:221], v183 offset:38912
	ds_read_b128 v[222:225], v183 offset:39936
	global_load_lds_dwordx4 v[232:233], off
	s_mov_b32 m0, s21
	v_lshl_add_u64 v[232:233], s[82:83], 0, v[144:145]
	global_load_lds_dwordx4 v[232:233], off
	s_waitcnt vmcnt(8) lgkmcnt(0)
	s_barrier
	s_setprio 1
	v_mfma_f32_16x16x32_bf16 v[124:127], v[128:131], v[194:197], v[124:127]
	v_mfma_f32_16x16x32_bf16 v[120:123], v[136:139], v[194:197], v[120:123]
	v_mfma_f32_16x16x32_bf16 v[124:127], v[132:135], v[198:201], v[124:127]
	v_mfma_f32_16x16x32_bf16 v[120:123], v[160:163], v[198:201], v[120:123]
	v_mfma_f32_16x16x32_bf16 v[108:111], v[128:131], v[202:205], v[108:111]
	v_mfma_f32_16x16x32_bf16 v[104:107], v[136:139], v[202:205], v[104:107]
	v_mfma_f32_16x16x32_bf16 v[108:111], v[132:135], v[206:209], v[108:111]
	v_mfma_f32_16x16x32_bf16 v[104:107], v[160:163], v[206:209], v[104:107]
	v_mfma_f32_16x16x32_bf16 v[92:95], v[128:131], v[210:213], v[92:95]
	v_mfma_f32_16x16x32_bf16 v[88:91], v[136:139], v[210:213], v[88:91]
	v_mfma_f32_16x16x32_bf16 v[92:95], v[132:135], v[214:217], v[92:95]
	v_mfma_f32_16x16x32_bf16 v[88:91], v[160:163], v[214:217], v[88:91]
	v_mfma_f32_16x16x32_bf16 v[76:79], v[128:131], v[218:221], v[76:79]
	v_mfma_f32_16x16x32_bf16 v[72:75], v[136:139], v[218:221], v[72:75]
	v_mfma_f32_16x16x32_bf16 v[76:79], v[132:135], v[222:225], v[76:79]
	v_mfma_f32_16x16x32_bf16 v[72:75], v[160:163], v[222:225], v[72:75]
	v_mfma_f32_16x16x32_bf16 v[116:119], v[164:167], v[194:197], v[116:119]
	v_mfma_f32_16x16x32_bf16 v[112:115], v[186:189], v[194:197], v[112:115]
	v_mfma_f32_16x16x32_bf16 v[116:119], v[168:171], v[198:201], v[116:119]
	v_mfma_f32_16x16x32_bf16 v[112:115], v[190:193], v[198:201], v[112:115]
	v_mfma_f32_16x16x32_bf16 v[100:103], v[164:167], v[202:205], v[100:103]
	v_mfma_f32_16x16x32_bf16 v[96:99], v[186:189], v[202:205], v[96:99]
	v_mfma_f32_16x16x32_bf16 v[100:103], v[168:171], v[206:209], v[100:103]
	v_mfma_f32_16x16x32_bf16 v[96:99], v[190:193], v[206:209], v[96:99]
	v_mfma_f32_16x16x32_bf16 v[84:87], v[164:167], v[210:213], v[84:87]
	v_mfma_f32_16x16x32_bf16 v[80:83], v[186:189], v[210:213], v[80:83]
	v_mfma_f32_16x16x32_bf16 v[84:87], v[168:171], v[214:217], v[84:87]
	v_mfma_f32_16x16x32_bf16 v[80:83], v[190:193], v[214:217], v[80:83]
	v_mfma_f32_16x16x32_bf16 v[68:71], v[164:167], v[218:221], v[68:71]
	v_mfma_f32_16x16x32_bf16 v[64:67], v[186:189], v[218:221], v[64:67]
	s_setprio 3
	s_barrier
	v_mfma_f32_16x16x32_bf16 v[68:71], v[168:171], v[222:225], v[68:71]
	v_mfma_f32_16x16x32_bf16 v[64:67], v[190:193], v[222:225], v[64:67]
	s_setprio 0
	s_add_i32 s69, s69, s17
	v_lshl_add_u64 v[172:173], v[172:173], 0, s[10:11]
	s_mov_b32 m0, s69
	ds_read_b128 v[194:197], v183 offset:49152
	ds_read_b128 v[198:201], v183 offset:50176
	ds_read_b128 v[202:205], v183 offset:51200
	ds_read_b128 v[206:209], v183 offset:52224
	ds_read_b128 v[210:213], v183 offset:53248
	ds_read_b128 v[214:217], v183 offset:54272
	ds_read_b128 v[218:221], v183 offset:55296
	ds_read_b128 v[222:225], v183 offset:56320
	global_load_lds_dwordx4 v[172:173], off
	s_add_i32 m0, s69, 0x2000
	s_add_u32 s80, s80, 0x40080
	v_lshl_add_u64 v[172:173], v[226:227], 0, s[10:11]
	s_addc_u32 s81, s81, 0
	s_add_i32 s69, s73, s17
	global_load_lds_dwordx4 v[172:173], off
	s_mov_b32 m0, s69
	v_lshl_add_u64 v[172:173], s[80:81], 0, v[142:143]
	global_load_lds_dwordx4 v[172:173], off
	s_add_i32 m0, s69, 0x2000
	v_lshl_add_u64 v[172:173], s[80:81], 0, v[146:147]
	global_load_lds_dwordx4 v[172:173], off
	s_mov_b32 m0, s23
	v_lshl_add_u64 v[172:173], v[228:229], 0, s[10:11]
	global_load_lds_dwordx4 v[172:173], off
	s_mov_b32 m0, s24
	v_lshl_add_u64 v[172:173], v[230:231], 0, s[10:11]
	global_load_lds_dwordx4 v[172:173], off
	s_waitcnt vmcnt(8) lgkmcnt(0)
	s_barrier
	s_setprio 1
	v_mfma_f32_16x16x32_bf16 v[60:63], v[128:131], v[194:197], v[60:63]
	v_mfma_f32_16x16x32_bf16 v[56:59], v[136:139], v[194:197], v[56:59]
	v_mfma_f32_16x16x32_bf16 v[60:63], v[132:135], v[198:201], v[60:63]
	v_mfma_f32_16x16x32_bf16 v[56:59], v[160:163], v[198:201], v[56:59]
	v_mfma_f32_16x16x32_bf16 v[44:47], v[128:131], v[202:205], v[44:47]
	v_mfma_f32_16x16x32_bf16 v[40:43], v[136:139], v[202:205], v[40:43]
	v_mfma_f32_16x16x32_bf16 v[44:47], v[132:135], v[206:209], v[44:47]
	v_mfma_f32_16x16x32_bf16 v[40:43], v[160:163], v[206:209], v[40:43]
	v_mfma_f32_16x16x32_bf16 v[28:31], v[128:131], v[210:213], v[28:31]
	v_mfma_f32_16x16x32_bf16 v[24:27], v[136:139], v[210:213], v[24:27]
	v_mfma_f32_16x16x32_bf16 v[28:31], v[132:135], v[214:217], v[28:31]
	v_mfma_f32_16x16x32_bf16 v[24:27], v[160:163], v[214:217], v[24:27]
	v_mfma_f32_16x16x32_bf16 v[12:15], v[128:131], v[218:221], v[12:15]
	v_mfma_f32_16x16x32_bf16 v[8:11], v[136:139], v[218:221], v[8:11]
	v_mfma_f32_16x16x32_bf16 v[12:15], v[132:135], v[222:225], v[12:15]
	v_mfma_f32_16x16x32_bf16 v[8:11], v[160:163], v[222:225], v[8:11]
	v_mfma_f32_16x16x32_bf16 v[52:55], v[164:167], v[194:197], v[52:55]
	v_mfma_f32_16x16x32_bf16 v[48:51], v[186:189], v[194:197], v[48:51]
	v_mfma_f32_16x16x32_bf16 v[52:55], v[168:171], v[198:201], v[52:55]
	v_mfma_f32_16x16x32_bf16 v[48:51], v[190:193], v[198:201], v[48:51]
	v_mfma_f32_16x16x32_bf16 v[36:39], v[164:167], v[202:205], v[36:39]
	v_mfma_f32_16x16x32_bf16 v[32:35], v[186:189], v[202:205], v[32:35]
	v_mfma_f32_16x16x32_bf16 v[36:39], v[168:171], v[206:209], v[36:39]
	v_mfma_f32_16x16x32_bf16 v[32:35], v[190:193], v[206:209], v[32:35]
	v_mfma_f32_16x16x32_bf16 v[20:23], v[164:167], v[210:213], v[20:23]
	v_mfma_f32_16x16x32_bf16 v[16:19], v[186:189], v[210:213], v[16:19]
	v_mfma_f32_16x16x32_bf16 v[20:23], v[168:171], v[214:217], v[20:23]
	v_mfma_f32_16x16x32_bf16 v[16:19], v[190:193], v[214:217], v[16:19]
	v_mfma_f32_16x16x32_bf16 v[4:7], v[164:167], v[218:221], v[4:7]
	v_mfma_f32_16x16x32_bf16 v[0:3], v[186:189], v[218:221], v[0:3]
	s_setprio 3
	s_barrier
	v_mfma_f32_16x16x32_bf16 v[4:7], v[168:171], v[222:225], v[4:7]
	v_mfma_f32_16x16x32_bf16 v[0:3], v[190:193], v[222:225], v[0:3]
	s_setprio 0
	s_add_i32 s68, s68, 2
	s_add_u32 s78, s78, 0x100
	s_addc_u32 s79, s79, 0
	s_add_u32 s66, s66, 0x100
	s_addc_u32 s67, s67, 0
	s_cmp_gt_u32 s68, 13
	s_cbranch_scc0 .LBB0_1760
	s_branch .Lzskip_8
.Lzv_8_0:
	v_mfma_f32_16x16x32_bf16 v[124:127], v[128:131], v[194:197], 0
	v_mfma_f32_16x16x32_bf16 v[120:123], v[136:139], v[194:197], 0
	v_mfma_f32_16x16x32_bf16 v[124:127], v[132:135], v[198:201], v[124:127]
	v_mfma_f32_16x16x32_bf16 v[120:123], v[160:163], v[198:201], v[120:123]
	v_mfma_f32_16x16x32_bf16 v[108:111], v[128:131], v[202:205], 0
	v_mfma_f32_16x16x32_bf16 v[104:107], v[136:139], v[202:205], 0
	v_mfma_f32_16x16x32_bf16 v[108:111], v[132:135], v[206:209], v[108:111]
	v_mfma_f32_16x16x32_bf16 v[104:107], v[160:163], v[206:209], v[104:107]
	v_mfma_f32_16x16x32_bf16 v[92:95], v[128:131], v[210:213], 0
	v_mfma_f32_16x16x32_bf16 v[88:91], v[136:139], v[210:213], 0
	v_mfma_f32_16x16x32_bf16 v[92:95], v[132:135], v[214:217], v[92:95]
	v_mfma_f32_16x16x32_bf16 v[88:91], v[160:163], v[214:217], v[88:91]
	v_mfma_f32_16x16x32_bf16 v[76:79], v[128:131], v[218:221], 0
	v_mfma_f32_16x16x32_bf16 v[72:75], v[136:139], v[218:221], 0
	v_mfma_f32_16x16x32_bf16 v[76:79], v[132:135], v[222:225], v[76:79]
	v_mfma_f32_16x16x32_bf16 v[72:75], v[160:163], v[222:225], v[72:75]
	v_mfma_f32_16x16x32_bf16 v[116:119], v[164:167], v[194:197], 0
	v_mfma_f32_16x16x32_bf16 v[112:115], v[186:189], v[194:197], 0
	v_mfma_f32_16x16x32_bf16 v[116:119], v[168:171], v[198:201], v[116:119]
	v_mfma_f32_16x16x32_bf16 v[112:115], v[190:193], v[198:201], v[112:115]
	v_mfma_f32_16x16x32_bf16 v[100:103], v[164:167], v[202:205], 0
	v_mfma_f32_16x16x32_bf16 v[96:99], v[186:189], v[202:205], 0
	v_mfma_f32_16x16x32_bf16 v[100:103], v[168:171], v[206:209], v[100:103]
	v_mfma_f32_16x16x32_bf16 v[96:99], v[190:193], v[206:209], v[96:99]
	v_mfma_f32_16x16x32_bf16 v[84:87], v[164:167], v[210:213], 0
	v_mfma_f32_16x16x32_bf16 v[80:83], v[186:189], v[210:213], 0
	v_mfma_f32_16x16x32_bf16 v[84:87], v[168:171], v[214:217], v[84:87]
	v_mfma_f32_16x16x32_bf16 v[80:83], v[190:193], v[214:217], v[80:83]
	v_mfma_f32_16x16x32_bf16 v[68:71], v[164:167], v[218:221], 0
	v_mfma_f32_16x16x32_bf16 v[64:67], v[186:189], v[218:221], 0
	s_setprio 3
	s_barrier
	v_mfma_f32_16x16x32_bf16 v[68:71], v[168:171], v[222:225], v[68:71]
	v_mfma_f32_16x16x32_bf16 v[64:67], v[190:193], v[222:225], v[64:67]
	s_setprio 0
	s_branch .Lzj_8_0
.Lzv_8_1:
	v_mfma_f32_16x16x32_bf16 v[60:63], v[128:131], v[194:197], 0
	v_mfma_f32_16x16x32_bf16 v[56:59], v[136:139], v[194:197], 0
	v_mfma_f32_16x16x32_bf16 v[60:63], v[132:135], v[198:201], v[60:63]
	v_mfma_f32_16x16x32_bf16 v[56:59], v[160:163], v[198:201], v[56:59]
	v_mfma_f32_16x16x32_bf16 v[44:47], v[128:131], v[202:205], 0
	v_mfma_f32_16x16x32_bf16 v[40:43], v[136:139], v[202:205], 0
	v_mfma_f32_16x16x32_bf16 v[44:47], v[132:135], v[206:209], v[44:47]
	v_mfma_f32_16x16x32_bf16 v[40:43], v[160:163], v[206:209], v[40:43]
	v_mfma_f32_16x16x32_bf16 v[28:31], v[128:131], v[210:213], 0
	v_mfma_f32_16x16x32_bf16 v[24:27], v[136:139], v[210:213], 0
	v_mfma_f32_16x16x32_bf16 v[28:31], v[132:135], v[214:217], v[28:31]
	v_mfma_f32_16x16x32_bf16 v[24:27], v[160:163], v[214:217], v[24:27]
	v_mfma_f32_16x16x32_bf16 v[12:15], v[128:131], v[218:221], 0
	v_mfma_f32_16x16x32_bf16 v[8:11], v[136:139], v[218:221], 0
	v_mfma_f32_16x16x32_bf16 v[12:15], v[132:135], v[222:225], v[12:15]
	v_mfma_f32_16x16x32_bf16 v[8:11], v[160:163], v[222:225], v[8:11]
	v_mfma_f32_16x16x32_bf16 v[52:55], v[164:167], v[194:197], 0
	v_mfma_f32_16x16x32_bf16 v[48:51], v[186:189], v[194:197], 0
	v_mfma_f32_16x16x32_bf16 v[52:55], v[168:171], v[198:201], v[52:55]
	v_mfma_f32_16x16x32_bf16 v[48:51], v[190:193], v[198:201], v[48:51]
	v_mfma_f32_16x16x32_bf16 v[36:39], v[164:167], v[202:205], 0
	v_mfma_f32_16x16x32_bf16 v[32:35], v[186:189], v[202:205], 0
	v_mfma_f32_16x16x32_bf16 v[36:39], v[168:171], v[206:209], v[36:39]
	v_mfma_f32_16x16x32_bf16 v[32:35], v[190:193], v[206:209], v[32:35]
	v_mfma_f32_16x16x32_bf16 v[20:23], v[164:167], v[210:213], 0
	v_mfma_f32_16x16x32_bf16 v[16:19], v[186:189], v[210:213], 0
	v_mfma_f32_16x16x32_bf16 v[20:23], v[168:171], v[214:217], v[20:23]
	v_mfma_f32_16x16x32_bf16 v[16:19], v[190:193], v[214:217], v[16:19]
	v_mfma_f32_16x16x32_bf16 v[4:7], v[164:167], v[218:221], 0
	v_mfma_f32_16x16x32_bf16 v[0:3], v[186:189], v[218:221], 0
	s_setprio 3
	s_barrier
	v_mfma_f32_16x16x32_bf16 v[4:7], v[168:171], v[222:225], v[4:7]
	v_mfma_f32_16x16x32_bf16 v[0:3], v[190:193], v[222:225], v[0:3]
	s_setprio 0
	s_branch .Lzj_8_1

.LBB0_2037:
	ds_read_b128 v[120:123], v245
	ds_read_b128 v[124:127], v245 offset:1024
	ds_read_b128 v[128:131], v245 offset:2048
	ds_read_b128 v[132:135], v245 offset:3072
	ds_read_b128 v[144:147], v246
	ds_read_b128 v[148:151], v246 offset:1024
	ds_read_b128 v[152:155], v246 offset:2048
	ds_read_b128 v[156:159], v246 offset:3072
	s_add_u32 s67, s76, 0xfffc0080
	s_addc_u32 s68, s77, -1
	s_cmp_eq_u32 s66, 12
	s_cselect_b32 s81, s53, s68
	s_cselect_b32 s80, s54, s67
	s_cselect_b32 s79, s51, s57
	s_cselect_b32 s78, s55, s56
	v_lshl_add_u64 v[204:205], s[76:77], 0, v[200:201]
	s_add_i32 m0, s16, 0xc000
	ds_read_b128 v[160:163], v247
	ds_read_b128 v[164:167], v247 offset:1024
	ds_read_b128 v[168:171], v247 offset:2048
	ds_read_b128 v[172:175], v247 offset:3072
	ds_read_b128 v[176:179], v247 offset:4096
	ds_read_b128 v[180:183], v247 offset:5120
	ds_read_b128 v[184:187], v247 offset:6144
	ds_read_b128 v[188:191], v247 offset:7168
	global_load_lds_dwordx4 v[204:205], off
	s_add_i32 m0, s16, 0xe000
	v_lshl_add_u64 v[204:205], s[76:77], 0, v[202:203]
	global_load_lds_dwordx4 v[204:205], off
	s_cmp_eq_u32 s66, -2
	s_waitcnt vmcnt(8) lgkmcnt(0)
	s_barrier
	s_setprio 1
	s_cbranch_scc1 .Lzv_9_0
	v_mfma_f32_16x16x32_bf16 v[140:143], v[120:123], v[160:163], v[140:143]
	v_mfma_f32_16x16x32_bf16 v[136:139], v[128:131], v[160:163], v[136:139]
	v_mfma_f32_16x16x32_bf16 v[140:143], v[124:127], v[164:167], v[140:143]
	v_mfma_f32_16x16x32_bf16 v[136:139], v[132:135], v[164:167], v[136:139]
	v_mfma_f32_16x16x32_bf16 v[108:111], v[120:123], v[168:171], v[108:111]
	v_mfma_f32_16x16x32_bf16 v[104:107], v[128:131], v[168:171], v[104:107]
	v_mfma_f32_16x16x32_bf16 v[108:111], v[124:127], v[172:175], v[108:111]
	v_mfma_f32_16x16x32_bf16 v[104:107], v[132:135], v[172:175], v[104:107]
	v_mfma_f32_16x16x32_bf16 v[92:95], v[120:123], v[176:179], v[92:95]
	v_mfma_f32_16x16x32_bf16 v[88:91], v[128:131], v[176:179], v[88:91]
	v_mfma_f32_16x16x32_bf16 v[92:95], v[124:127], v[180:183], v[92:95]
	v_mfma_f32_16x16x32_bf16 v[88:91], v[132:135], v[180:183], v[88:91]
	v_mfma_f32_16x16x32_bf16 v[76:79], v[120:123], v[184:187], v[76:79]
	v_mfma_f32_16x16x32_bf16 v[72:75], v[128:131], v[184:187], v[72:75]
	v_mfma_f32_16x16x32_bf16 v[76:79], v[124:127], v[188:191], v[76:79]
	v_mfma_f32_16x16x32_bf16 v[72:75], v[132:135], v[188:191], v[72:75]
	v_mfma_f32_16x16x32_bf16 v[116:119], v[144:147], v[160:163], v[116:119]
	v_mfma_f32_16x16x32_bf16 v[112:115], v[152:155], v[160:163], v[112:115]
	v_mfma_f32_16x16x32_bf16 v[116:119], v[148:151], v[164:167], v[116:119]
	v_mfma_f32_16x16x32_bf16 v[112:115], v[156:159], v[164:167], v[112:115]
	v_mfma_f32_16x16x32_bf16 v[100:103], v[144:147], v[168:171], v[100:103]
	v_mfma_f32_16x16x32_bf16 v[96:99], v[152:155], v[168:171], v[96:99]
	v_mfma_f32_16x16x32_bf16 v[100:103], v[148:151], v[172:175], v[100:103]
	v_mfma_f32_16x16x32_bf16 v[96:99], v[156:159], v[172:175], v[96:99]
	v_mfma_f32_16x16x32_bf16 v[84:87], v[144:147], v[176:179], v[84:87]
	v_mfma_f32_16x16x32_bf16 v[80:83], v[152:155], v[176:179], v[80:83]
	v_mfma_f32_16x16x32_bf16 v[84:87], v[148:151], v[180:183], v[84:87]
	v_mfma_f32_16x16x32_bf16 v[80:83], v[156:159], v[180:183], v[80:83]
	v_mfma_f32_16x16x32_bf16 v[68:71], v[144:147], v[184:187], v[68:71]
	v_mfma_f32_16x16x32_bf16 v[64:67], v[152:155], v[184:187], v[64:67]
	s_setprio 3
	s_barrier
	v_mfma_f32_16x16x32_bf16 v[68:71], v[148:151], v[188:191], v[68:71]
	v_mfma_f32_16x16x32_bf16 v[64:67], v[156:159], v[188:191], v[64:67]
	s_setprio 0
.Lzj_9_0:
	s_add_i32 s67, s26, s15
	v_lshl_add_u64 v[204:205], s[78:79], 0, v[194:195]
	s_mov_b32 m0, s67
	ds_read_b128 v[160:163], v247 offset:16384
	ds_read_b128 v[164:167], v247 offset:17408
	ds_read_b128 v[168:171], v247 offset:18432
	ds_read_b128 v[172:175], v247 offset:19456
	ds_read_b128 v[176:179], v247 offset:20480
	ds_read_b128 v[180:183], v247 offset:21504
	ds_read_b128 v[184:187], v247 offset:22528
	ds_read_b128 v[188:191], v247 offset:23552
	global_load_lds_dwordx4 v[204:205], off
	s_add_i32 m0, s67, 0x2000
	s_add_u32 s68, s78, 0x40000
	v_lshl_add_u64 v[206:207], s[78:79], 0, v[198:199]
	s_addc_u32 s69, s79, 0
	s_add_i32 s67, s27, s15
	global_load_lds_dwordx4 v[206:207], off
	v_lshl_add_u64 v[208:209], s[68:69], 0, v[194:195]
	s_mov_b32 m0, s67
	global_load_lds_dwordx4 v[208:209], off
	s_add_i32 m0, s67, 0x2000
	v_lshl_add_u64 v[208:209], s[68:69], 0, v[198:199]
	global_load_lds_dwordx4 v[208:209], off
	s_mov_b32 m0, s16
	v_lshl_add_u64 v[208:209], s[80:81], 0, v[192:193]
	global_load_lds_dwordx4 v[208:209], off
	s_mov_b32 m0, s17
	v_lshl_add_u64 v[210:211], s[80:81], 0, v[196:197]
	global_load_lds_dwordx4 v[210:211], off
	s_cmp_eq_u32 s66, -2
	s_waitcnt vmcnt(8) lgkmcnt(0)
	s_barrier
	s_setprio 1
	s_cbranch_scc1 .Lzv_9_1
	v_mfma_f32_16x16x32_bf16 v[60:63], v[120:123], v[160:163], v[60:63]
	v_mfma_f32_16x16x32_bf16 v[56:59], v[128:131], v[160:163], v[56:59]
	v_mfma_f32_16x16x32_bf16 v[60:63], v[124:127], v[164:167], v[60:63]
	v_mfma_f32_16x16x32_bf16 v[56:59], v[132:135], v[164:167], v[56:59]
	v_mfma_f32_16x16x32_bf16 v[44:47], v[120:123], v[168:171], v[44:47]
	v_mfma_f32_16x16x32_bf16 v[40:43], v[128:131], v[168:171], v[40:43]
	v_mfma_f32_16x16x32_bf16 v[44:47], v[124:127], v[172:175], v[44:47]
	v_mfma_f32_16x16x32_bf16 v[40:43], v[132:135], v[172:175], v[40:43]
	v_mfma_f32_16x16x32_bf16 v[28:31], v[120:123], v[176:179], v[28:31]
	v_mfma_f32_16x16x32_bf16 v[24:27], v[128:131], v[176:179], v[24:27]
	v_mfma_f32_16x16x32_bf16 v[28:31], v[124:127], v[180:183], v[28:31]
	v_mfma_f32_16x16x32_bf16 v[24:27], v[132:135], v[180:183], v[24:27]
	v_mfma_f32_16x16x32_bf16 v[12:15], v[120:123], v[184:187], v[12:15]
	v_mfma_f32_16x16x32_bf16 v[8:11], v[128:131], v[184:187], v[8:11]
	v_mfma_f32_16x16x32_bf16 v[12:15], v[124:127], v[188:191], v[12:15]
	v_mfma_f32_16x16x32_bf16 v[8:11], v[132:135], v[188:191], v[8:11]
	v_mfma_f32_16x16x32_bf16 v[52:55], v[144:147], v[160:163], v[52:55]
	v_mfma_f32_16x16x32_bf16 v[48:51], v[152:155], v[160:163], v[48:51]
	v_mfma_f32_16x16x32_bf16 v[52:55], v[148:151], v[164:167], v[52:55]
	v_mfma_f32_16x16x32_bf16 v[48:51], v[156:159], v[164:167], v[48:51]
	v_mfma_f32_16x16x32_bf16 v[36:39], v[144:147], v[168:171], v[36:39]
	v_mfma_f32_16x16x32_bf16 v[32:35], v[152:155], v[168:171], v[32:35]
	v_mfma_f32_16x16x32_bf16 v[36:39], v[148:151], v[172:175], v[36:39]
	v_mfma_f32_16x16x32_bf16 v[32:35], v[156:159], v[172:175], v[32:35]
	v_mfma_f32_16x16x32_bf16 v[20:23], v[144:147], v[176:179], v[20:23]
	v_mfma_f32_16x16x32_bf16 v[16:19], v[152:155], v[176:179], v[16:19]
	v_mfma_f32_16x16x32_bf16 v[20:23], v[148:151], v[180:183], v[20:23]
	v_mfma_f32_16x16x32_bf16 v[16:19], v[156:159], v[180:183], v[16:19]
	v_mfma_f32_16x16x32_bf16 v[4:7], v[144:147], v[184:187], v[4:7]
	v_mfma_f32_16x16x32_bf16 v[0:3], v[152:155], v[184:187], v[0:3]
	s_setprio 3
	s_barrier
	v_mfma_f32_16x16x32_bf16 v[4:7], v[148:151], v[188:191], v[4:7]
	v_mfma_f32_16x16x32_bf16 v[0:3], v[156:159], v[188:191], v[0:3]
	s_setprio 0
.Lzj_9_1:
	s_add_i32 s67, 0, 0x18000
	s_add_i32 s75, 0, 0x1c000
	v_add_u32_e32 v132, s67, v243
	v_add_u32_e32 v156, s75, v243
	ds_read_b128 v[120:123], v132
	ds_read_b128 v[124:127], v132 offset:1024
	ds_read_b128 v[128:131], v132 offset:2048
	ds_read_b128 v[132:135], v132 offset:3072
	ds_read_b128 v[144:147], v156
	ds_read_b128 v[148:151], v156 offset:1024
	ds_read_b128 v[152:155], v156 offset:2048
	ds_read_b128 v[156:159], v156 offset:3072
	s_add_u32 s68, s80, 0x40000
	s_addc_u32 s69, s81, 0
	s_mov_b32 m0, s18
	v_lshl_add_u64 v[212:213], s[68:69], 0, v[192:193]
	ds_read_b128 v[160:163], v247 offset:32768
	ds_read_b128 v[164:167], v247 offset:33792
	ds_read_b128 v[168:171], v247 offset:34816
	ds_read_b128 v[172:175], v247 offset:35840
	ds_read_b128 v[176:179], v247 offset:36864
	ds_read_b128 v[180:183], v247 offset:37888
	ds_read_b128 v[184:187], v247 offset:38912
	ds_read_b128 v[188:191], v247 offset:39936
	global_load_lds_dwordx4 v[212:213], off
	s_mov_b32 m0, s19
	v_lshl_add_u64 v[212:213], s[68:69], 0, v[196:197]
	global_load_lds_dwordx4 v[212:213], off
	s_waitcnt vmcnt(8) lgkmcnt(0)
	s_barrier
	s_setprio 1
	v_mfma_f32_16x16x32_bf16 v[140:143], v[120:123], v[160:163], v[140:143]
	v_mfma_f32_16x16x32_bf16 v[136:139], v[128:131], v[160:163], v[136:139]
	v_mfma_f32_16x16x32_bf16 v[140:143], v[124:127], v[164:167], v[140:143]
	v_mfma_f32_16x16x32_bf16 v[136:139], v[132:135], v[164:167], v[136:139]
	v_mfma_f32_16x16x32_bf16 v[108:111], v[120:123], v[168:171], v[108:111]
	v_mfma_f32_16x16x32_bf16 v[104:107], v[128:131], v[168:171], v[104:107]
	v_mfma_f32_16x16x32_bf16 v[108:111], v[124:127], v[172:175], v[108:111]
	v_mfma_f32_16x16x32_bf16 v[104:107], v[132:135], v[172:175], v[104:107]
	v_mfma_f32_16x16x32_bf16 v[92:95], v[120:123], v[176:179], v[92:95]
	v_mfma_f32_16x16x32_bf16 v[88:91], v[128:131], v[176:179], v[88:91]
	v_mfma_f32_16x16x32_bf16 v[92:95], v[124:127], v[180:183], v[92:95]
	v_mfma_f32_16x16x32_bf16 v[88:91], v[132:135], v[180:183], v[88:91]
	v_mfma_f32_16x16x32_bf16 v[76:79], v[120:123], v[184:187], v[76:79]
	v_mfma_f32_16x16x32_bf16 v[72:75], v[128:131], v[184:187], v[72:75]
	v_mfma_f32_16x16x32_bf16 v[76:79], v[124:127], v[188:191], v[76:79]
	v_mfma_f32_16x16x32_bf16 v[72:75], v[132:135], v[188:191], v[72:75]
	v_mfma_f32_16x16x32_bf16 v[116:119], v[144:147], v[160:163], v[116:119]
	v_mfma_f32_16x16x32_bf16 v[112:115], v[152:155], v[160:163], v[112:115]
	v_mfma_f32_16x16x32_bf16 v[116:119], v[148:151], v[164:167], v[116:119]
	v_mfma_f32_16x16x32_bf16 v[112:115], v[156:159], v[164:167], v[112:115]
	v_mfma_f32_16x16x32_bf16 v[100:103], v[144:147], v[168:171], v[100:103]
	v_mfma_f32_16x16x32_bf16 v[96:99], v[152:155], v[168:171], v[96:99]
	v_mfma_f32_16x16x32_bf16 v[100:103], v[148:151], v[172:175], v[100:103]
	v_mfma_f32_16x16x32_bf16 v[96:99], v[156:159], v[172:175], v[96:99]
	v_mfma_f32_16x16x32_bf16 v[84:87], v[144:147], v[176:179], v[84:87]
	v_mfma_f32_16x16x32_bf16 v[80:83], v[152:155], v[176:179], v[80:83]
	v_mfma_f32_16x16x32_bf16 v[84:87], v[148:151], v[180:183], v[84:87]
	v_mfma_f32_16x16x32_bf16 v[80:83], v[156:159], v[180:183], v[80:83]
	v_mfma_f32_16x16x32_bf16 v[68:71], v[144:147], v[184:187], v[68:71]
	v_mfma_f32_16x16x32_bf16 v[64:67], v[152:155], v[184:187], v[64:67]
	s_setprio 3
	s_barrier
	v_mfma_f32_16x16x32_bf16 v[68:71], v[148:151], v[188:191], v[68:71]
	v_mfma_f32_16x16x32_bf16 v[64:67], v[156:159], v[188:191], v[64:67]
	s_setprio 0
	s_add_i32 s67, s67, s15
	v_lshl_add_u64 v[204:205], v[204:205], 0, s[46:47]
	s_mov_b32 m0, s67
	ds_read_b128 v[160:163], v247 offset:49152
	ds_read_b128 v[164:167], v247 offset:50176
	ds_read_b128 v[168:171], v247 offset:51200
	ds_read_b128 v[172:175], v247 offset:52224
	ds_read_b128 v[176:179], v247 offset:53248
	ds_read_b128 v[180:183], v247 offset:54272
	ds_read_b128 v[184:187], v247 offset:55296
	ds_read_b128 v[188:191], v247 offset:56320
	global_load_lds_dwordx4 v[204:205], off
	s_add_i32 m0, s67, 0x2000
	s_add_u32 s68, s78, 0x40080
	v_lshl_add_u64 v[204:205], v[206:207], 0, s[46:47]
	s_addc_u32 s69, s79, 0
	s_add_i32 s67, s75, s15
	global_load_lds_dwordx4 v[204:205], off
	s_mov_b32 m0, s67
	v_lshl_add_u64 v[204:205], s[68:69], 0, v[194:195]
	global_load_lds_dwordx4 v[204:205], off
	s_add_i32 m0, s67, 0x2000
	v_lshl_add_u64 v[204:205], s[68:69], 0, v[198:199]
	global_load_lds_dwordx4 v[204:205], off
	s_mov_b32 m0, s21
	v_lshl_add_u64 v[204:205], v[208:209], 0, s[46:47]
	global_load_lds_dwordx4 v[204:205], off
	s_mov_b32 m0, s22
	v_lshl_add_u64 v[204:205], v[210:211], 0, s[46:47]
	global_load_lds_dwordx4 v[204:205], off
	s_waitcnt vmcnt(8) lgkmcnt(0)
	s_barrier
	s_setprio 1
	v_mfma_f32_16x16x32_bf16 v[60:63], v[120:123], v[160:163], v[60:63]
	v_mfma_f32_16x16x32_bf16 v[56:59], v[128:131], v[160:163], v[56:59]
	v_mfma_f32_16x16x32_bf16 v[60:63], v[124:127], v[164:167], v[60:63]
	v_mfma_f32_16x16x32_bf16 v[56:59], v[132:135], v[164:167], v[56:59]
	v_mfma_f32_16x16x32_bf16 v[44:47], v[120:123], v[168:171], v[44:47]
	v_mfma_f32_16x16x32_bf16 v[40:43], v[128:131], v[168:171], v[40:43]
	v_mfma_f32_16x16x32_bf16 v[44:47], v[124:127], v[172:175], v[44:47]
	v_mfma_f32_16x16x32_bf16 v[40:43], v[132:135], v[172:175], v[40:43]
	v_mfma_f32_16x16x32_bf16 v[28:31], v[120:123], v[176:179], v[28:31]
	v_mfma_f32_16x16x32_bf16 v[24:27], v[128:131], v[176:179], v[24:27]
	v_mfma_f32_16x16x32_bf16 v[28:31], v[124:127], v[180:183], v[28:31]
	v_mfma_f32_16x16x32_bf16 v[24:27], v[132:135], v[180:183], v[24:27]
	v_mfma_f32_16x16x32_bf16 v[12:15], v[120:123], v[184:187], v[12:15]
	v_mfma_f32_16x16x32_bf16 v[8:11], v[128:131], v[184:187], v[8:11]
	v_mfma_f32_16x16x32_bf16 v[12:15], v[124:127], v[188:191], v[12:15]
	v_mfma_f32_16x16x32_bf16 v[8:11], v[132:135], v[188:191], v[8:11]
	v_mfma_f32_16x16x32_bf16 v[52:55], v[144:147], v[160:163], v[52:55]
	v_mfma_f32_16x16x32_bf16 v[48:51], v[152:155], v[160:163], v[48:51]
	v_mfma_f32_16x16x32_bf16 v[52:55], v[148:151], v[164:167], v[52:55]
	v_mfma_f32_16x16x32_bf16 v[48:51], v[156:159], v[164:167], v[48:51]
	v_mfma_f32_16x16x32_bf16 v[36:39], v[144:147], v[168:171], v[36:39]
	v_mfma_f32_16x16x32_bf16 v[32:35], v[152:155], v[168:171], v[32:35]
	v_mfma_f32_16x16x32_bf16 v[36:39], v[148:151], v[172:175], v[36:39]
	v_mfma_f32_16x16x32_bf16 v[32:35], v[156:159], v[172:175], v[32:35]
	v_mfma_f32_16x16x32_bf16 v[20:23], v[144:147], v[176:179], v[20:23]
	v_mfma_f32_16x16x32_bf16 v[16:19], v[152:155], v[176:179], v[16:19]
	v_mfma_f32_16x16x32_bf16 v[20:23], v[148:151], v[180:183], v[20:23]
	v_mfma_f32_16x16x32_bf16 v[16:19], v[156:159], v[180:183], v[16:19]
	v_mfma_f32_16x16x32_bf16 v[4:7], v[144:147], v[184:187], v[4:7]
	v_mfma_f32_16x16x32_bf16 v[0:3], v[152:155], v[184:187], v[0:3]
	s_setprio 3
	s_barrier
	v_mfma_f32_16x16x32_bf16 v[4:7], v[148:151], v[188:191], v[4:7]
	v_mfma_f32_16x16x32_bf16 v[0:3], v[156:159], v[188:191], v[0:3]
	s_setprio 0
	s_add_i32 s66, s66, 2
	s_add_u32 s76, s76, 0x100
	s_addc_u32 s77, s77, 0
	s_add_u32 s56, s56, 0x100
	s_addc_u32 s57, s57, 0
	s_cmp_gt_u32 s66, 13
	s_cbranch_scc0 .LBB0_2037
	s_branch .Lzskip_9

.LBB0_2192:
	ds_read_b128 v[146:149], v174
	ds_read_b128 v[150:153], v174 offset:1024
	ds_read_b128 v[154:157], v174 offset:2048
	ds_read_b128 v[158:161], v174 offset:3072
	ds_read_b128 v[162:165], v175
	ds_read_b128 v[178:181], v175 offset:1024
	ds_read_b128 v[182:185], v175 offset:2048
	ds_read_b128 v[186:189], v175 offset:3072
	s_add_u32 s70, s58, 0xfffc0080
	s_addc_u32 s71, s59, -1
	s_cmp_eq_u32 s69, 12
	s_cselect_b32 s73, s47, s71
	s_cselect_b32 s72, s53, s70
	s_cselect_b32 s71, s45, s68
	s_cselect_b32 s70, s66, s67
	v_lshl_add_u64 v[166:167], s[58:59], 0, v[136:137]
	s_add_i32 m0, s17, 0xc000
	ds_read_b128 v[190:193], v176
	ds_read_b128 v[194:197], v176 offset:1024
	ds_read_b128 v[198:201], v176 offset:2048
	ds_read_b128 v[202:205], v176 offset:3072
	ds_read_b128 v[206:209], v176 offset:4096
	ds_read_b128 v[210:213], v176 offset:5120
	ds_read_b128 v[214:217], v176 offset:6144
	ds_read_b128 v[218:221], v176 offset:7168
	global_load_lds_dwordx4 v[166:167], off
	s_add_i32 m0, s17, 0xe000
	v_lshl_add_u64 v[166:167], s[58:59], 0, v[140:141]
	global_load_lds_dwordx4 v[166:167], off
	s_cmp_eq_u32 s69, -2
	s_waitcnt vmcnt(8) lgkmcnt(0)
	s_barrier
	s_setprio 1
	s_cbranch_scc1 .Lzv_10_0
	v_mfma_f32_16x16x32_bf16 v[124:127], v[146:149], v[190:193], v[124:127]
	v_mfma_f32_16x16x32_bf16 v[116:119], v[154:157], v[190:193], v[116:119]
	v_mfma_f32_16x16x32_bf16 v[124:127], v[150:153], v[194:197], v[124:127]
	v_mfma_f32_16x16x32_bf16 v[116:119], v[158:161], v[194:197], v[116:119]
	v_mfma_f32_16x16x32_bf16 v[108:111], v[146:149], v[198:201], v[108:111]
	v_mfma_f32_16x16x32_bf16 v[100:103], v[154:157], v[198:201], v[100:103]
	v_mfma_f32_16x16x32_bf16 v[108:111], v[150:153], v[202:205], v[108:111]
	v_mfma_f32_16x16x32_bf16 v[100:103], v[158:161], v[202:205], v[100:103]
	v_mfma_f32_16x16x32_bf16 v[92:95], v[146:149], v[206:209], v[92:95]
	v_mfma_f32_16x16x32_bf16 v[84:87], v[154:157], v[206:209], v[84:87]
	v_mfma_f32_16x16x32_bf16 v[92:95], v[150:153], v[210:213], v[92:95]
	v_mfma_f32_16x16x32_bf16 v[84:87], v[158:161], v[210:213], v[84:87]
	v_mfma_f32_16x16x32_bf16 v[76:79], v[146:149], v[214:217], v[76:79]
	v_mfma_f32_16x16x32_bf16 v[68:71], v[154:157], v[214:217], v[68:71]
	v_mfma_f32_16x16x32_bf16 v[76:79], v[150:153], v[218:221], v[76:79]
	v_mfma_f32_16x16x32_bf16 v[68:71], v[158:161], v[218:221], v[68:71]
	v_mfma_f32_16x16x32_bf16 v[120:123], v[162:165], v[190:193], v[120:123]
	v_mfma_f32_16x16x32_bf16 v[112:115], v[182:185], v[190:193], v[112:115]
	v_mfma_f32_16x16x32_bf16 v[120:123], v[178:181], v[194:197], v[120:123]
	v_mfma_f32_16x16x32_bf16 v[112:115], v[186:189], v[194:197], v[112:115]
	v_mfma_f32_16x16x32_bf16 v[104:107], v[162:165], v[198:201], v[104:107]
	v_mfma_f32_16x16x32_bf16 v[96:99], v[182:185], v[198:201], v[96:99]
	v_mfma_f32_16x16x32_bf16 v[104:107], v[178:181], v[202:205], v[104:107]
	v_mfma_f32_16x16x32_bf16 v[96:99], v[186:189], v[202:205], v[96:99]
	v_mfma_f32_16x16x32_bf16 v[88:91], v[162:165], v[206:209], v[88:91]
	v_mfma_f32_16x16x32_bf16 v[80:83], v[182:185], v[206:209], v[80:83]
	v_mfma_f32_16x16x32_bf16 v[88:91], v[178:181], v[210:213], v[88:91]
	v_mfma_f32_16x16x32_bf16 v[80:83], v[186:189], v[210:213], v[80:83]
	v_mfma_f32_16x16x32_bf16 v[72:75], v[162:165], v[214:217], v[72:75]
	v_mfma_f32_16x16x32_bf16 v[64:67], v[182:185], v[214:217], v[64:67]
	s_setprio 3
	s_barrier
	v_mfma_f32_16x16x32_bf16 v[72:75], v[178:181], v[218:221], v[72:75]
	v_mfma_f32_16x16x32_bf16 v[64:67], v[186:189], v[218:221], v[64:67]
	s_setprio 0
.Lzj_10_0:
	s_add_i32 s74, s26, s16
	v_lshl_add_u64 v[166:167], s[70:71], 0, v[132:133]
	s_mov_b32 m0, s74
	ds_read_b128 v[190:193], v176 offset:16384
	ds_read_b128 v[194:197], v176 offset:17408
	ds_read_b128 v[198:201], v176 offset:18432
	ds_read_b128 v[202:205], v176 offset:19456
	ds_read_b128 v[206:209], v176 offset:20480
	ds_read_b128 v[210:213], v176 offset:21504
	ds_read_b128 v[214:217], v176 offset:22528
	ds_read_b128 v[218:221], v176 offset:23552
	global_load_lds_dwordx4 v[166:167], off
	s_add_i32 m0, s74, 0x2000
	s_add_u32 s74, s70, 0x40000
	v_lshl_add_u64 v[222:223], s[70:71], 0, v[128:129]
	s_addc_u32 s75, s71, 0
	s_add_i32 s76, s27, s16
	global_load_lds_dwordx4 v[222:223], off
	v_lshl_add_u64 v[224:225], s[74:75], 0, v[132:133]
	s_mov_b32 m0, s76
	global_load_lds_dwordx4 v[224:225], off
	s_add_i32 m0, s76, 0x2000
	v_lshl_add_u64 v[224:225], s[74:75], 0, v[128:129]
	global_load_lds_dwordx4 v[224:225], off
	s_mov_b32 m0, s17
	v_lshl_add_u64 v[224:225], s[72:73], 0, v[134:135]
	global_load_lds_dwordx4 v[224:225], off
	s_mov_b32 m0, s18
	v_lshl_add_u64 v[226:227], s[72:73], 0, v[130:131]
	global_load_lds_dwordx4 v[226:227], off
	s_cmp_eq_u32 s69, -2
	s_waitcnt vmcnt(8) lgkmcnt(0)
	s_barrier
	s_setprio 1
	s_cbranch_scc1 .Lzv_10_1
	v_mfma_f32_16x16x32_bf16 v[60:63], v[146:149], v[190:193], v[60:63]
	v_mfma_f32_16x16x32_bf16 v[52:55], v[154:157], v[190:193], v[52:55]
	v_mfma_f32_16x16x32_bf16 v[60:63], v[150:153], v[194:197], v[60:63]
	v_mfma_f32_16x16x32_bf16 v[52:55], v[158:161], v[194:197], v[52:55]
	v_mfma_f32_16x16x32_bf16 v[44:47], v[146:149], v[198:201], v[44:47]
	v_mfma_f32_16x16x32_bf16 v[36:39], v[154:157], v[198:201], v[36:39]
	v_mfma_f32_16x16x32_bf16 v[44:47], v[150:153], v[202:205], v[44:47]
	v_mfma_f32_16x16x32_bf16 v[36:39], v[158:161], v[202:205], v[36:39]
	v_mfma_f32_16x16x32_bf16 v[28:31], v[146:149], v[206:209], v[28:31]
	v_mfma_f32_16x16x32_bf16 v[20:23], v[154:157], v[206:209], v[20:23]
	v_mfma_f32_16x16x32_bf16 v[28:31], v[150:153], v[210:213], v[28:31]
	v_mfma_f32_16x16x32_bf16 v[20:23], v[158:161], v[210:213], v[20:23]
	v_mfma_f32_16x16x32_bf16 v[12:15], v[146:149], v[214:217], v[12:15]
	v_mfma_f32_16x16x32_bf16 v[4:7], v[154:157], v[214:217], v[4:7]
	v_mfma_f32_16x16x32_bf16 v[12:15], v[150:153], v[218:221], v[12:15]
	v_mfma_f32_16x16x32_bf16 v[4:7], v[158:161], v[218:221], v[4:7]
	v_mfma_f32_16x16x32_bf16 v[56:59], v[162:165], v[190:193], v[56:59]
	v_mfma_f32_16x16x32_bf16 v[48:51], v[182:185], v[190:193], v[48:51]
	v_mfma_f32_16x16x32_bf16 v[56:59], v[178:181], v[194:197], v[56:59]
	v_mfma_f32_16x16x32_bf16 v[48:51], v[186:189], v[194:197], v[48:51]
	v_mfma_f32_16x16x32_bf16 v[40:43], v[162:165], v[198:201], v[40:43]
	v_mfma_f32_16x16x32_bf16 v[32:35], v[182:185], v[198:201], v[32:35]
	v_mfma_f32_16x16x32_bf16 v[40:43], v[178:181], v[202:205], v[40:43]
	v_mfma_f32_16x16x32_bf16 v[32:35], v[186:189], v[202:205], v[32:35]
	v_mfma_f32_16x16x32_bf16 v[24:27], v[162:165], v[206:209], v[24:27]
	v_mfma_f32_16x16x32_bf16 v[16:19], v[182:185], v[206:209], v[16:19]
	v_mfma_f32_16x16x32_bf16 v[24:27], v[178:181], v[210:213], v[24:27]
	v_mfma_f32_16x16x32_bf16 v[16:19], v[186:189], v[210:213], v[16:19]
	v_mfma_f32_16x16x32_bf16 v[8:11], v[162:165], v[214:217], v[8:11]
	v_mfma_f32_16x16x32_bf16 v[0:3], v[182:185], v[214:217], v[0:3]
	s_setprio 3
	s_barrier
	v_mfma_f32_16x16x32_bf16 v[8:11], v[178:181], v[218:221], v[8:11]
	v_mfma_f32_16x16x32_bf16 v[0:3], v[186:189], v[218:221], v[0:3]
	s_setprio 0
.Lzj_10_1:
	s_add_i32 s74, 0, 0x18000
	s_add_i32 s75, 0, 0x1c000
	v_add_u32_e32 v158, s74, v171
	v_add_u32_e32 v186, s75, v171
	ds_read_b128 v[146:149], v158
	ds_read_b128 v[150:153], v158 offset:1024
	ds_read_b128 v[154:157], v158 offset:2048
	ds_read_b128 v[158:161], v158 offset:3072
	ds_read_b128 v[162:165], v186
	ds_read_b128 v[178:181], v186 offset:1024
	ds_read_b128 v[182:185], v186 offset:2048
	ds_read_b128 v[186:189], v186 offset:3072
	s_add_u32 s72, s72, 0x40000
	s_addc_u32 s73, s73, 0
	s_mov_b32 m0, s19
	v_lshl_add_u64 v[228:229], s[72:73], 0, v[134:135]
	ds_read_b128 v[190:193], v176 offset:32768
	ds_read_b128 v[194:197], v176 offset:33792
	ds_read_b128 v[198:201], v176 offset:34816
	ds_read_b128 v[202:205], v176 offset:35840
	ds_read_b128 v[206:209], v176 offset:36864
	ds_read_b128 v[210:213], v176 offset:37888
	ds_read_b128 v[214:217], v176 offset:38912
	ds_read_b128 v[218:221], v176 offset:39936
	global_load_lds_dwordx4 v[228:229], off
	s_mov_b32 m0, s20
	v_lshl_add_u64 v[228:229], s[72:73], 0, v[130:131]
	global_load_lds_dwordx4 v[228:229], off
	s_waitcnt vmcnt(8) lgkmcnt(0)
	s_barrier
	s_setprio 1
	v_mfma_f32_16x16x32_bf16 v[124:127], v[146:149], v[190:193], v[124:127]
	v_mfma_f32_16x16x32_bf16 v[116:119], v[154:157], v[190:193], v[116:119]
	v_mfma_f32_16x16x32_bf16 v[124:127], v[150:153], v[194:197], v[124:127]
	v_mfma_f32_16x16x32_bf16 v[116:119], v[158:161], v[194:197], v[116:119]
	v_mfma_f32_16x16x32_bf16 v[108:111], v[146:149], v[198:201], v[108:111]
	v_mfma_f32_16x16x32_bf16 v[100:103], v[154:157], v[198:201], v[100:103]
	v_mfma_f32_16x16x32_bf16 v[108:111], v[150:153], v[202:205], v[108:111]
	v_mfma_f32_16x16x32_bf16 v[100:103], v[158:161], v[202:205], v[100:103]
	v_mfma_f32_16x16x32_bf16 v[92:95], v[146:149], v[206:209], v[92:95]
	v_mfma_f32_16x16x32_bf16 v[84:87], v[154:157], v[206:209], v[84:87]
	v_mfma_f32_16x16x32_bf16 v[92:95], v[150:153], v[210:213], v[92:95]
	v_mfma_f32_16x16x32_bf16 v[84:87], v[158:161], v[210:213], v[84:87]
	v_mfma_f32_16x16x32_bf16 v[76:79], v[146:149], v[214:217], v[76:79]
	v_mfma_f32_16x16x32_bf16 v[68:71], v[154:157], v[214:217], v[68:71]
	v_mfma_f32_16x16x32_bf16 v[76:79], v[150:153], v[218:221], v[76:79]
	v_mfma_f32_16x16x32_bf16 v[68:71], v[158:161], v[218:221], v[68:71]
	v_mfma_f32_16x16x32_bf16 v[120:123], v[162:165], v[190:193], v[120:123]
	v_mfma_f32_16x16x32_bf16 v[112:115], v[182:185], v[190:193], v[112:115]
	v_mfma_f32_16x16x32_bf16 v[120:123], v[178:181], v[194:197], v[120:123]
	v_mfma_f32_16x16x32_bf16 v[112:115], v[186:189], v[194:197], v[112:115]
	v_mfma_f32_16x16x32_bf16 v[104:107], v[162:165], v[198:201], v[104:107]
	v_mfma_f32_16x16x32_bf16 v[96:99], v[182:185], v[198:201], v[96:99]
	v_mfma_f32_16x16x32_bf16 v[104:107], v[178:181], v[202:205], v[104:107]
	v_mfma_f32_16x16x32_bf16 v[96:99], v[186:189], v[202:205], v[96:99]
	v_mfma_f32_16x16x32_bf16 v[88:91], v[162:165], v[206:209], v[88:91]
	v_mfma_f32_16x16x32_bf16 v[80:83], v[182:185], v[206:209], v[80:83]
	v_mfma_f32_16x16x32_bf16 v[88:91], v[178:181], v[210:213], v[88:91]
	v_mfma_f32_16x16x32_bf16 v[80:83], v[186:189], v[210:213], v[80:83]
	v_mfma_f32_16x16x32_bf16 v[72:75], v[162:165], v[214:217], v[72:75]
	v_mfma_f32_16x16x32_bf16 v[64:67], v[182:185], v[214:217], v[64:67]
	s_setprio 3
	s_barrier
	v_mfma_f32_16x16x32_bf16 v[72:75], v[178:181], v[218:221], v[72:75]
	v_mfma_f32_16x16x32_bf16 v[64:67], v[186:189], v[218:221], v[64:67]
	s_setprio 0
	s_add_i32 s72, s74, s16
	v_lshl_add_u64 v[166:167], v[166:167], 0, s[10:11]
	s_mov_b32 m0, s72
	ds_read_b128 v[190:193], v176 offset:49152
	ds_read_b128 v[194:197], v176 offset:50176
	ds_read_b128 v[198:201], v176 offset:51200
	ds_read_b128 v[202:205], v176 offset:52224
	ds_read_b128 v[206:209], v176 offset:53248
	ds_read_b128 v[210:213], v176 offset:54272
	ds_read_b128 v[214:217], v176 offset:55296
	ds_read_b128 v[218:221], v176 offset:56320
	global_load_lds_dwordx4 v[166:167], off
	s_add_i32 m0, s72, 0x2000
	s_add_u32 s70, s70, 0x40080
	v_lshl_add_u64 v[166:167], v[222:223], 0, s[10:11]
	s_addc_u32 s71, s71, 0
	s_add_i32 s72, s75, s16
	global_load_lds_dwordx4 v[166:167], off
	s_mov_b32 m0, s72
	v_lshl_add_u64 v[166:167], s[70:71], 0, v[132:133]
	global_load_lds_dwordx4 v[166:167], off
	s_add_i32 m0, s72, 0x2000
	v_lshl_add_u64 v[166:167], s[70:71], 0, v[128:129]
	global_load_lds_dwordx4 v[166:167], off
	s_mov_b32 m0, s23
	v_lshl_add_u64 v[166:167], v[224:225], 0, s[10:11]
	global_load_lds_dwordx4 v[166:167], off
	s_mov_b32 m0, s24
	v_lshl_add_u64 v[166:167], v[226:227], 0, s[10:11]
	global_load_lds_dwordx4 v[166:167], off
	s_waitcnt vmcnt(8) lgkmcnt(0)
	s_barrier
	s_setprio 1
	v_mfma_f32_16x16x32_bf16 v[60:63], v[146:149], v[190:193], v[60:63]
	v_mfma_f32_16x16x32_bf16 v[52:55], v[154:157], v[190:193], v[52:55]
	v_mfma_f32_16x16x32_bf16 v[60:63], v[150:153], v[194:197], v[60:63]
	v_mfma_f32_16x16x32_bf16 v[52:55], v[158:161], v[194:197], v[52:55]
	v_mfma_f32_16x16x32_bf16 v[44:47], v[146:149], v[198:201], v[44:47]
	v_mfma_f32_16x16x32_bf16 v[36:39], v[154:157], v[198:201], v[36:39]
	v_mfma_f32_16x16x32_bf16 v[44:47], v[150:153], v[202:205], v[44:47]
	v_mfma_f32_16x16x32_bf16 v[36:39], v[158:161], v[202:205], v[36:39]
	v_mfma_f32_16x16x32_bf16 v[28:31], v[146:149], v[206:209], v[28:31]
	v_mfma_f32_16x16x32_bf16 v[20:23], v[154:157], v[206:209], v[20:23]
	v_mfma_f32_16x16x32_bf16 v[28:31], v[150:153], v[210:213], v[28:31]
	v_mfma_f32_16x16x32_bf16 v[20:23], v[158:161], v[210:213], v[20:23]
	v_mfma_f32_16x16x32_bf16 v[12:15], v[146:149], v[214:217], v[12:15]
	v_mfma_f32_16x16x32_bf16 v[4:7], v[154:157], v[214:217], v[4:7]
	v_mfma_f32_16x16x32_bf16 v[12:15], v[150:153], v[218:221], v[12:15]
	v_mfma_f32_16x16x32_bf16 v[4:7], v[158:161], v[218:221], v[4:7]
	v_mfma_f32_16x16x32_bf16 v[56:59], v[162:165], v[190:193], v[56:59]
	v_mfma_f32_16x16x32_bf16 v[48:51], v[182:185], v[190:193], v[48:51]
	v_mfma_f32_16x16x32_bf16 v[56:59], v[178:181], v[194:197], v[56:59]
	v_mfma_f32_16x16x32_bf16 v[48:51], v[186:189], v[194:197], v[48:51]
	v_mfma_f32_16x16x32_bf16 v[40:43], v[162:165], v[198:201], v[40:43]
	v_mfma_f32_16x16x32_bf16 v[32:35], v[182:185], v[198:201], v[32:35]
	v_mfma_f32_16x16x32_bf16 v[40:43], v[178:181], v[202:205], v[40:43]
	v_mfma_f32_16x16x32_bf16 v[32:35], v[186:189], v[202:205], v[32:35]
	v_mfma_f32_16x16x32_bf16 v[24:27], v[162:165], v[206:209], v[24:27]
	v_mfma_f32_16x16x32_bf16 v[16:19], v[182:185], v[206:209], v[16:19]
	v_mfma_f32_16x16x32_bf16 v[24:27], v[178:181], v[210:213], v[24:27]
	v_mfma_f32_16x16x32_bf16 v[16:19], v[186:189], v[210:213], v[16:19]
	v_mfma_f32_16x16x32_bf16 v[8:11], v[162:165], v[214:217], v[8:11]
	v_mfma_f32_16x16x32_bf16 v[0:3], v[182:185], v[214:217], v[0:3]
	s_setprio 3
	s_barrier
	v_mfma_f32_16x16x32_bf16 v[8:11], v[178:181], v[218:221], v[8:11]
	v_mfma_f32_16x16x32_bf16 v[0:3], v[186:189], v[218:221], v[0:3]
	s_setprio 0
	s_add_i32 s69, s69, 2
	s_add_u32 s58, s58, 0x100
	s_addc_u32 s59, s59, 0
	s_add_u32 s67, s67, 0x100
	s_addc_u32 s68, s68, 0
	s_cmp_gt_u32 s69, 13
	s_cbranch_scc0 .LBB0_2192
	s_branch .Lzskip_10

.LBB0_2341:
	ds_read_b128 v[128:131], v197
	ds_read_b128 v[132:135], v197 offset:1024
	ds_read_b128 v[136:139], v197 offset:2048
	ds_read_b128 v[140:143], v197 offset:3072
	ds_read_b128 v[144:147], v198
	ds_read_b128 v[148:151], v198 offset:1024
	ds_read_b128 v[152:155], v198 offset:2048
	ds_read_b128 v[156:159], v198 offset:3072
	s_add_u32 s18, s16, 0xfff50080
	s_addc_u32 s19, s17, -1
	s_cmp_eq_u32 s45, 40
	s_cselect_b32 s21, s5, s19
	s_cselect_b32 s20, s4, s18
	s_cselect_b32 s19, s15, s44
	s_cselect_b32 s18, s14, s43
	v_lshl_add_u64 v[192:193], s[16:17], 0, v[172:173]
	s_add_i32 m0, s25, 0xc000
	ds_read_b128 v[160:163], v199
	ds_read_b128 v[180:183], v199 offset:1024
	ds_read_b128 v[184:187], v199 offset:2048
	ds_read_b128 v[188:191], v199 offset:3072
	ds_read_b128 v[200:203], v199 offset:4096
	ds_read_b128 v[204:207], v199 offset:5120
	ds_read_b128 v[208:211], v199 offset:6144
	ds_read_b128 v[212:215], v199 offset:7168
	global_load_lds_dwordx4 v[192:193], off
	s_add_i32 m0, s25, 0xe000
	v_lshl_add_u64 v[192:193], s[16:17], 0, v[174:175]
	global_load_lds_dwordx4 v[192:193], off
	s_cmp_eq_u32 s45, -2
	s_waitcnt vmcnt(8) lgkmcnt(0)
	s_barrier
	s_setprio 1
	s_cbranch_scc1 .Lzv_11_0
	v_mfma_f32_16x16x32_bf16 v[124:127], v[128:131], v[160:163], v[124:127]
	v_mfma_f32_16x16x32_bf16 v[120:123], v[136:139], v[160:163], v[120:123]
	v_mfma_f32_16x16x32_bf16 v[124:127], v[132:135], v[180:183], v[124:127]
	v_mfma_f32_16x16x32_bf16 v[120:123], v[140:143], v[180:183], v[120:123]
	v_mfma_f32_16x16x32_bf16 v[108:111], v[128:131], v[184:187], v[108:111]
	v_mfma_f32_16x16x32_bf16 v[104:107], v[136:139], v[184:187], v[104:107]
	v_mfma_f32_16x16x32_bf16 v[108:111], v[132:135], v[188:191], v[108:111]
	v_mfma_f32_16x16x32_bf16 v[104:107], v[140:143], v[188:191], v[104:107]
	v_mfma_f32_16x16x32_bf16 v[96:99], v[128:131], v[200:203], v[96:99]
	v_mfma_f32_16x16x32_bf16 v[88:91], v[136:139], v[200:203], v[88:91]
	v_mfma_f32_16x16x32_bf16 v[96:99], v[132:135], v[204:207], v[96:99]
	v_mfma_f32_16x16x32_bf16 v[88:91], v[140:143], v[204:207], v[88:91]
	v_mfma_f32_16x16x32_bf16 v[80:83], v[128:131], v[208:211], v[80:83]
	v_mfma_f32_16x16x32_bf16 v[72:75], v[136:139], v[208:211], v[72:75]
	v_mfma_f32_16x16x32_bf16 v[80:83], v[132:135], v[212:215], v[80:83]
	v_mfma_f32_16x16x32_bf16 v[72:75], v[140:143], v[212:215], v[72:75]
	v_mfma_f32_16x16x32_bf16 v[116:119], v[144:147], v[160:163], v[116:119]
	v_mfma_f32_16x16x32_bf16 v[112:115], v[152:155], v[160:163], v[112:115]
	v_mfma_f32_16x16x32_bf16 v[116:119], v[148:151], v[180:183], v[116:119]
	v_mfma_f32_16x16x32_bf16 v[112:115], v[156:159], v[180:183], v[112:115]
	v_mfma_f32_16x16x32_bf16 v[100:103], v[144:147], v[184:187], v[100:103]
	v_mfma_f32_16x16x32_bf16 v[92:95], v[152:155], v[184:187], v[92:95]
	v_mfma_f32_16x16x32_bf16 v[100:103], v[148:151], v[188:191], v[100:103]
	v_mfma_f32_16x16x32_bf16 v[92:95], v[156:159], v[188:191], v[92:95]
	v_mfma_f32_16x16x32_bf16 v[84:87], v[144:147], v[200:203], v[84:87]
	v_mfma_f32_16x16x32_bf16 v[76:79], v[152:155], v[200:203], v[76:79]
	v_mfma_f32_16x16x32_bf16 v[84:87], v[148:151], v[204:207], v[84:87]
	v_mfma_f32_16x16x32_bf16 v[76:79], v[156:159], v[204:207], v[76:79]
	v_mfma_f32_16x16x32_bf16 v[68:71], v[144:147], v[208:211], v[68:71]
	v_mfma_f32_16x16x32_bf16 v[64:67], v[152:155], v[208:211], v[64:67]
	s_setprio 3
	s_barrier
	v_mfma_f32_16x16x32_bf16 v[68:71], v[148:151], v[212:215], v[68:71]
	v_mfma_f32_16x16x32_bf16 v[64:67], v[156:159], v[212:215], v[64:67]
	s_setprio 0
.Lzj_11_0:
	s_add_i32 s46, s37, s24
	v_lshl_add_u64 v[192:193], s[18:19], 0, v[166:167]
	s_mov_b32 m0, s46
	ds_read_b128 v[160:163], v199 offset:16384
	ds_read_b128 v[180:183], v199 offset:17408
	ds_read_b128 v[184:187], v199 offset:18432
	ds_read_b128 v[188:191], v199 offset:19456
	ds_read_b128 v[200:203], v199 offset:20480
	ds_read_b128 v[204:207], v199 offset:21504
	ds_read_b128 v[208:211], v199 offset:22528
	ds_read_b128 v[212:215], v199 offset:23552
	global_load_lds_dwordx4 v[192:193], off
	s_add_i32 m0, s46, 0x2000
	s_add_u32 s46, s18, 0xb0000
	v_lshl_add_u64 v[216:217], s[18:19], 0, v[170:171]
	s_addc_u32 s47, s19, 0
	s_add_i32 s48, s38, s24
	global_load_lds_dwordx4 v[216:217], off
	v_lshl_add_u64 v[218:219], s[46:47], 0, v[166:167]
	s_mov_b32 m0, s48
	global_load_lds_dwordx4 v[218:219], off
	s_add_i32 m0, s48, 0x2000
	v_lshl_add_u64 v[218:219], s[46:47], 0, v[170:171]
	global_load_lds_dwordx4 v[218:219], off
	s_mov_b32 m0, s25
	v_lshl_add_u64 v[218:219], s[20:21], 0, v[164:165]
	global_load_lds_dwordx4 v[218:219], off
	s_mov_b32 m0, s26
	v_lshl_add_u64 v[220:221], s[20:21], 0, v[168:169]
	global_load_lds_dwordx4 v[220:221], off
	s_cmp_eq_u32 s45, -2
	s_waitcnt vmcnt(8) lgkmcnt(0)
	s_barrier
	s_setprio 1
	s_cbranch_scc1 .Lzv_11_1
	v_mfma_f32_16x16x32_bf16 v[60:63], v[128:131], v[160:163], v[60:63]
	v_mfma_f32_16x16x32_bf16 v[56:59], v[136:139], v[160:163], v[56:59]
	v_mfma_f32_16x16x32_bf16 v[60:63], v[132:135], v[180:183], v[60:63]
	v_mfma_f32_16x16x32_bf16 v[56:59], v[140:143], v[180:183], v[56:59]
	v_mfma_f32_16x16x32_bf16 v[48:51], v[128:131], v[184:187], v[48:51]
	v_mfma_f32_16x16x32_bf16 v[40:43], v[136:139], v[184:187], v[40:43]
	v_mfma_f32_16x16x32_bf16 v[48:51], v[132:135], v[188:191], v[48:51]
	v_mfma_f32_16x16x32_bf16 v[40:43], v[140:143], v[188:191], v[40:43]
	v_mfma_f32_16x16x32_bf16 v[32:35], v[128:131], v[200:203], v[32:35]
	v_mfma_f32_16x16x32_bf16 v[24:27], v[136:139], v[200:203], v[24:27]
	v_mfma_f32_16x16x32_bf16 v[32:35], v[132:135], v[204:207], v[32:35]
	v_mfma_f32_16x16x32_bf16 v[24:27], v[140:143], v[204:207], v[24:27]
	v_mfma_f32_16x16x32_bf16 v[16:19], v[128:131], v[208:211], v[16:19]
	v_mfma_f32_16x16x32_bf16 v[8:11], v[136:139], v[208:211], v[8:11]
	v_mfma_f32_16x16x32_bf16 v[16:19], v[132:135], v[212:215], v[16:19]
	v_mfma_f32_16x16x32_bf16 v[8:11], v[140:143], v[212:215], v[8:11]
	v_mfma_f32_16x16x32_bf16 v[52:55], v[144:147], v[160:163], v[52:55]
	v_mfma_f32_16x16x32_bf16 v[44:47], v[152:155], v[160:163], v[44:47]
	v_mfma_f32_16x16x32_bf16 v[52:55], v[148:151], v[180:183], v[52:55]
	v_mfma_f32_16x16x32_bf16 v[44:47], v[156:159], v[180:183], v[44:47]
	v_mfma_f32_16x16x32_bf16 v[36:39], v[144:147], v[184:187], v[36:39]
	v_mfma_f32_16x16x32_bf16 v[28:31], v[152:155], v[184:187], v[28:31]
	v_mfma_f32_16x16x32_bf16 v[36:39], v[148:151], v[188:191], v[36:39]
	v_mfma_f32_16x16x32_bf16 v[28:31], v[156:159], v[188:191], v[28:31]
	v_mfma_f32_16x16x32_bf16 v[20:23], v[144:147], v[200:203], v[20:23]
	v_mfma_f32_16x16x32_bf16 v[12:15], v[152:155], v[200:203], v[12:15]
	v_mfma_f32_16x16x32_bf16 v[20:23], v[148:151], v[204:207], v[20:23]
	v_mfma_f32_16x16x32_bf16 v[12:15], v[156:159], v[204:207], v[12:15]
	v_mfma_f32_16x16x32_bf16 v[4:7], v[144:147], v[208:211], v[4:7]
	v_mfma_f32_16x16x32_bf16 v[0:3], v[152:155], v[208:211], v[0:3]
	s_setprio 3
	s_barrier
	v_mfma_f32_16x16x32_bf16 v[4:7], v[148:151], v[212:215], v[4:7]
	v_mfma_f32_16x16x32_bf16 v[0:3], v[156:159], v[212:215], v[0:3]
	s_setprio 0
.Lzj_11_1:
	s_add_i32 s46, 0, 0x18000
	s_add_i32 s47, 0, 0x1c000
	v_add_u32_e32 v140, s46, v195
	v_add_u32_e32 v156, s47, v195
	ds_read_b128 v[128:131], v140
	ds_read_b128 v[132:135], v140 offset:1024
	ds_read_b128 v[136:139], v140 offset:2048
	ds_read_b128 v[140:143], v140 offset:3072
	ds_read_b128 v[144:147], v156
	ds_read_b128 v[148:151], v156 offset:1024
	ds_read_b128 v[152:155], v156 offset:2048
	ds_read_b128 v[156:159], v156 offset:3072
	s_add_u32 s20, s20, 0xb0000
	s_addc_u32 s21, s21, 0
	s_mov_b32 m0, s27
	v_lshl_add_u64 v[222:223], s[20:21], 0, v[164:165]
	ds_read_b128 v[160:163], v199 offset:32768
	ds_read_b128 v[180:183], v199 offset:33792
	ds_read_b128 v[184:187], v199 offset:34816
	ds_read_b128 v[188:191], v199 offset:35840
	ds_read_b128 v[200:203], v199 offset:36864
	ds_read_b128 v[204:207], v199 offset:37888
	ds_read_b128 v[208:211], v199 offset:38912
	ds_read_b128 v[212:215], v199 offset:39936
	global_load_lds_dwordx4 v[222:223], off
	s_mov_b32 m0, s28
	v_lshl_add_u64 v[222:223], s[20:21], 0, v[168:169]
	global_load_lds_dwordx4 v[222:223], off
	s_waitcnt vmcnt(8) lgkmcnt(0)
	s_barrier
	s_setprio 1
	v_mfma_f32_16x16x32_bf16 v[124:127], v[128:131], v[160:163], v[124:127]
	v_mfma_f32_16x16x32_bf16 v[120:123], v[136:139], v[160:163], v[120:123]
	v_mfma_f32_16x16x32_bf16 v[124:127], v[132:135], v[180:183], v[124:127]
	v_mfma_f32_16x16x32_bf16 v[120:123], v[140:143], v[180:183], v[120:123]
	v_mfma_f32_16x16x32_bf16 v[108:111], v[128:131], v[184:187], v[108:111]
	v_mfma_f32_16x16x32_bf16 v[104:107], v[136:139], v[184:187], v[104:107]
	v_mfma_f32_16x16x32_bf16 v[108:111], v[132:135], v[188:191], v[108:111]
	v_mfma_f32_16x16x32_bf16 v[104:107], v[140:143], v[188:191], v[104:107]
	v_mfma_f32_16x16x32_bf16 v[96:99], v[128:131], v[200:203], v[96:99]
	v_mfma_f32_16x16x32_bf16 v[88:91], v[136:139], v[200:203], v[88:91]
	v_mfma_f32_16x16x32_bf16 v[96:99], v[132:135], v[204:207], v[96:99]
	v_mfma_f32_16x16x32_bf16 v[88:91], v[140:143], v[204:207], v[88:91]
	v_mfma_f32_16x16x32_bf16 v[80:83], v[128:131], v[208:211], v[80:83]
	v_mfma_f32_16x16x32_bf16 v[72:75], v[136:139], v[208:211], v[72:75]
	v_mfma_f32_16x16x32_bf16 v[80:83], v[132:135], v[212:215], v[80:83]
	v_mfma_f32_16x16x32_bf16 v[72:75], v[140:143], v[212:215], v[72:75]
	v_mfma_f32_16x16x32_bf16 v[116:119], v[144:147], v[160:163], v[116:119]
	v_mfma_f32_16x16x32_bf16 v[112:115], v[152:155], v[160:163], v[112:115]
	v_mfma_f32_16x16x32_bf16 v[116:119], v[148:151], v[180:183], v[116:119]
	v_mfma_f32_16x16x32_bf16 v[112:115], v[156:159], v[180:183], v[112:115]
	v_mfma_f32_16x16x32_bf16 v[100:103], v[144:147], v[184:187], v[100:103]
	v_mfma_f32_16x16x32_bf16 v[92:95], v[152:155], v[184:187], v[92:95]
	v_mfma_f32_16x16x32_bf16 v[100:103], v[148:151], v[188:191], v[100:103]
	v_mfma_f32_16x16x32_bf16 v[92:95], v[156:159], v[188:191], v[92:95]
	v_mfma_f32_16x16x32_bf16 v[84:87], v[144:147], v[200:203], v[84:87]
	v_mfma_f32_16x16x32_bf16 v[76:79], v[152:155], v[200:203], v[76:79]
	v_mfma_f32_16x16x32_bf16 v[84:87], v[148:151], v[204:207], v[84:87]
	v_mfma_f32_16x16x32_bf16 v[76:79], v[156:159], v[204:207], v[76:79]
	v_mfma_f32_16x16x32_bf16 v[68:71], v[144:147], v[208:211], v[68:71]
	v_mfma_f32_16x16x32_bf16 v[64:67], v[152:155], v[208:211], v[64:67]
	s_setprio 3
	s_barrier
	v_mfma_f32_16x16x32_bf16 v[68:71], v[148:151], v[212:215], v[68:71]
	v_mfma_f32_16x16x32_bf16 v[64:67], v[156:159], v[212:215], v[64:67]
	s_setprio 0
	s_add_i32 s20, s46, s24
	v_lshl_add_u64 v[192:193], v[192:193], 0, s[8:9]
	s_mov_b32 m0, s20
	ds_read_b128 v[160:163], v199 offset:49152
	ds_read_b128 v[180:183], v199 offset:50176
	ds_read_b128 v[184:187], v199 offset:51200
	ds_read_b128 v[188:191], v199 offset:52224
	ds_read_b128 v[200:203], v199 offset:53248
	ds_read_b128 v[204:207], v199 offset:54272
	ds_read_b128 v[208:211], v199 offset:55296
	ds_read_b128 v[212:215], v199 offset:56320
	global_load_lds_dwordx4 v[192:193], off
	s_add_i32 m0, s20, 0x2000
	s_add_u32 s18, s18, 0xb0080
	v_lshl_add_u64 v[192:193], v[216:217], 0, s[8:9]
	s_addc_u32 s19, s19, 0
	s_add_i32 s20, s47, s24
	global_load_lds_dwordx4 v[192:193], off
	s_mov_b32 m0, s20
	v_lshl_add_u64 v[192:193], s[18:19], 0, v[166:167]
	global_load_lds_dwordx4 v[192:193], off
	s_add_i32 m0, s20, 0x2000
	v_lshl_add_u64 v[192:193], s[18:19], 0, v[170:171]
	global_load_lds_dwordx4 v[192:193], off
	s_mov_b32 m0, s33
	v_lshl_add_u64 v[192:193], v[218:219], 0, s[8:9]
	global_load_lds_dwordx4 v[192:193], off
	s_mov_b32 m0, s35
	v_lshl_add_u64 v[192:193], v[220:221], 0, s[8:9]
	global_load_lds_dwordx4 v[192:193], off
	s_waitcnt vmcnt(8) lgkmcnt(0)
	s_barrier
	s_setprio 1
	v_mfma_f32_16x16x32_bf16 v[60:63], v[128:131], v[160:163], v[60:63]
	v_mfma_f32_16x16x32_bf16 v[56:59], v[136:139], v[160:163], v[56:59]
	v_mfma_f32_16x16x32_bf16 v[60:63], v[132:135], v[180:183], v[60:63]
	v_mfma_f32_16x16x32_bf16 v[56:59], v[140:143], v[180:183], v[56:59]
	v_mfma_f32_16x16x32_bf16 v[48:51], v[128:131], v[184:187], v[48:51]
	v_mfma_f32_16x16x32_bf16 v[40:43], v[136:139], v[184:187], v[40:43]
	v_mfma_f32_16x16x32_bf16 v[48:51], v[132:135], v[188:191], v[48:51]
	v_mfma_f32_16x16x32_bf16 v[40:43], v[140:143], v[188:191], v[40:43]
	v_mfma_f32_16x16x32_bf16 v[32:35], v[128:131], v[200:203], v[32:35]
	v_mfma_f32_16x16x32_bf16 v[24:27], v[136:139], v[200:203], v[24:27]
	v_mfma_f32_16x16x32_bf16 v[32:35], v[132:135], v[204:207], v[32:35]
	v_mfma_f32_16x16x32_bf16 v[24:27], v[140:143], v[204:207], v[24:27]
	v_mfma_f32_16x16x32_bf16 v[16:19], v[128:131], v[208:211], v[16:19]
	v_mfma_f32_16x16x32_bf16 v[8:11], v[136:139], v[208:211], v[8:11]
	v_mfma_f32_16x16x32_bf16 v[16:19], v[132:135], v[212:215], v[16:19]
	v_mfma_f32_16x16x32_bf16 v[8:11], v[140:143], v[212:215], v[8:11]
	v_mfma_f32_16x16x32_bf16 v[52:55], v[144:147], v[160:163], v[52:55]
	v_mfma_f32_16x16x32_bf16 v[44:47], v[152:155], v[160:163], v[44:47]
	v_mfma_f32_16x16x32_bf16 v[52:55], v[148:151], v[180:183], v[52:55]
	v_mfma_f32_16x16x32_bf16 v[44:47], v[156:159], v[180:183], v[44:47]
	v_mfma_f32_16x16x32_bf16 v[36:39], v[144:147], v[184:187], v[36:39]
	v_mfma_f32_16x16x32_bf16 v[28:31], v[152:155], v[184:187], v[28:31]
	v_mfma_f32_16x16x32_bf16 v[36:39], v[148:151], v[188:191], v[36:39]
	v_mfma_f32_16x16x32_bf16 v[28:31], v[156:159], v[188:191], v[28:31]
	v_mfma_f32_16x16x32_bf16 v[20:23], v[144:147], v[200:203], v[20:23]
	v_mfma_f32_16x16x32_bf16 v[12:15], v[152:155], v[200:203], v[12:15]
	v_mfma_f32_16x16x32_bf16 v[20:23], v[148:151], v[204:207], v[20:23]
	v_mfma_f32_16x16x32_bf16 v[12:15], v[156:159], v[204:207], v[12:15]
	v_mfma_f32_16x16x32_bf16 v[4:7], v[144:147], v[208:211], v[4:7]
	v_mfma_f32_16x16x32_bf16 v[0:3], v[152:155], v[208:211], v[0:3]
	s_setprio 3
	s_barrier
	v_mfma_f32_16x16x32_bf16 v[4:7], v[148:151], v[212:215], v[4:7]
	v_mfma_f32_16x16x32_bf16 v[0:3], v[156:159], v[212:215], v[0:3]
	s_setprio 0
	s_add_i32 s45, s45, 2
	s_add_u32 s16, s16, 0x100
	s_addc_u32 s17, s17, 0
	s_add_u32 s43, s43, 0x100
	s_addc_u32 s44, s44, 0
	s_cmp_gt_u32 s45, 41
	s_cbranch_scc0 .LBB0_2341
	s_branch .Lzskip_11
.Lzv_11_0:
	v_mfma_f32_16x16x32_bf16 v[124:127], v[128:131], v[160:163], 0
	v_mfma_f32_16x16x32_bf16 v[120:123], v[136:139], v[160:163], 0
	v_mfma_f32_16x16x32_bf16 v[124:127], v[132:135], v[180:183], v[124:127]
	v_mfma_f32_16x16x32_bf16 v[120:123], v[140:143], v[180:183], v[120:123]
	v_mfma_f32_16x16x32_bf16 v[108:111], v[128:131], v[184:187], 0
	v_mfma_f32_16x16x32_bf16 v[104:107], v[136:139], v[184:187], 0
	v_mfma_f32_16x16x32_bf16 v[108:111], v[132:135], v[188:191], v[108:111]
	v_mfma_f32_16x16x32_bf16 v[104:107], v[140:143], v[188:191], v[104:107]
	v_mfma_f32_16x16x32_bf16 v[96:99], v[128:131], v[200:203], 0
	v_mfma_f32_16x16x32_bf16 v[88:91], v[136:139], v[200:203], 0
	v_mfma_f32_16x16x32_bf16 v[96:99], v[132:135], v[204:207], v[96:99]
	v_mfma_f32_16x16x32_bf16 v[88:91], v[140:143], v[204:207], v[88:91]
	v_mfma_f32_16x16x32_bf16 v[80:83], v[128:131], v[208:211], 0
	v_mfma_f32_16x16x32_bf16 v[72:75], v[136:139], v[208:211], 0
	v_mfma_f32_16x16x32_bf16 v[80:83], v[132:135], v[212:215], v[80:83]
	v_mfma_f32_16x16x32_bf16 v[72:75], v[140:143], v[212:215], v[72:75]
	v_mfma_f32_16x16x32_bf16 v[116:119], v[144:147], v[160:163], 0
	v_mfma_f32_16x16x32_bf16 v[112:115], v[152:155], v[160:163], 0
	v_mfma_f32_16x16x32_bf16 v[116:119], v[148:151], v[180:183], v[116:119]
	v_mfma_f32_16x16x32_bf16 v[112:115], v[156:159], v[180:183], v[112:115]
	v_mfma_f32_16x16x32_bf16 v[100:103], v[144:147], v[184:187], 0
	v_mfma_f32_16x16x32_bf16 v[92:95], v[152:155], v[184:187], 0
	v_mfma_f32_16x16x32_bf16 v[100:103], v[148:151], v[188:191], v[100:103]
	v_mfma_f32_16x16x32_bf16 v[92:95], v[156:159], v[188:191], v[92:95]
	v_mfma_f32_16x16x32_bf16 v[84:87], v[144:147], v[200:203], 0
	v_mfma_f32_16x16x32_bf16 v[76:79], v[152:155], v[200:203], 0
	v_mfma_f32_16x16x32_bf16 v[84:87], v[148:151], v[204:207], v[84:87]
	v_mfma_f32_16x16x32_bf16 v[76:79], v[156:159], v[204:207], v[76:79]
	v_mfma_f32_16x16x32_bf16 v[68:71], v[144:147], v[208:211], 0
	v_mfma_f32_16x16x32_bf16 v[64:67], v[152:155], v[208:211], 0
	s_setprio 3
	s_barrier
	v_mfma_f32_16x16x32_bf16 v[68:71], v[148:151], v[212:215], v[68:71]
	v_mfma_f32_16x16x32_bf16 v[64:67], v[156:159], v[212:215], v[64:67]
	s_setprio 0
	s_branch .Lzj_11_0
.Lzv_11_1:
	v_mfma_f32_16x16x32_bf16 v[60:63], v[128:131], v[160:163], 0
	v_mfma_f32_16x16x32_bf16 v[56:59], v[136:139], v[160:163], 0
	v_mfma_f32_16x16x32_bf16 v[60:63], v[132:135], v[180:183], v[60:63]
	v_mfma_f32_16x16x32_bf16 v[56:59], v[140:143], v[180:183], v[56:59]
	v_mfma_f32_16x16x32_bf16 v[48:51], v[128:131], v[184:187], 0
	v_mfma_f32_16x16x32_bf16 v[40:43], v[136:139], v[184:187], 0
	v_mfma_f32_16x16x32_bf16 v[48:51], v[132:135], v[188:191], v[48:51]
	v_mfma_f32_16x16x32_bf16 v[40:43], v[140:143], v[188:191], v[40:43]
	v_mfma_f32_16x16x32_bf16 v[32:35], v[128:131], v[200:203], 0
	v_mfma_f32_16x16x32_bf16 v[24:27], v[136:139], v[200:203], 0
	v_mfma_f32_16x16x32_bf16 v[32:35], v[132:135], v[204:207], v[32:35]
	v_mfma_f32_16x16x32_bf16 v[24:27], v[140:143], v[204:207], v[24:27]
	v_mfma_f32_16x16x32_bf16 v[16:19], v[128:131], v[208:211], 0
	v_mfma_f32_16x16x32_bf16 v[8:11], v[136:139], v[208:211], 0
	v_mfma_f32_16x16x32_bf16 v[16:19], v[132:135], v[212:215], v[16:19]
	v_mfma_f32_16x16x32_bf16 v[8:11], v[140:143], v[212:215], v[8:11]
	v_mfma_f32_16x16x32_bf16 v[52:55], v[144:147], v[160:163], 0
	v_mfma_f32_16x16x32_bf16 v[44:47], v[152:155], v[160:163], 0
	v_mfma_f32_16x16x32_bf16 v[52:55], v[148:151], v[180:183], v[52:55]
	v_mfma_f32_16x16x32_bf16 v[44:47], v[156:159], v[180:183], v[44:47]
	v_mfma_f32_16x16x32_bf16 v[36:39], v[144:147], v[184:187], 0
	v_mfma_f32_16x16x32_bf16 v[28:31], v[152:155], v[184:187], 0
	v_mfma_f32_16x16x32_bf16 v[36:39], v[148:151], v[188:191], v[36:39]
	v_mfma_f32_16x16x32_bf16 v[28:31], v[156:159], v[188:191], v[28:31]
	v_mfma_f32_16x16x32_bf16 v[20:23], v[144:147], v[200:203], 0
	v_mfma_f32_16x16x32_bf16 v[12:15], v[152:155], v[200:203], 0
	v_mfma_f32_16x16x32_bf16 v[20:23], v[148:151], v[204:207], v[20:23]
	v_mfma_f32_16x16x32_bf16 v[12:15], v[156:159], v[204:207], v[12:15]
	v_mfma_f32_16x16x32_bf16 v[4:7], v[144:147], v[208:211], 0
	v_mfma_f32_16x16x32_bf16 v[0:3], v[152:155], v[208:211], 0
	s_setprio 3
	s_barrier
	v_mfma_f32_16x16x32_bf16 v[4:7], v[148:151], v[212:215], v[4:7]
	v_mfma_f32_16x16x32_bf16 v[0:3], v[156:159], v[212:215], v[0:3]
	s_setprio 0
	s_branch .Lzj_11_1
